# v67 + the 12 K-loop head labels aligned to 64 bytes (.p2align 6)
# speedup vs baseline: 1.0056x; 1.0056x over previous
.LBB0_296:
	s_add_u32 s22, s3, s62
	s_mov_b32 s23, 0
	s_addc_u32 s23, s35, s23
	s_and_b64 s[26:27], s[20:21], exec
	s_cselect_b32 s70, s23, s39
	s_cselect_b32 s71, s22, s38
	s_add_u32 s26, s96, s12
	s_addc_u32 s27, s97, s13
	s_and_b64 s[42:43], s[20:21], exec
	v_mov_b32_e32 v2, 0
	s_cselect_b32 s72, s27, s37
	s_cselect_b32 s73, s26, s36
	s_mov_b32 s46, 0
	s_mov_b64 s[42:43], -1
	s_mov_b64 s[44:45], 0
	v_mov_b32_e32 v3, v2
	v_mov_b32_e32 v4, v2
	v_mov_b32_e32 v5, v2
	v_mov_b32_e32 v6, v2
	v_mov_b32_e32 v7, v2
	v_mov_b32_e32 v8, v2
	v_mov_b32_e32 v9, v2
	v_mov_b32_e32 v10, v2
	v_mov_b32_e32 v11, v2
	v_mov_b32_e32 v12, v2
	v_mov_b32_e32 v13, v2
	v_mov_b32_e32 v14, v2
	v_mov_b32_e32 v15, v2
	v_mov_b32_e32 v16, v2
	v_mov_b32_e32 v17, v2
	v_mov_b32_e32 v26, v2
	v_mov_b32_e32 v27, v2
	v_mov_b32_e32 v28, v2
	v_mov_b32_e32 v29, v2
	v_mov_b32_e32 v30, v2
	v_mov_b32_e32 v31, v2
	v_mov_b32_e32 v32, v2
	v_mov_b32_e32 v33, v2
	v_mov_b32_e32 v42, v2
	v_mov_b32_e32 v43, v2
	v_mov_b32_e32 v44, v2
	v_mov_b32_e32 v45, v2
	v_mov_b32_e32 v46, v2
	v_mov_b32_e32 v47, v2
	v_mov_b32_e32 v48, v2
	v_mov_b32_e32 v49, v2
	v_mov_b32_e32 v18, v2
	v_mov_b32_e32 v19, v2
	v_mov_b32_e32 v20, v2
	v_mov_b32_e32 v21, v2
	v_mov_b32_e32 v22, v2
	v_mov_b32_e32 v23, v2
	v_mov_b32_e32 v24, v2
	v_mov_b32_e32 v25, v2
	v_mov_b32_e32 v34, v2
	v_mov_b32_e32 v35, v2
	v_mov_b32_e32 v36, v2
	v_mov_b32_e32 v37, v2
	v_mov_b32_e32 v38, v2
	v_mov_b32_e32 v39, v2
	v_mov_b32_e32 v40, v2
	v_mov_b32_e32 v41, v2
	v_mov_b32_e32 v50, v2
	v_mov_b32_e32 v51, v2
	v_mov_b32_e32 v52, v2
	v_mov_b32_e32 v53, v2
	v_mov_b32_e32 v54, v2
	v_mov_b32_e32 v55, v2
	v_mov_b32_e32 v56, v2
	v_mov_b32_e32 v57, v2
	v_mov_b32_e32 v58, v2
	v_mov_b32_e32 v59, v2
	v_mov_b32_e32 v60, v2
	v_mov_b32_e32 v61, v2
	v_mov_b32_e32 v62, v2
	v_mov_b32_e32 v63, v2
	v_mov_b32_e32 v64, v2
	v_mov_b32_e32 v65, v2
	v_mov_b32_e32 v66, v2
	v_mov_b32_e32 v67, v2
	v_mov_b32_e32 v68, v2
	v_mov_b32_e32 v69, v2
	v_mov_b32_e32 v70, v2
	v_mov_b32_e32 v71, v2
	v_mov_b32_e32 v72, v2
	v_mov_b32_e32 v73, v2
	v_mov_b32_e32 v74, v2
	v_mov_b32_e32 v75, v2
	v_mov_b32_e32 v76, v2
	v_mov_b32_e32 v77, v2
	v_mov_b32_e32 v78, v2
	v_mov_b32_e32 v79, v2
	v_mov_b32_e32 v80, v2
	v_mov_b32_e32 v81, v2
	v_mov_b32_e32 v90, v2
	v_mov_b32_e32 v91, v2
	v_mov_b32_e32 v92, v2
	v_mov_b32_e32 v93, v2
	v_mov_b32_e32 v94, v2
	v_mov_b32_e32 v95, v2
	v_mov_b32_e32 v96, v2
	v_mov_b32_e32 v97, v2
	v_mov_b32_e32 v106, v2
	v_mov_b32_e32 v107, v2
	v_mov_b32_e32 v108, v2
	v_mov_b32_e32 v109, v2
	v_mov_b32_e32 v110, v2
	v_mov_b32_e32 v111, v2
	v_mov_b32_e32 v112, v2
	v_mov_b32_e32 v113, v2
	v_mov_b32_e32 v82, v2
	v_mov_b32_e32 v83, v2
	v_mov_b32_e32 v84, v2
	v_mov_b32_e32 v85, v2
	v_mov_b32_e32 v86, v2
	v_mov_b32_e32 v87, v2
	v_mov_b32_e32 v88, v2
	v_mov_b32_e32 v89, v2
	v_mov_b32_e32 v98, v2
	v_mov_b32_e32 v99, v2
	v_mov_b32_e32 v100, v2
	v_mov_b32_e32 v101, v2
	v_mov_b32_e32 v102, v2
	v_mov_b32_e32 v103, v2
	v_mov_b32_e32 v104, v2
	v_mov_b32_e32 v105, v2
	v_mov_b32_e32 v114, v2
	v_mov_b32_e32 v115, v2
	v_mov_b32_e32 v116, v2
	v_mov_b32_e32 v117, v2
	v_mov_b32_e32 v118, v2
	v_mov_b32_e32 v119, v2
	v_mov_b32_e32 v120, v2
	v_mov_b32_e32 v121, v2
	v_mov_b32_e32 v122, v2
	v_mov_b32_e32 v123, v2
	v_mov_b32_e32 v124, v2
	v_mov_b32_e32 v125, v2
	v_mov_b32_e32 v126, v2
	v_mov_b32_e32 v127, v2
	v_mov_b32_e32 v128, v2
	v_mov_b32_e32 v129, v2
	.p2align	6

.LBB0_312:
	s_add_u32 s22, s3, s72
	s_mov_b32 s23, 0
	s_addc_u32 s23, s35, s23
	s_and_b64 s[26:27], s[20:21], exec
	s_cselect_b32 s43, s23, s39
	s_cselect_b32 s75, s22, s38
	s_add_u32 s26, s96, s12
	s_addc_u32 s27, s97, s13
	s_and_b64 s[44:45], s[20:21], exec
	v_mov_b32_e32 v2, 0
	s_cselect_b32 s76, s27, s37
	s_cselect_b32 s77, s26, s36
	s_mov_b32 s48, 0
	s_mov_b64 s[44:45], -1
	s_mov_b64 s[46:47], 0
	v_mov_b32_e32 v3, v2
	v_mov_b32_e32 v4, v2
	v_mov_b32_e32 v5, v2
	v_mov_b32_e32 v6, v2
	v_mov_b32_e32 v7, v2
	v_mov_b32_e32 v8, v2
	v_mov_b32_e32 v9, v2
	v_mov_b32_e32 v10, v2
	v_mov_b32_e32 v11, v2
	v_mov_b32_e32 v12, v2
	v_mov_b32_e32 v13, v2
	v_mov_b32_e32 v14, v2
	v_mov_b32_e32 v15, v2
	v_mov_b32_e32 v16, v2
	v_mov_b32_e32 v17, v2
	v_mov_b32_e32 v26, v2
	v_mov_b32_e32 v27, v2
	v_mov_b32_e32 v28, v2
	v_mov_b32_e32 v29, v2
	v_mov_b32_e32 v30, v2
	v_mov_b32_e32 v31, v2
	v_mov_b32_e32 v32, v2
	v_mov_b32_e32 v33, v2
	v_mov_b32_e32 v42, v2
	v_mov_b32_e32 v43, v2
	v_mov_b32_e32 v44, v2
	v_mov_b32_e32 v45, v2
	v_mov_b32_e32 v46, v2
	v_mov_b32_e32 v47, v2
	v_mov_b32_e32 v48, v2
	v_mov_b32_e32 v49, v2
	v_mov_b32_e32 v18, v2
	v_mov_b32_e32 v19, v2
	v_mov_b32_e32 v20, v2
	v_mov_b32_e32 v21, v2
	v_mov_b32_e32 v22, v2
	v_mov_b32_e32 v23, v2
	v_mov_b32_e32 v24, v2
	v_mov_b32_e32 v25, v2
	v_mov_b32_e32 v34, v2
	v_mov_b32_e32 v35, v2
	v_mov_b32_e32 v36, v2
	v_mov_b32_e32 v37, v2
	v_mov_b32_e32 v38, v2
	v_mov_b32_e32 v39, v2
	v_mov_b32_e32 v40, v2
	v_mov_b32_e32 v41, v2
	v_mov_b32_e32 v50, v2
	v_mov_b32_e32 v51, v2
	v_mov_b32_e32 v52, v2
	v_mov_b32_e32 v53, v2
	v_mov_b32_e32 v54, v2
	v_mov_b32_e32 v55, v2
	v_mov_b32_e32 v56, v2
	v_mov_b32_e32 v57, v2
	v_mov_b32_e32 v58, v2
	v_mov_b32_e32 v59, v2
	v_mov_b32_e32 v60, v2
	v_mov_b32_e32 v61, v2
	v_mov_b32_e32 v62, v2
	v_mov_b32_e32 v63, v2
	v_mov_b32_e32 v64, v2
	v_mov_b32_e32 v65, v2
	v_mov_b32_e32 v66, v2
	v_mov_b32_e32 v67, v2
	v_mov_b32_e32 v68, v2
	v_mov_b32_e32 v69, v2
	v_mov_b32_e32 v70, v2
	v_mov_b32_e32 v71, v2
	v_mov_b32_e32 v72, v2
	v_mov_b32_e32 v73, v2
	v_mov_b32_e32 v74, v2
	v_mov_b32_e32 v75, v2
	v_mov_b32_e32 v76, v2
	v_mov_b32_e32 v77, v2
	v_mov_b32_e32 v78, v2
	v_mov_b32_e32 v79, v2
	v_mov_b32_e32 v80, v2
	v_mov_b32_e32 v81, v2
	v_mov_b32_e32 v90, v2
	v_mov_b32_e32 v91, v2
	v_mov_b32_e32 v92, v2
	v_mov_b32_e32 v93, v2
	v_mov_b32_e32 v94, v2
	v_mov_b32_e32 v95, v2
	v_mov_b32_e32 v96, v2
	v_mov_b32_e32 v97, v2
	v_mov_b32_e32 v106, v2
	v_mov_b32_e32 v107, v2
	v_mov_b32_e32 v108, v2
	v_mov_b32_e32 v109, v2
	v_mov_b32_e32 v110, v2
	v_mov_b32_e32 v111, v2
	v_mov_b32_e32 v112, v2
	v_mov_b32_e32 v113, v2
	v_mov_b32_e32 v82, v2
	v_mov_b32_e32 v83, v2
	v_mov_b32_e32 v84, v2
	v_mov_b32_e32 v85, v2
	v_mov_b32_e32 v86, v2
	v_mov_b32_e32 v87, v2
	v_mov_b32_e32 v88, v2
	v_mov_b32_e32 v89, v2
	v_mov_b32_e32 v98, v2
	v_mov_b32_e32 v99, v2
	v_mov_b32_e32 v100, v2
	v_mov_b32_e32 v101, v2
	v_mov_b32_e32 v102, v2
	v_mov_b32_e32 v103, v2
	v_mov_b32_e32 v104, v2
	v_mov_b32_e32 v105, v2
	v_mov_b32_e32 v114, v2
	v_mov_b32_e32 v115, v2
	v_mov_b32_e32 v116, v2
	v_mov_b32_e32 v117, v2
	v_mov_b32_e32 v118, v2
	v_mov_b32_e32 v119, v2
	v_mov_b32_e32 v120, v2
	v_mov_b32_e32 v121, v2
	v_mov_b32_e32 v122, v2
	v_mov_b32_e32 v123, v2
	v_mov_b32_e32 v124, v2
	v_mov_b32_e32 v125, v2
	v_mov_b32_e32 v126, v2
	v_mov_b32_e32 v127, v2
	v_mov_b32_e32 v128, v2
	v_mov_b32_e32 v129, v2
	.p2align	6

.LBB0_383:
	s_add_u32 s26, s0, s22
	s_addc_u32 s27, s1, s23
	s_and_b64 s[44:45], s[36:37], exec
	s_cselect_b32 s15, s27, s43
	s_cselect_b32 s39, s26, s42
	s_add_u32 s66, s42, 0x100
	s_addc_u32 s67, s43, 0
	s_mov_b32 s68, -2
	s_mov_b64 s[42:43], 0
	ds_read_b128 v[152:155], v146
	ds_read_b128 v[156:159], v146 offset:1024
	ds_read_b128 v[160:163], v146 offset:2048
	ds_read_b128 v[164:167], v146 offset:3072
	ds_read_b128 v[168:171], v147
	ds_read_b128 v[172:175], v147 offset:1024
	ds_read_b128 v[176:179], v147 offset:2048
	ds_read_b128 v[180:183], v147 offset:3072
	s_add_u32 s44, s42, 0x100
	s_addc_u32 s45, s43, 0
	s_add_u32 s46, s66, s42
	s_addc_u32 s47, s67, s43
	s_cmp_eq_u32 s68, 4
	s_cselect_b32 s48, 0, s44
	s_cselect_b32 s49, 0, s45
	s_cselect_b32 s46, s39, s46
	s_cselect_b32 s47, s15, s47
	s_add_u32 s48, s6, s48
	s_addc_u32 s49, s7, s49
	s_mov_b32 m0, s29
	v_lshl_add_u64 v[218:219], v[138:139], 0, s[42:43]
	ds_read_b128 v[184:187], v148
	ds_read_b128 v[188:191], v148 offset:1024
	ds_read_b128 v[192:195], v148 offset:2048
	ds_read_b128 v[196:199], v148 offset:3072
	ds_read_b128 v[200:203], v148 offset:4096
	ds_read_b128 v[206:209], v148 offset:5120
	ds_read_b128 v[210:213], v148 offset:6144
	ds_read_b128 v[214:217], v148 offset:7168
	global_load_lds_dwordx4 v[218:219], off
	s_mov_b32 m0, s30
	v_lshl_add_u64 v[218:219], v[140:141], 0, s[42:43]
	global_load_lds_dwordx4 v[218:219], off
	s_waitcnt vmcnt(8) lgkmcnt(0)
	s_setprio 1
	s_barrier
	v_mfma_f32_16x16x32_bf16 v[126:129], v[152:155], v[184:187], 0
	v_mfma_f32_16x16x32_bf16 v[122:125], v[160:163], v[184:187], 0
	v_mfma_f32_16x16x32_bf16 v[118:121], v[152:155], v[192:195], 0
	v_mfma_f32_16x16x32_bf16 v[114:117], v[160:163], v[192:195], 0
	v_mfma_f32_16x16x32_bf16 v[102:105], v[152:155], v[200:203], 0
	v_mfma_f32_16x16x32_bf16 v[98:101], v[160:163], v[200:203], 0
	v_mfma_f32_16x16x32_bf16 v[86:89], v[152:155], v[210:213], 0
	v_mfma_f32_16x16x32_bf16 v[82:85], v[160:163], v[210:213], 0
	v_mfma_f32_16x16x32_bf16 v[126:129], v[156:159], v[188:191], v[126:129]
	v_mfma_f32_16x16x32_bf16 v[122:125], v[164:167], v[188:191], v[122:125]
	v_mfma_f32_16x16x32_bf16 v[118:121], v[156:159], v[196:199], v[118:121]
	v_mfma_f32_16x16x32_bf16 v[114:117], v[164:167], v[196:199], v[114:117]
	v_mfma_f32_16x16x32_bf16 v[102:105], v[156:159], v[206:209], v[102:105]
	v_mfma_f32_16x16x32_bf16 v[98:101], v[164:167], v[206:209], v[98:101]
	v_mfma_f32_16x16x32_bf16 v[86:89], v[156:159], v[214:217], v[86:89]
	v_mfma_f32_16x16x32_bf16 v[82:85], v[164:167], v[214:217], v[82:85]
	v_mfma_f32_16x16x32_bf16 v[110:113], v[168:171], v[184:187], 0
	v_mfma_f32_16x16x32_bf16 v[106:109], v[176:179], v[184:187], 0
	v_mfma_f32_16x16x32_bf16 v[94:97], v[168:171], v[192:195], 0
	v_mfma_f32_16x16x32_bf16 v[90:93], v[176:179], v[192:195], 0
	v_mfma_f32_16x16x32_bf16 v[78:81], v[168:171], v[200:203], 0
	v_mfma_f32_16x16x32_bf16 v[74:77], v[176:179], v[200:203], 0
	v_mfma_f32_16x16x32_bf16 v[70:73], v[168:171], v[210:213], 0
	v_mfma_f32_16x16x32_bf16 v[66:69], v[176:179], v[210:213], 0
	v_mfma_f32_16x16x32_bf16 v[110:113], v[172:175], v[188:191], v[110:113]
	v_mfma_f32_16x16x32_bf16 v[106:109], v[180:183], v[188:191], v[106:109]
	v_mfma_f32_16x16x32_bf16 v[94:97], v[172:175], v[196:199], v[94:97]
	v_mfma_f32_16x16x32_bf16 v[90:93], v[180:183], v[196:199], v[90:93]
	v_mfma_f32_16x16x32_bf16 v[78:81], v[172:175], v[206:209], v[78:81]
	v_mfma_f32_16x16x32_bf16 v[74:77], v[180:183], v[206:209], v[74:77]
	v_mfma_f32_16x16x32_bf16 v[70:73], v[172:175], v[214:217], v[70:73]
	v_mfma_f32_16x16x32_bf16 v[66:69], v[180:183], v[214:217], v[66:69]
	s_setprio 0
	s_barrier
	s_mov_b32 m0, s31
	v_lshl_add_u64 v[218:219], s[46:47], 0, v[134:135]
	s_add_u32 s42, s46, 0x20000
	ds_read_b128 v[184:187], v148 offset:16384
	ds_read_b128 v[188:191], v148 offset:17408
	ds_read_b128 v[192:195], v148 offset:18432
	ds_read_b128 v[196:199], v148 offset:19456
	ds_read_b128 v[200:203], v148 offset:20480
	ds_read_b128 v[206:209], v148 offset:21504
	ds_read_b128 v[210:213], v148 offset:22528
	ds_read_b128 v[214:217], v148 offset:23552
	global_load_lds_dwordx4 v[218:219], off
	v_lshl_add_u64 v[220:221], s[46:47], 0, v[130:131]
	s_mov_b32 m0, s33
	s_addc_u32 s43, s47, 0
	global_load_lds_dwordx4 v[220:221], off
	v_lshl_add_u64 v[222:223], s[42:43], 0, v[134:135]
	s_mov_b32 m0, s34
	v_lshl_add_u64 v[224:225], s[48:49], 0, v[132:133]
	global_load_lds_dwordx4 v[222:223], off
	s_mov_b32 m0, s35
	v_lshl_add_u64 v[222:223], s[42:43], 0, v[130:131]
	global_load_lds_dwordx4 v[222:223], off
	s_mov_b32 m0, s2
	v_lshl_add_u64 v[222:223], s[48:49], 0, v[136:137]
	global_load_lds_dwordx4 v[222:223], off
	s_mov_b32 m0, s3
	s_nop 0
	global_load_lds_dwordx4 v[224:225], off
	s_waitcnt vmcnt(8) lgkmcnt(0)
	s_setprio 1
	s_barrier
	v_mfma_f32_16x16x32_bf16 v[62:65], v[152:155], v[184:187], 0
	v_mfma_f32_16x16x32_bf16 v[58:61], v[160:163], v[184:187], 0
	v_mfma_f32_16x16x32_bf16 v[54:57], v[152:155], v[192:195], 0
	v_mfma_f32_16x16x32_bf16 v[50:53], v[160:163], v[192:195], 0
	v_mfma_f32_16x16x32_bf16 v[38:41], v[152:155], v[200:203], 0
	v_mfma_f32_16x16x32_bf16 v[34:37], v[160:163], v[200:203], 0
	v_mfma_f32_16x16x32_bf16 v[22:25], v[152:155], v[210:213], 0
	v_mfma_f32_16x16x32_bf16 v[18:21], v[160:163], v[210:213], 0
	v_mfma_f32_16x16x32_bf16 v[62:65], v[156:159], v[188:191], v[62:65]
	v_mfma_f32_16x16x32_bf16 v[58:61], v[164:167], v[188:191], v[58:61]
	v_mfma_f32_16x16x32_bf16 v[54:57], v[156:159], v[196:199], v[54:57]
	v_mfma_f32_16x16x32_bf16 v[50:53], v[164:167], v[196:199], v[50:53]
	v_mfma_f32_16x16x32_bf16 v[38:41], v[156:159], v[206:209], v[38:41]
	v_mfma_f32_16x16x32_bf16 v[34:37], v[164:167], v[206:209], v[34:37]
	v_mfma_f32_16x16x32_bf16 v[22:25], v[156:159], v[214:217], v[22:25]
	v_mfma_f32_16x16x32_bf16 v[18:21], v[164:167], v[214:217], v[18:21]
	v_mfma_f32_16x16x32_bf16 v[46:49], v[168:171], v[184:187], 0
	v_mfma_f32_16x16x32_bf16 v[42:45], v[176:179], v[184:187], 0
	v_mfma_f32_16x16x32_bf16 v[30:33], v[168:171], v[192:195], 0
	v_mfma_f32_16x16x32_bf16 v[26:29], v[176:179], v[192:195], 0
	v_mfma_f32_16x16x32_bf16 v[14:17], v[168:171], v[200:203], 0
	v_mfma_f32_16x16x32_bf16 v[10:13], v[176:179], v[200:203], 0
	v_mfma_f32_16x16x32_bf16 v[6:9], v[168:171], v[210:213], 0
	v_mfma_f32_16x16x32_bf16 v[2:5], v[176:179], v[210:213], 0
	v_mfma_f32_16x16x32_bf16 v[46:49], v[172:175], v[188:191], v[46:49]
	v_mfma_f32_16x16x32_bf16 v[42:45], v[180:183], v[188:191], v[42:45]
	v_mfma_f32_16x16x32_bf16 v[30:33], v[172:175], v[196:199], v[30:33]
	v_mfma_f32_16x16x32_bf16 v[26:29], v[180:183], v[196:199], v[26:29]
	v_mfma_f32_16x16x32_bf16 v[14:17], v[172:175], v[206:209], v[14:17]
	v_mfma_f32_16x16x32_bf16 v[10:13], v[180:183], v[206:209], v[10:13]
	v_mfma_f32_16x16x32_bf16 v[6:9], v[172:175], v[214:217], v[6:9]
	v_mfma_f32_16x16x32_bf16 v[2:5], v[180:183], v[214:217], v[2:5]
	s_setprio 0
	s_barrier
	ds_read_b128 v[152:155], v149
	ds_read_b128 v[156:159], v149 offset:1024
	ds_read_b128 v[160:163], v149 offset:2048
	ds_read_b128 v[164:167], v149 offset:3072
	ds_read_b128 v[168:171], v150
	ds_read_b128 v[172:175], v150 offset:1024
	ds_read_b128 v[176:179], v150 offset:2048
	ds_read_b128 v[180:183], v150 offset:3072
	s_add_u32 s42, s48, 0x20000
	s_addc_u32 s43, s49, 0
	s_mov_b32 m0, s16
	v_lshl_add_u64 v[226:227], s[42:43], 0, v[136:137]
	ds_read_b128 v[184:187], v148 offset:32768
	ds_read_b128 v[188:191], v148 offset:33792
	ds_read_b128 v[192:195], v148 offset:34816
	ds_read_b128 v[196:199], v148 offset:35840
	ds_read_b128 v[200:203], v148 offset:36864
	ds_read_b128 v[206:209], v148 offset:37888
	ds_read_b128 v[210:213], v148 offset:38912
	ds_read_b128 v[214:217], v148 offset:39936
	global_load_lds_dwordx4 v[226:227], off
	s_mov_b32 m0, s17
	v_lshl_add_u64 v[226:227], s[42:43], 0, v[132:133]
	global_load_lds_dwordx4 v[226:227], off
	s_waitcnt vmcnt(8) lgkmcnt(0)
	s_setprio 1
	s_barrier
	v_mfma_f32_16x16x32_bf16 v[126:129], v[152:155], v[184:187], v[126:129]
	v_mfma_f32_16x16x32_bf16 v[122:125], v[160:163], v[184:187], v[122:125]
	v_mfma_f32_16x16x32_bf16 v[118:121], v[152:155], v[192:195], v[118:121]
	v_mfma_f32_16x16x32_bf16 v[114:117], v[160:163], v[192:195], v[114:117]
	v_mfma_f32_16x16x32_bf16 v[102:105], v[152:155], v[200:203], v[102:105]
	v_mfma_f32_16x16x32_bf16 v[98:101], v[160:163], v[200:203], v[98:101]
	v_mfma_f32_16x16x32_bf16 v[86:89], v[152:155], v[210:213], v[86:89]
	v_mfma_f32_16x16x32_bf16 v[82:85], v[160:163], v[210:213], v[82:85]
	v_mfma_f32_16x16x32_bf16 v[126:129], v[156:159], v[188:191], v[126:129]
	v_mfma_f32_16x16x32_bf16 v[122:125], v[164:167], v[188:191], v[122:125]
	v_mfma_f32_16x16x32_bf16 v[118:121], v[156:159], v[196:199], v[118:121]
	v_mfma_f32_16x16x32_bf16 v[114:117], v[164:167], v[196:199], v[114:117]
	v_mfma_f32_16x16x32_bf16 v[102:105], v[156:159], v[206:209], v[102:105]
	v_mfma_f32_16x16x32_bf16 v[98:101], v[164:167], v[206:209], v[98:101]
	v_mfma_f32_16x16x32_bf16 v[86:89], v[156:159], v[214:217], v[86:89]
	v_mfma_f32_16x16x32_bf16 v[82:85], v[164:167], v[214:217], v[82:85]
	v_mfma_f32_16x16x32_bf16 v[110:113], v[168:171], v[184:187], v[110:113]
	v_mfma_f32_16x16x32_bf16 v[106:109], v[176:179], v[184:187], v[106:109]
	v_mfma_f32_16x16x32_bf16 v[94:97], v[168:171], v[192:195], v[94:97]
	v_mfma_f32_16x16x32_bf16 v[90:93], v[176:179], v[192:195], v[90:93]
	v_mfma_f32_16x16x32_bf16 v[78:81], v[168:171], v[200:203], v[78:81]
	v_mfma_f32_16x16x32_bf16 v[74:77], v[176:179], v[200:203], v[74:77]
	v_mfma_f32_16x16x32_bf16 v[70:73], v[168:171], v[210:213], v[70:73]
	v_mfma_f32_16x16x32_bf16 v[66:69], v[176:179], v[210:213], v[66:69]
	v_mfma_f32_16x16x32_bf16 v[110:113], v[172:175], v[188:191], v[110:113]
	v_mfma_f32_16x16x32_bf16 v[106:109], v[180:183], v[188:191], v[106:109]
	v_mfma_f32_16x16x32_bf16 v[94:97], v[172:175], v[196:199], v[94:97]
	v_mfma_f32_16x16x32_bf16 v[90:93], v[180:183], v[196:199], v[90:93]
	v_mfma_f32_16x16x32_bf16 v[78:81], v[172:175], v[206:209], v[78:81]
	v_mfma_f32_16x16x32_bf16 v[74:77], v[180:183], v[206:209], v[74:77]
	v_mfma_f32_16x16x32_bf16 v[70:73], v[172:175], v[214:217], v[70:73]
	v_mfma_f32_16x16x32_bf16 v[66:69], v[180:183], v[214:217], v[66:69]
	s_setprio 0
	s_barrier
	s_mov_b32 m0, s62
	v_lshl_add_u64 v[218:219], v[218:219], 0, s[10:11]
	s_add_u32 s42, s46, 0x20080
	ds_read_b128 v[184:187], v148 offset:49152
	ds_read_b128 v[188:191], v148 offset:50176
	ds_read_b128 v[192:195], v148 offset:51200
	ds_read_b128 v[196:199], v148 offset:52224
	ds_read_b128 v[200:203], v148 offset:53248
	ds_read_b128 v[206:209], v148 offset:54272
	ds_read_b128 v[210:213], v148 offset:55296
	ds_read_b128 v[214:217], v148 offset:56320
	global_load_lds_dwordx4 v[218:219], off
	v_lshl_add_u64 v[218:219], v[220:221], 0, s[10:11]
	s_mov_b32 m0, s63
	s_addc_u32 s43, s47, 0
	global_load_lds_dwordx4 v[218:219], off
	s_mov_b32 m0, s64
	v_lshl_add_u64 v[218:219], s[42:43], 0, v[134:135]
	global_load_lds_dwordx4 v[218:219], off
	s_mov_b32 m0, s65
	v_lshl_add_u64 v[218:219], s[42:43], 0, v[130:131]
	global_load_lds_dwordx4 v[218:219], off
	s_mov_b32 m0, s25
	v_lshl_add_u64 v[218:219], v[222:223], 0, s[10:11]
	global_load_lds_dwordx4 v[218:219], off
	s_mov_b32 m0, s28
	v_lshl_add_u64 v[218:219], v[224:225], 0, s[10:11]
	global_load_lds_dwordx4 v[218:219], off
	s_waitcnt vmcnt(8) lgkmcnt(0)
	s_setprio 1
	s_barrier
	v_mfma_f32_16x16x32_bf16 v[62:65], v[152:155], v[184:187], v[62:65]
	v_mfma_f32_16x16x32_bf16 v[58:61], v[160:163], v[184:187], v[58:61]
	v_mfma_f32_16x16x32_bf16 v[54:57], v[152:155], v[192:195], v[54:57]
	v_mfma_f32_16x16x32_bf16 v[50:53], v[160:163], v[192:195], v[50:53]
	v_mfma_f32_16x16x32_bf16 v[38:41], v[152:155], v[200:203], v[38:41]
	v_mfma_f32_16x16x32_bf16 v[34:37], v[160:163], v[200:203], v[34:37]
	v_mfma_f32_16x16x32_bf16 v[22:25], v[152:155], v[210:213], v[22:25]
	v_mfma_f32_16x16x32_bf16 v[18:21], v[160:163], v[210:213], v[18:21]
	v_mfma_f32_16x16x32_bf16 v[62:65], v[156:159], v[188:191], v[62:65]
	v_mfma_f32_16x16x32_bf16 v[58:61], v[164:167], v[188:191], v[58:61]
	v_mfma_f32_16x16x32_bf16 v[54:57], v[156:159], v[196:199], v[54:57]
	v_mfma_f32_16x16x32_bf16 v[50:53], v[164:167], v[196:199], v[50:53]
	v_mfma_f32_16x16x32_bf16 v[38:41], v[156:159], v[206:209], v[38:41]
	v_mfma_f32_16x16x32_bf16 v[34:37], v[164:167], v[206:209], v[34:37]
	v_mfma_f32_16x16x32_bf16 v[22:25], v[156:159], v[214:217], v[22:25]
	v_mfma_f32_16x16x32_bf16 v[18:21], v[164:167], v[214:217], v[18:21]
	v_mfma_f32_16x16x32_bf16 v[46:49], v[168:171], v[184:187], v[46:49]
	v_mfma_f32_16x16x32_bf16 v[42:45], v[176:179], v[184:187], v[42:45]
	v_mfma_f32_16x16x32_bf16 v[30:33], v[168:171], v[192:195], v[30:33]
	v_mfma_f32_16x16x32_bf16 v[26:29], v[176:179], v[192:195], v[26:29]
	v_mfma_f32_16x16x32_bf16 v[14:17], v[168:171], v[200:203], v[14:17]
	v_mfma_f32_16x16x32_bf16 v[10:13], v[176:179], v[200:203], v[10:13]
	v_mfma_f32_16x16x32_bf16 v[6:9], v[168:171], v[210:213], v[6:9]
	v_mfma_f32_16x16x32_bf16 v[2:5], v[176:179], v[210:213], v[2:5]
	v_mfma_f32_16x16x32_bf16 v[46:49], v[172:175], v[188:191], v[46:49]
	v_mfma_f32_16x16x32_bf16 v[42:45], v[180:183], v[188:191], v[42:45]
	v_mfma_f32_16x16x32_bf16 v[30:33], v[172:175], v[196:199], v[30:33]
	v_mfma_f32_16x16x32_bf16 v[26:29], v[180:183], v[196:199], v[26:29]
	v_mfma_f32_16x16x32_bf16 v[14:17], v[172:175], v[206:209], v[14:17]
	v_mfma_f32_16x16x32_bf16 v[10:13], v[180:183], v[206:209], v[10:13]
	v_mfma_f32_16x16x32_bf16 v[6:9], v[172:175], v[214:217], v[6:9]
	v_mfma_f32_16x16x32_bf16 v[2:5], v[180:183], v[214:217], v[2:5]
	s_setprio 0
	s_barrier
	s_add_i32 s68, s68, 2
	s_cmp_gt_u32 s68, 5
	s_mov_b64 s[42:43], s[44:45]
	.p2align	6

.LBB0_405:
	s_add_u32 s44, s2, s42
	s_addc_u32 s45, s3, s43
	s_and_b64 s[14:15], s[46:47], exec
	v_mov_b32_e32 v2, 0
	s_cselect_b32 s14, s45, s49
	s_cselect_b32 s15, s44, s48
	s_mov_b32 s12, 0
	s_mov_b64 s[66:67], -1
	v_mov_b32_e32 v3, v2
	v_mov_b32_e32 v4, v2
	v_mov_b32_e32 v5, v2
	v_mov_b32_e32 v6, v2
	v_mov_b32_e32 v7, v2
	v_mov_b32_e32 v8, v2
	v_mov_b32_e32 v9, v2
	v_mov_b32_e32 v10, v2
	v_mov_b32_e32 v11, v2
	v_mov_b32_e32 v12, v2
	v_mov_b32_e32 v13, v2
	v_mov_b32_e32 v14, v2
	v_mov_b32_e32 v15, v2
	v_mov_b32_e32 v16, v2
	v_mov_b32_e32 v17, v2
	v_mov_b32_e32 v26, v2
	v_mov_b32_e32 v27, v2
	v_mov_b32_e32 v28, v2
	v_mov_b32_e32 v29, v2
	v_mov_b32_e32 v30, v2
	v_mov_b32_e32 v31, v2
	v_mov_b32_e32 v32, v2
	v_mov_b32_e32 v33, v2
	v_mov_b32_e32 v42, v2
	v_mov_b32_e32 v43, v2
	v_mov_b32_e32 v44, v2
	v_mov_b32_e32 v45, v2
	v_mov_b32_e32 v46, v2
	v_mov_b32_e32 v47, v2
	v_mov_b32_e32 v48, v2
	v_mov_b32_e32 v49, v2
	v_mov_b32_e32 v18, v2
	v_mov_b32_e32 v19, v2
	v_mov_b32_e32 v20, v2
	v_mov_b32_e32 v21, v2
	v_mov_b32_e32 v22, v2
	v_mov_b32_e32 v23, v2
	v_mov_b32_e32 v24, v2
	v_mov_b32_e32 v25, v2
	v_mov_b32_e32 v34, v2
	v_mov_b32_e32 v35, v2
	v_mov_b32_e32 v36, v2
	v_mov_b32_e32 v37, v2
	v_mov_b32_e32 v38, v2
	v_mov_b32_e32 v39, v2
	v_mov_b32_e32 v40, v2
	v_mov_b32_e32 v41, v2
	v_mov_b32_e32 v50, v2
	v_mov_b32_e32 v51, v2
	v_mov_b32_e32 v52, v2
	v_mov_b32_e32 v53, v2
	v_mov_b32_e32 v54, v2
	v_mov_b32_e32 v55, v2
	v_mov_b32_e32 v56, v2
	v_mov_b32_e32 v57, v2
	v_mov_b32_e32 v58, v2
	v_mov_b32_e32 v59, v2
	v_mov_b32_e32 v60, v2
	v_mov_b32_e32 v61, v2
	v_mov_b32_e32 v62, v2
	v_mov_b32_e32 v63, v2
	v_mov_b32_e32 v64, v2
	v_mov_b32_e32 v65, v2
	v_mov_b32_e32 v66, v2
	v_mov_b32_e32 v67, v2
	v_mov_b32_e32 v68, v2
	v_mov_b32_e32 v69, v2
	v_mov_b32_e32 v70, v2
	v_mov_b32_e32 v71, v2
	v_mov_b32_e32 v72, v2
	v_mov_b32_e32 v73, v2
	v_mov_b32_e32 v74, v2
	v_mov_b32_e32 v75, v2
	v_mov_b32_e32 v76, v2
	v_mov_b32_e32 v77, v2
	v_mov_b32_e32 v78, v2
	v_mov_b32_e32 v79, v2
	v_mov_b32_e32 v80, v2
	v_mov_b32_e32 v81, v2
	v_mov_b32_e32 v90, v2
	v_mov_b32_e32 v91, v2
	v_mov_b32_e32 v92, v2
	v_mov_b32_e32 v93, v2
	v_mov_b32_e32 v94, v2
	v_mov_b32_e32 v95, v2
	v_mov_b32_e32 v96, v2
	v_mov_b32_e32 v97, v2
	v_mov_b32_e32 v106, v2
	v_mov_b32_e32 v107, v2
	v_mov_b32_e32 v108, v2
	v_mov_b32_e32 v109, v2
	v_mov_b32_e32 v114, v2
	v_mov_b32_e32 v115, v2
	v_mov_b32_e32 v116, v2
	v_mov_b32_e32 v117, v2
	v_mov_b32_e32 v82, v2
	v_mov_b32_e32 v83, v2
	v_mov_b32_e32 v84, v2
	v_mov_b32_e32 v85, v2
	v_mov_b32_e32 v86, v2
	v_mov_b32_e32 v87, v2
	v_mov_b32_e32 v88, v2
	v_mov_b32_e32 v89, v2
	v_mov_b32_e32 v98, v2
	v_mov_b32_e32 v99, v2
	v_mov_b32_e32 v100, v2
	v_mov_b32_e32 v101, v2
	v_mov_b32_e32 v102, v2
	v_mov_b32_e32 v103, v2
	v_mov_b32_e32 v104, v2
	v_mov_b32_e32 v105, v2
	v_mov_b32_e32 v110, v2
	v_mov_b32_e32 v111, v2
	v_mov_b32_e32 v112, v2
	v_mov_b32_e32 v113, v2
	v_mov_b32_e32 v118, v2
	v_mov_b32_e32 v119, v2
	v_mov_b32_e32 v120, v2
	v_mov_b32_e32 v121, v2
	v_mov_b32_e32 v122, v2
	v_mov_b32_e32 v123, v2
	v_mov_b32_e32 v124, v2
	v_mov_b32_e32 v125, v2
	v_mov_b32_e32 v126, v2
	v_mov_b32_e32 v127, v2
	v_mov_b32_e32 v128, v2
	v_mov_b32_e32 v129, v2
	.p2align	6

.LBB0_476:
	s_add_u32 s22, s2, s49
	s_addc_u32 s23, s3, s29
	s_and_b64 s[26:27], s[20:21], exec
	s_cselect_b32 s63, s23, s37
	s_cselect_b32 s64, s22, s36
	s_add_u32 s26, s16, s12
	s_addc_u32 s27, s17, s13
	s_and_b64 s[42:43], s[20:21], exec
	s_cselect_b32 s65, s27, s39
	s_cselect_b32 s66, s26, s38
	s_add_u32 s36, s36, 0x20080
	s_addc_u32 s37, s37, 0
	s_add_u32 s67, s38, 0x100
	s_addc_u32 s68, s39, 0
	s_mov_b32 s69, -2
	ds_read_b128 v[148:151], v144
	ds_read_b128 v[152:155], v144 offset:1024
	ds_read_b128 v[156:159], v144 offset:2048
	ds_read_b128 v[160:163], v144 offset:3072
	ds_read_b128 v[164:167], v145
	ds_read_b128 v[168:171], v145 offset:1024
	ds_read_b128 v[172:175], v145 offset:2048
	ds_read_b128 v[176:179], v145 offset:3072
	s_add_u32 s38, s36, 0xfffe0080
	s_addc_u32 s39, s37, -1
	s_cmp_eq_u32 s69, 4
	s_cselect_b32 s43, s63, s39
	s_cselect_b32 s42, s64, s38
	s_cselect_b32 s39, s65, s68
	s_cselect_b32 s38, s66, s67
	v_lshl_add_u64 v[214:215], s[36:37], 0, v[138:139]
	s_add_i32 m0, s19, 0xc000
	ds_read_b128 v[180:183], v146
	ds_read_b128 v[184:187], v146 offset:1024
	ds_read_b128 v[188:191], v146 offset:2048
	ds_read_b128 v[192:195], v146 offset:3072
	ds_read_b128 v[196:199], v146 offset:4096
	ds_read_b128 v[200:203], v146 offset:5120
	ds_read_b128 v[206:209], v146 offset:6144
	ds_read_b128 v[210:213], v146 offset:7168
	global_load_lds_dwordx4 v[214:215], off
	s_add_i32 m0, s19, 0xe000
	v_lshl_add_u64 v[214:215], s[36:37], 0, v[140:141]
	global_load_lds_dwordx4 v[214:215], off
	s_waitcnt vmcnt(8) lgkmcnt(0)
	s_setprio 1
	s_barrier
	v_mfma_f32_16x16x32_bf16 v[126:129], v[148:151], v[180:183], 0
	v_mfma_f32_16x16x32_bf16 v[122:125], v[156:159], v[180:183], 0
	v_mfma_f32_16x16x32_bf16 v[118:121], v[148:151], v[188:191], 0
	v_mfma_f32_16x16x32_bf16 v[114:117], v[156:159], v[188:191], 0
	v_mfma_f32_16x16x32_bf16 v[102:105], v[148:151], v[196:199], 0
	v_mfma_f32_16x16x32_bf16 v[98:101], v[156:159], v[196:199], 0
	v_mfma_f32_16x16x32_bf16 v[86:89], v[148:151], v[206:209], 0
	v_mfma_f32_16x16x32_bf16 v[82:85], v[156:159], v[206:209], 0
	v_mfma_f32_16x16x32_bf16 v[126:129], v[152:155], v[184:187], v[126:129]
	v_mfma_f32_16x16x32_bf16 v[122:125], v[160:163], v[184:187], v[122:125]
	v_mfma_f32_16x16x32_bf16 v[118:121], v[152:155], v[192:195], v[118:121]
	v_mfma_f32_16x16x32_bf16 v[114:117], v[160:163], v[192:195], v[114:117]
	v_mfma_f32_16x16x32_bf16 v[102:105], v[152:155], v[200:203], v[102:105]
	v_mfma_f32_16x16x32_bf16 v[98:101], v[160:163], v[200:203], v[98:101]
	v_mfma_f32_16x16x32_bf16 v[86:89], v[152:155], v[210:213], v[86:89]
	v_mfma_f32_16x16x32_bf16 v[82:85], v[160:163], v[210:213], v[82:85]
	v_mfma_f32_16x16x32_bf16 v[110:113], v[164:167], v[180:183], 0
	v_mfma_f32_16x16x32_bf16 v[106:109], v[172:175], v[180:183], 0
	v_mfma_f32_16x16x32_bf16 v[94:97], v[164:167], v[188:191], 0
	v_mfma_f32_16x16x32_bf16 v[90:93], v[172:175], v[188:191], 0
	v_mfma_f32_16x16x32_bf16 v[78:81], v[164:167], v[196:199], 0
	v_mfma_f32_16x16x32_bf16 v[74:77], v[172:175], v[196:199], 0
	v_mfma_f32_16x16x32_bf16 v[70:73], v[164:167], v[206:209], 0
	v_mfma_f32_16x16x32_bf16 v[66:69], v[172:175], v[206:209], 0
	v_mfma_f32_16x16x32_bf16 v[110:113], v[168:171], v[184:187], v[110:113]
	v_mfma_f32_16x16x32_bf16 v[106:109], v[176:179], v[184:187], v[106:109]
	v_mfma_f32_16x16x32_bf16 v[94:97], v[168:171], v[192:195], v[94:97]
	v_mfma_f32_16x16x32_bf16 v[90:93], v[176:179], v[192:195], v[90:93]
	v_mfma_f32_16x16x32_bf16 v[78:81], v[168:171], v[200:203], v[78:81]
	v_mfma_f32_16x16x32_bf16 v[74:77], v[176:179], v[200:203], v[74:77]
	v_mfma_f32_16x16x32_bf16 v[70:73], v[168:171], v[210:213], v[70:73]
	v_mfma_f32_16x16x32_bf16 v[66:69], v[176:179], v[210:213], v[66:69]
	s_setprio 0
	s_barrier
	s_add_i32 s70, s35, s18
	v_lshl_add_u64 v[214:215], s[38:39], 0, v[134:135]
	s_mov_b32 m0, s70
	ds_read_b128 v[180:183], v146 offset:16384
	ds_read_b128 v[184:187], v146 offset:17408
	ds_read_b128 v[188:191], v146 offset:18432
	ds_read_b128 v[192:195], v146 offset:19456
	ds_read_b128 v[196:199], v146 offset:20480
	ds_read_b128 v[200:203], v146 offset:21504
	ds_read_b128 v[206:209], v146 offset:22528
	ds_read_b128 v[210:213], v146 offset:23552
	global_load_lds_dwordx4 v[214:215], off
	s_add_i32 m0, s70, 0x2000
	s_add_u32 s70, s38, 0x200000
	v_lshl_add_u64 v[216:217], s[38:39], 0, v[130:131]
	s_addc_u32 s71, s39, 0
	s_add_i32 s72, s44, s18
	global_load_lds_dwordx4 v[216:217], off
	v_lshl_add_u64 v[218:219], s[70:71], 0, v[134:135]
	s_mov_b32 m0, s72
	v_lshl_add_u64 v[220:221], s[42:43], 0, v[132:133]
	global_load_lds_dwordx4 v[218:219], off
	s_add_i32 m0, s72, 0x2000
	v_lshl_add_u64 v[218:219], s[70:71], 0, v[130:131]
	global_load_lds_dwordx4 v[218:219], off
	s_mov_b32 m0, s19
	v_lshl_add_u64 v[218:219], s[42:43], 0, v[136:137]
	global_load_lds_dwordx4 v[218:219], off
	s_mov_b32 m0, s24
	s_nop 0
	global_load_lds_dwordx4 v[220:221], off
	s_waitcnt vmcnt(8) lgkmcnt(0)
	s_setprio 1
	s_barrier
	v_mfma_f32_16x16x32_bf16 v[62:65], v[148:151], v[180:183], 0
	v_mfma_f32_16x16x32_bf16 v[58:61], v[156:159], v[180:183], 0
	v_mfma_f32_16x16x32_bf16 v[54:57], v[148:151], v[188:191], 0
	v_mfma_f32_16x16x32_bf16 v[50:53], v[156:159], v[188:191], 0
	v_mfma_f32_16x16x32_bf16 v[38:41], v[148:151], v[196:199], 0
	v_mfma_f32_16x16x32_bf16 v[34:37], v[156:159], v[196:199], 0
	v_mfma_f32_16x16x32_bf16 v[22:25], v[148:151], v[206:209], 0
	v_mfma_f32_16x16x32_bf16 v[18:21], v[156:159], v[206:209], 0
	v_mfma_f32_16x16x32_bf16 v[62:65], v[152:155], v[184:187], v[62:65]
	v_mfma_f32_16x16x32_bf16 v[58:61], v[160:163], v[184:187], v[58:61]
	v_mfma_f32_16x16x32_bf16 v[54:57], v[152:155], v[192:195], v[54:57]
	v_mfma_f32_16x16x32_bf16 v[50:53], v[160:163], v[192:195], v[50:53]
	v_mfma_f32_16x16x32_bf16 v[38:41], v[152:155], v[200:203], v[38:41]
	v_mfma_f32_16x16x32_bf16 v[34:37], v[160:163], v[200:203], v[34:37]
	v_mfma_f32_16x16x32_bf16 v[22:25], v[152:155], v[210:213], v[22:25]
	v_mfma_f32_16x16x32_bf16 v[18:21], v[160:163], v[210:213], v[18:21]
	v_mfma_f32_16x16x32_bf16 v[46:49], v[164:167], v[180:183], 0
	v_mfma_f32_16x16x32_bf16 v[42:45], v[172:175], v[180:183], 0
	v_mfma_f32_16x16x32_bf16 v[30:33], v[164:167], v[188:191], 0
	v_mfma_f32_16x16x32_bf16 v[26:29], v[172:175], v[188:191], 0
	v_mfma_f32_16x16x32_bf16 v[14:17], v[164:167], v[196:199], 0
	v_mfma_f32_16x16x32_bf16 v[10:13], v[172:175], v[196:199], 0
	v_mfma_f32_16x16x32_bf16 v[6:9], v[164:167], v[206:209], 0
	v_mfma_f32_16x16x32_bf16 v[2:5], v[172:175], v[206:209], 0
	v_mfma_f32_16x16x32_bf16 v[46:49], v[168:171], v[184:187], v[46:49]
	v_mfma_f32_16x16x32_bf16 v[42:45], v[176:179], v[184:187], v[42:45]
	v_mfma_f32_16x16x32_bf16 v[30:33], v[168:171], v[192:195], v[30:33]
	v_mfma_f32_16x16x32_bf16 v[26:29], v[176:179], v[192:195], v[26:29]
	v_mfma_f32_16x16x32_bf16 v[14:17], v[168:171], v[200:203], v[14:17]
	v_mfma_f32_16x16x32_bf16 v[10:13], v[176:179], v[200:203], v[10:13]
	v_mfma_f32_16x16x32_bf16 v[6:9], v[168:171], v[210:213], v[6:9]
	v_mfma_f32_16x16x32_bf16 v[2:5], v[176:179], v[210:213], v[2:5]
	s_setprio 0
	s_barrier
	s_add_i32 s70, 0, 0x18000
	v_add_u32_e32 v147, s70, v143
	s_add_i32 s71, 0, 0x1c000
	ds_read_b128 v[148:151], v147
	ds_read_b128 v[152:155], v147 offset:1024
	ds_read_b128 v[156:159], v147 offset:2048
	ds_read_b128 v[160:163], v147 offset:3072
	v_add_u32_e32 v147, s71, v143
	ds_read_b128 v[164:167], v147
	ds_read_b128 v[168:171], v147 offset:1024
	ds_read_b128 v[172:175], v147 offset:2048
	ds_read_b128 v[176:179], v147 offset:3072
	s_add_u32 s42, s42, 0x20000
	s_addc_u32 s43, s43, 0
	s_mov_b32 m0, s25
	v_lshl_add_u64 v[222:223], s[42:43], 0, v[136:137]
	ds_read_b128 v[180:183], v146 offset:32768
	ds_read_b128 v[184:187], v146 offset:33792
	ds_read_b128 v[188:191], v146 offset:34816
	ds_read_b128 v[192:195], v146 offset:35840
	ds_read_b128 v[196:199], v146 offset:36864
	ds_read_b128 v[200:203], v146 offset:37888
	ds_read_b128 v[206:209], v146 offset:38912
	ds_read_b128 v[210:213], v146 offset:39936
	global_load_lds_dwordx4 v[222:223], off
	s_mov_b32 m0, s28
	v_lshl_add_u64 v[222:223], s[42:43], 0, v[132:133]
	global_load_lds_dwordx4 v[222:223], off
	s_waitcnt vmcnt(8) lgkmcnt(0)
	s_setprio 1
	s_barrier
	v_mfma_f32_16x16x32_bf16 v[126:129], v[148:151], v[180:183], v[126:129]
	v_mfma_f32_16x16x32_bf16 v[122:125], v[156:159], v[180:183], v[122:125]
	v_mfma_f32_16x16x32_bf16 v[118:121], v[148:151], v[188:191], v[118:121]
	v_mfma_f32_16x16x32_bf16 v[114:117], v[156:159], v[188:191], v[114:117]
	v_mfma_f32_16x16x32_bf16 v[102:105], v[148:151], v[196:199], v[102:105]
	v_mfma_f32_16x16x32_bf16 v[98:101], v[156:159], v[196:199], v[98:101]
	v_mfma_f32_16x16x32_bf16 v[86:89], v[148:151], v[206:209], v[86:89]
	v_mfma_f32_16x16x32_bf16 v[82:85], v[156:159], v[206:209], v[82:85]
	v_mfma_f32_16x16x32_bf16 v[126:129], v[152:155], v[184:187], v[126:129]
	v_mfma_f32_16x16x32_bf16 v[122:125], v[160:163], v[184:187], v[122:125]
	v_mfma_f32_16x16x32_bf16 v[118:121], v[152:155], v[192:195], v[118:121]
	v_mfma_f32_16x16x32_bf16 v[114:117], v[160:163], v[192:195], v[114:117]
	v_mfma_f32_16x16x32_bf16 v[102:105], v[152:155], v[200:203], v[102:105]
	v_mfma_f32_16x16x32_bf16 v[98:101], v[160:163], v[200:203], v[98:101]
	v_mfma_f32_16x16x32_bf16 v[86:89], v[152:155], v[210:213], v[86:89]
	v_mfma_f32_16x16x32_bf16 v[82:85], v[160:163], v[210:213], v[82:85]
	v_mfma_f32_16x16x32_bf16 v[110:113], v[164:167], v[180:183], v[110:113]
	v_mfma_f32_16x16x32_bf16 v[106:109], v[172:175], v[180:183], v[106:109]
	v_mfma_f32_16x16x32_bf16 v[94:97], v[164:167], v[188:191], v[94:97]
	v_mfma_f32_16x16x32_bf16 v[90:93], v[172:175], v[188:191], v[90:93]
	v_mfma_f32_16x16x32_bf16 v[78:81], v[164:167], v[196:199], v[78:81]
	v_mfma_f32_16x16x32_bf16 v[74:77], v[172:175], v[196:199], v[74:77]
	v_mfma_f32_16x16x32_bf16 v[70:73], v[164:167], v[206:209], v[70:73]
	v_mfma_f32_16x16x32_bf16 v[66:69], v[172:175], v[206:209], v[66:69]
	v_mfma_f32_16x16x32_bf16 v[110:113], v[168:171], v[184:187], v[110:113]
	v_mfma_f32_16x16x32_bf16 v[106:109], v[176:179], v[184:187], v[106:109]
	v_mfma_f32_16x16x32_bf16 v[94:97], v[168:171], v[192:195], v[94:97]
	v_mfma_f32_16x16x32_bf16 v[90:93], v[176:179], v[192:195], v[90:93]
	v_mfma_f32_16x16x32_bf16 v[78:81], v[168:171], v[200:203], v[78:81]
	v_mfma_f32_16x16x32_bf16 v[74:77], v[176:179], v[200:203], v[74:77]
	v_mfma_f32_16x16x32_bf16 v[70:73], v[168:171], v[210:213], v[70:73]
	v_mfma_f32_16x16x32_bf16 v[66:69], v[176:179], v[210:213], v[66:69]
	s_setprio 0
	s_barrier
	s_add_i32 s42, s70, s18
	v_lshl_add_u64 v[214:215], v[214:215], 0, s[8:9]
	s_mov_b32 m0, s42
	ds_read_b128 v[180:183], v146 offset:49152
	ds_read_b128 v[184:187], v146 offset:50176
	ds_read_b128 v[188:191], v146 offset:51200
	ds_read_b128 v[192:195], v146 offset:52224
	ds_read_b128 v[196:199], v146 offset:53248
	ds_read_b128 v[200:203], v146 offset:54272
	ds_read_b128 v[206:209], v146 offset:55296
	ds_read_b128 v[210:213], v146 offset:56320
	global_load_lds_dwordx4 v[214:215], off
	s_add_i32 m0, s42, 0x2000
	s_add_u32 s38, s38, 0x200080
	v_lshl_add_u64 v[214:215], v[216:217], 0, s[8:9]
	s_addc_u32 s39, s39, 0
	s_add_i32 s42, s71, s18
	global_load_lds_dwordx4 v[214:215], off
	s_mov_b32 m0, s42
	v_lshl_add_u64 v[214:215], s[38:39], 0, v[134:135]
	global_load_lds_dwordx4 v[214:215], off
	s_add_i32 m0, s42, 0x2000
	v_lshl_add_u64 v[214:215], s[38:39], 0, v[130:131]
	global_load_lds_dwordx4 v[214:215], off
	s_mov_b32 m0, s33
	v_lshl_add_u64 v[214:215], v[218:219], 0, s[8:9]
	global_load_lds_dwordx4 v[214:215], off
	s_mov_b32 m0, s34
	v_lshl_add_u64 v[214:215], v[220:221], 0, s[8:9]
	global_load_lds_dwordx4 v[214:215], off
	s_waitcnt vmcnt(8) lgkmcnt(0)
	s_setprio 1
	s_barrier
	v_mfma_f32_16x16x32_bf16 v[62:65], v[148:151], v[180:183], v[62:65]
	v_mfma_f32_16x16x32_bf16 v[58:61], v[156:159], v[180:183], v[58:61]
	v_mfma_f32_16x16x32_bf16 v[54:57], v[148:151], v[188:191], v[54:57]
	v_mfma_f32_16x16x32_bf16 v[50:53], v[156:159], v[188:191], v[50:53]
	v_mfma_f32_16x16x32_bf16 v[38:41], v[148:151], v[196:199], v[38:41]
	v_mfma_f32_16x16x32_bf16 v[34:37], v[156:159], v[196:199], v[34:37]
	v_mfma_f32_16x16x32_bf16 v[22:25], v[148:151], v[206:209], v[22:25]
	v_mfma_f32_16x16x32_bf16 v[18:21], v[156:159], v[206:209], v[18:21]
	v_mfma_f32_16x16x32_bf16 v[62:65], v[152:155], v[184:187], v[62:65]
	v_mfma_f32_16x16x32_bf16 v[58:61], v[160:163], v[184:187], v[58:61]
	v_mfma_f32_16x16x32_bf16 v[54:57], v[152:155], v[192:195], v[54:57]
	v_mfma_f32_16x16x32_bf16 v[50:53], v[160:163], v[192:195], v[50:53]
	v_mfma_f32_16x16x32_bf16 v[38:41], v[152:155], v[200:203], v[38:41]
	v_mfma_f32_16x16x32_bf16 v[34:37], v[160:163], v[200:203], v[34:37]
	v_mfma_f32_16x16x32_bf16 v[22:25], v[152:155], v[210:213], v[22:25]
	v_mfma_f32_16x16x32_bf16 v[18:21], v[160:163], v[210:213], v[18:21]
	v_mfma_f32_16x16x32_bf16 v[46:49], v[164:167], v[180:183], v[46:49]
	v_mfma_f32_16x16x32_bf16 v[42:45], v[172:175], v[180:183], v[42:45]
	v_mfma_f32_16x16x32_bf16 v[30:33], v[164:167], v[188:191], v[30:33]
	v_mfma_f32_16x16x32_bf16 v[26:29], v[172:175], v[188:191], v[26:29]
	v_mfma_f32_16x16x32_bf16 v[14:17], v[164:167], v[196:199], v[14:17]
	v_mfma_f32_16x16x32_bf16 v[10:13], v[172:175], v[196:199], v[10:13]
	v_mfma_f32_16x16x32_bf16 v[6:9], v[164:167], v[206:209], v[6:9]
	v_mfma_f32_16x16x32_bf16 v[2:5], v[172:175], v[206:209], v[2:5]
	v_mfma_f32_16x16x32_bf16 v[46:49], v[168:171], v[184:187], v[46:49]
	v_mfma_f32_16x16x32_bf16 v[42:45], v[176:179], v[184:187], v[42:45]
	v_mfma_f32_16x16x32_bf16 v[30:33], v[168:171], v[192:195], v[30:33]
	v_mfma_f32_16x16x32_bf16 v[26:29], v[176:179], v[192:195], v[26:29]
	v_mfma_f32_16x16x32_bf16 v[14:17], v[168:171], v[200:203], v[14:17]
	v_mfma_f32_16x16x32_bf16 v[10:13], v[176:179], v[200:203], v[10:13]
	v_mfma_f32_16x16x32_bf16 v[6:9], v[168:171], v[210:213], v[6:9]
	v_mfma_f32_16x16x32_bf16 v[2:5], v[176:179], v[210:213], v[2:5]
	s_setprio 0
	s_barrier
	s_add_i32 s69, s69, 2
	s_add_u32 s36, s36, 0x100
	s_addc_u32 s37, s37, 0
	s_add_u32 s67, s67, 0x100
	s_addc_u32 s68, s68, 0
	s_cmp_gt_u32 s69, 5
	.p2align	6

.LBB0_565:
	v_readlane_b32 s62, v249, 27
	v_readlane_b32 s63, v249, 28
	s_add_u32 s72, s62, s68
	s_addc_u32 s73, s63, s69
	s_and_b64 s[62:63], s[70:71], exec
	s_cselect_b32 s31, s73, s77
	s_cselect_b32 s33, s72, s76
	s_add_u32 s74, s35, s66
	s_addc_u32 s75, s85, s67
	s_and_b64 s[62:63], s[70:71], exec
	s_cselect_b32 s34, s75, s79
	s_cselect_b32 s39, s74, s78
	s_add_i32 s45, s7, -2
	s_add_u32 s76, s76, 0x40080
	s_addc_u32 s77, s77, 0
	s_add_u32 s47, s78, 0x100
	s_addc_u32 s62, s79, 0
	s_mov_b32 s63, 0
	s_waitcnt vmcnt(0)
	ds_read_b128 v[114:117], v190
	ds_read_b128 v[118:121], v190 offset:1024
	ds_read_b128 v[122:125], v190 offset:2048
	ds_read_b128 v[126:129], v190 offset:3072
	ds_read_b128 v[146:149], v191
	ds_read_b128 v[150:153], v191 offset:1024
	ds_read_b128 v[154:157], v191 offset:2048
	ds_read_b128 v[158:161], v191 offset:3072
	s_add_i32 s82, s63, 2
	s_add_u32 s78, s76, 0xfffc0080
	s_addc_u32 s79, s77, -1
	s_cmp_eq_u32 s45, s63
	s_cselect_b32 s81, s31, s79
	s_cselect_b32 s80, s33, s78
	s_cselect_b32 s79, s34, s62
	s_cselect_b32 s78, s39, s47
	v_lshl_add_u64 v[186:187], s[76:77], 0, v[180:181]
	s_add_i32 m0, s87, 0xc000
	ds_read_b128 v[162:165], v192
	ds_read_b128 v[166:169], v192 offset:1024
	ds_read_b128 v[194:197], v192 offset:2048
	ds_read_b128 v[198:201], v192 offset:3072
	ds_read_b128 v[206:209], v192 offset:4096
	ds_read_b128 v[210:213], v192 offset:5120
	ds_read_b128 v[214:217], v192 offset:6144
	ds_read_b128 v[218:221], v192 offset:7168
	global_load_lds_dwordx4 v[186:187], off
	s_add_i32 m0, s87, 0xe000
	v_lshl_add_u64 v[186:187], s[76:77], 0, v[182:183]
	global_load_lds_dwordx4 v[186:187], off
	s_waitcnt vmcnt(8)
	s_waitcnt lgkmcnt(0)
	s_setprio 1
	s_barrier
	v_mfma_f32_16x16x32_bf16 v[142:145], v[114:117], v[162:165], 0
	v_mfma_f32_16x16x32_bf16 v[138:141], v[122:125], v[162:165], 0
	v_mfma_f32_16x16x32_bf16 v[110:113], v[114:117], v[194:197], 0
	v_mfma_f32_16x16x32_bf16 v[106:109], v[122:125], v[194:197], 0
	v_mfma_f32_16x16x32_bf16 v[98:101], v[114:117], v[206:209], 0
	v_mfma_f32_16x16x32_bf16 v[90:93], v[122:125], v[206:209], 0
	v_mfma_f32_16x16x32_bf16 v[82:85], v[114:117], v[214:217], 0
	v_mfma_f32_16x16x32_bf16 v[74:77], v[122:125], v[214:217], 0
	v_mfma_f32_16x16x32_bf16 v[142:145], v[118:121], v[166:169], v[142:145]
	v_mfma_f32_16x16x32_bf16 v[138:141], v[126:129], v[166:169], v[138:141]
	v_mfma_f32_16x16x32_bf16 v[110:113], v[118:121], v[198:201], v[110:113]
	v_mfma_f32_16x16x32_bf16 v[106:109], v[126:129], v[198:201], v[106:109]
	v_mfma_f32_16x16x32_bf16 v[98:101], v[118:121], v[210:213], v[98:101]
	v_mfma_f32_16x16x32_bf16 v[90:93], v[126:129], v[210:213], v[90:93]
	v_mfma_f32_16x16x32_bf16 v[82:85], v[118:121], v[218:221], v[82:85]
	v_mfma_f32_16x16x32_bf16 v[74:77], v[126:129], v[218:221], v[74:77]
	v_mfma_f32_16x16x32_bf16 v[134:137], v[146:149], v[162:165], 0
	v_mfma_f32_16x16x32_bf16 v[130:133], v[154:157], v[162:165], 0
	v_mfma_f32_16x16x32_bf16 v[102:105], v[146:149], v[194:197], 0
	v_mfma_f32_16x16x32_bf16 v[94:97], v[154:157], v[194:197], 0
	v_mfma_f32_16x16x32_bf16 v[86:89], v[146:149], v[206:209], 0
	v_mfma_f32_16x16x32_bf16 v[78:81], v[154:157], v[206:209], 0
	v_mfma_f32_16x16x32_bf16 v[70:73], v[146:149], v[214:217], 0
	v_mfma_f32_16x16x32_bf16 v[66:69], v[154:157], v[214:217], 0
	v_mfma_f32_16x16x32_bf16 v[134:137], v[150:153], v[166:169], v[134:137]
	v_mfma_f32_16x16x32_bf16 v[130:133], v[158:161], v[166:169], v[130:133]
	v_mfma_f32_16x16x32_bf16 v[102:105], v[150:153], v[198:201], v[102:105]
	v_mfma_f32_16x16x32_bf16 v[94:97], v[158:161], v[198:201], v[94:97]
	v_mfma_f32_16x16x32_bf16 v[86:89], v[150:153], v[210:213], v[86:89]
	v_mfma_f32_16x16x32_bf16 v[78:81], v[158:161], v[210:213], v[78:81]
	v_mfma_f32_16x16x32_bf16 v[70:73], v[150:153], v[218:221], v[70:73]
	v_mfma_f32_16x16x32_bf16 v[66:69], v[158:161], v[218:221], v[66:69]
	s_setprio 0
	s_barrier
	s_add_i32 s63, s24, s86
	v_lshl_add_u64 v[186:187], s[78:79], 0, v[172:173]
	s_mov_b32 m0, s63
	ds_read_b128 v[162:165], v192 offset:16384
	ds_read_b128 v[166:169], v192 offset:17408
	ds_read_b128 v[194:197], v192 offset:18432
	ds_read_b128 v[198:201], v192 offset:19456
	ds_read_b128 v[206:209], v192 offset:20480
	ds_read_b128 v[210:213], v192 offset:21504
	ds_read_b128 v[214:217], v192 offset:22528
	ds_read_b128 v[218:221], v192 offset:23552
	global_load_lds_dwordx4 v[186:187], off
	s_add_i32 m0, s63, 0x2000
	s_add_u32 vcc_lo, s78, 0x40000
	v_lshl_add_u64 v[202:203], s[78:79], 0, v[176:177]
	s_addc_u32 vcc_hi, s79, 0
	s_add_i32 s63, s25, s86
	global_load_lds_dwordx4 v[202:203], off
	v_lshl_add_u64 v[222:223], vcc, 0, v[172:173]
	s_mov_b32 m0, s63
	v_lshl_add_u64 v[224:225], s[80:81], 0, v[174:175]
	global_load_lds_dwordx4 v[222:223], off
	s_add_i32 m0, s63, 0x2000
	v_lshl_add_u64 v[222:223], vcc, 0, v[176:177]
	global_load_lds_dwordx4 v[222:223], off
	s_mov_b32 m0, s87
	v_lshl_add_u64 v[222:223], s[80:81], 0, v[170:171]
	global_load_lds_dwordx4 v[222:223], off
	s_mov_b32 m0, s88
	s_nop 0
	global_load_lds_dwordx4 v[224:225], off
	s_waitcnt vmcnt(8) lgkmcnt(0)
	s_setprio 1
	s_barrier
	v_mfma_f32_16x16x32_bf16 v[62:65], v[114:117], v[162:165], 0
	v_mfma_f32_16x16x32_bf16 v[58:61], v[122:125], v[162:165], 0
	v_mfma_f32_16x16x32_bf16 v[50:53], v[114:117], v[194:197], 0
	v_mfma_f32_16x16x32_bf16 v[42:45], v[122:125], v[194:197], 0
	v_mfma_f32_16x16x32_bf16 v[34:37], v[114:117], v[206:209], 0
	v_mfma_f32_16x16x32_bf16 v[26:29], v[122:125], v[206:209], 0
	v_mfma_f32_16x16x32_bf16 v[18:21], v[114:117], v[214:217], 0
	v_mfma_f32_16x16x32_bf16 v[10:13], v[122:125], v[214:217], 0
	v_mfma_f32_16x16x32_bf16 v[62:65], v[118:121], v[166:169], v[62:65]
	v_mfma_f32_16x16x32_bf16 v[58:61], v[126:129], v[166:169], v[58:61]
	v_mfma_f32_16x16x32_bf16 v[50:53], v[118:121], v[198:201], v[50:53]
	v_mfma_f32_16x16x32_bf16 v[42:45], v[126:129], v[198:201], v[42:45]
	v_mfma_f32_16x16x32_bf16 v[34:37], v[118:121], v[210:213], v[34:37]
	v_mfma_f32_16x16x32_bf16 v[26:29], v[126:129], v[210:213], v[26:29]
	v_mfma_f32_16x16x32_bf16 v[18:21], v[118:121], v[218:221], v[18:21]
	v_mfma_f32_16x16x32_bf16 v[10:13], v[126:129], v[218:221], v[10:13]
	v_mfma_f32_16x16x32_bf16 v[54:57], v[146:149], v[162:165], 0
	v_mfma_f32_16x16x32_bf16 v[46:49], v[154:157], v[162:165], 0
	v_mfma_f32_16x16x32_bf16 v[38:41], v[146:149], v[194:197], 0
	v_mfma_f32_16x16x32_bf16 v[30:33], v[154:157], v[194:197], 0
	v_mfma_f32_16x16x32_bf16 v[22:25], v[146:149], v[206:209], 0
	v_mfma_f32_16x16x32_bf16 v[14:17], v[154:157], v[206:209], 0
	v_mfma_f32_16x16x32_bf16 v[6:9], v[146:149], v[214:217], 0
	v_mfma_f32_16x16x32_bf16 v[2:5], v[154:157], v[214:217], 0
	v_mfma_f32_16x16x32_bf16 v[54:57], v[150:153], v[166:169], v[54:57]
	v_mfma_f32_16x16x32_bf16 v[46:49], v[158:161], v[166:169], v[46:49]
	v_mfma_f32_16x16x32_bf16 v[38:41], v[150:153], v[198:201], v[38:41]
	v_mfma_f32_16x16x32_bf16 v[30:33], v[158:161], v[198:201], v[30:33]
	v_mfma_f32_16x16x32_bf16 v[22:25], v[150:153], v[210:213], v[22:25]
	v_mfma_f32_16x16x32_bf16 v[14:17], v[158:161], v[210:213], v[14:17]
	v_mfma_f32_16x16x32_bf16 v[6:9], v[150:153], v[218:221], v[6:9]
	v_mfma_f32_16x16x32_bf16 v[2:5], v[158:161], v[218:221], v[2:5]
	s_setprio 0
	s_barrier
	s_add_i32 s63, 0, 0x18000
	s_add_i32 s83, 0, 0x1c000
	v_add_u32_e32 v126, s63, v189
	v_add_u32_e32 v158, s83, v189
	ds_read_b128 v[114:117], v126
	ds_read_b128 v[118:121], v126 offset:1024
	ds_read_b128 v[122:125], v126 offset:2048
	ds_read_b128 v[126:129], v126 offset:3072
	ds_read_b128 v[146:149], v158
	ds_read_b128 v[150:153], v158 offset:1024
	ds_read_b128 v[154:157], v158 offset:2048
	ds_read_b128 v[158:161], v158 offset:3072
	s_add_u32 s80, s80, 0x40000
	s_addc_u32 s81, s81, 0
	s_mov_b32 m0, s89
	v_lshl_add_u64 v[226:227], s[80:81], 0, v[170:171]
	ds_read_b128 v[162:165], v192 offset:32768
	ds_read_b128 v[166:169], v192 offset:33792
	ds_read_b128 v[194:197], v192 offset:34816
	ds_read_b128 v[198:201], v192 offset:35840
	ds_read_b128 v[206:209], v192 offset:36864
	ds_read_b128 v[210:213], v192 offset:37888
	ds_read_b128 v[214:217], v192 offset:38912
	ds_read_b128 v[218:221], v192 offset:39936
	global_load_lds_dwordx4 v[226:227], off
	s_mov_b32 m0, s90
	v_lshl_add_u64 v[226:227], s[80:81], 0, v[174:175]
	global_load_lds_dwordx4 v[226:227], off
	s_waitcnt vmcnt(8) lgkmcnt(0)
	s_setprio 1
	s_barrier
	v_mfma_f32_16x16x32_bf16 v[142:145], v[114:117], v[162:165], v[142:145]
	v_mfma_f32_16x16x32_bf16 v[138:141], v[122:125], v[162:165], v[138:141]
	v_mfma_f32_16x16x32_bf16 v[110:113], v[114:117], v[194:197], v[110:113]
	v_mfma_f32_16x16x32_bf16 v[106:109], v[122:125], v[194:197], v[106:109]
	v_mfma_f32_16x16x32_bf16 v[98:101], v[114:117], v[206:209], v[98:101]
	v_mfma_f32_16x16x32_bf16 v[90:93], v[122:125], v[206:209], v[90:93]
	v_mfma_f32_16x16x32_bf16 v[82:85], v[114:117], v[214:217], v[82:85]
	v_mfma_f32_16x16x32_bf16 v[74:77], v[122:125], v[214:217], v[74:77]
	v_mfma_f32_16x16x32_bf16 v[142:145], v[118:121], v[166:169], v[142:145]
	v_mfma_f32_16x16x32_bf16 v[138:141], v[126:129], v[166:169], v[138:141]
	v_mfma_f32_16x16x32_bf16 v[110:113], v[118:121], v[198:201], v[110:113]
	v_mfma_f32_16x16x32_bf16 v[106:109], v[126:129], v[198:201], v[106:109]
	v_mfma_f32_16x16x32_bf16 v[98:101], v[118:121], v[210:213], v[98:101]
	v_mfma_f32_16x16x32_bf16 v[90:93], v[126:129], v[210:213], v[90:93]
	v_mfma_f32_16x16x32_bf16 v[82:85], v[118:121], v[218:221], v[82:85]
	v_mfma_f32_16x16x32_bf16 v[74:77], v[126:129], v[218:221], v[74:77]
	v_mfma_f32_16x16x32_bf16 v[134:137], v[146:149], v[162:165], v[134:137]
	v_mfma_f32_16x16x32_bf16 v[130:133], v[154:157], v[162:165], v[130:133]
	v_mfma_f32_16x16x32_bf16 v[102:105], v[146:149], v[194:197], v[102:105]
	v_mfma_f32_16x16x32_bf16 v[94:97], v[154:157], v[194:197], v[94:97]
	v_mfma_f32_16x16x32_bf16 v[86:89], v[146:149], v[206:209], v[86:89]
	v_mfma_f32_16x16x32_bf16 v[78:81], v[154:157], v[206:209], v[78:81]
	v_mfma_f32_16x16x32_bf16 v[70:73], v[146:149], v[214:217], v[70:73]
	v_mfma_f32_16x16x32_bf16 v[66:69], v[154:157], v[214:217], v[66:69]
	v_mfma_f32_16x16x32_bf16 v[134:137], v[150:153], v[166:169], v[134:137]
	v_mfma_f32_16x16x32_bf16 v[130:133], v[158:161], v[166:169], v[130:133]
	v_mfma_f32_16x16x32_bf16 v[102:105], v[150:153], v[198:201], v[102:105]
	v_mfma_f32_16x16x32_bf16 v[94:97], v[158:161], v[198:201], v[94:97]
	v_mfma_f32_16x16x32_bf16 v[86:89], v[150:153], v[210:213], v[86:89]
	v_mfma_f32_16x16x32_bf16 v[78:81], v[158:161], v[210:213], v[78:81]
	v_mfma_f32_16x16x32_bf16 v[70:73], v[150:153], v[218:221], v[70:73]
	v_mfma_f32_16x16x32_bf16 v[66:69], v[158:161], v[218:221], v[66:69]
	s_setprio 0
	s_barrier
	s_add_i32 s63, s63, s86
	v_lshl_add_u64 v[186:187], v[186:187], 0, s[22:23]
	s_mov_b32 m0, s63
	ds_read_b128 v[162:165], v192 offset:49152
	ds_read_b128 v[166:169], v192 offset:50176
	ds_read_b128 v[194:197], v192 offset:51200
	ds_read_b128 v[198:201], v192 offset:52224
	ds_read_b128 v[206:209], v192 offset:53248
	ds_read_b128 v[210:213], v192 offset:54272
	ds_read_b128 v[214:217], v192 offset:55296
	ds_read_b128 v[218:221], v192 offset:56320
	global_load_lds_dwordx4 v[186:187], off
	s_add_i32 m0, s63, 0x2000
	s_add_u32 s78, s78, 0x40080
	v_lshl_add_u64 v[186:187], v[202:203], 0, s[22:23]
	s_addc_u32 s79, s79, 0
	s_add_i32 s63, s83, s86
	global_load_lds_dwordx4 v[186:187], off
	s_mov_b32 m0, s63
	v_lshl_add_u64 v[186:187], s[78:79], 0, v[172:173]
	global_load_lds_dwordx4 v[186:187], off
	s_add_i32 m0, s63, 0x2000
	v_lshl_add_u64 v[186:187], s[78:79], 0, v[176:177]
	global_load_lds_dwordx4 v[186:187], off
	s_mov_b32 m0, s95
	v_lshl_add_u64 v[186:187], v[222:223], 0, s[22:23]
	global_load_lds_dwordx4 v[186:187], off
	s_mov_b32 m0, s96
	v_lshl_add_u64 v[186:187], v[224:225], 0, s[22:23]
	global_load_lds_dwordx4 v[186:187], off
	s_waitcnt vmcnt(8) lgkmcnt(0)
	s_setprio 1
	s_barrier
	v_mfma_f32_16x16x32_bf16 v[62:65], v[114:117], v[162:165], v[62:65]
	v_mfma_f32_16x16x32_bf16 v[58:61], v[122:125], v[162:165], v[58:61]
	v_mfma_f32_16x16x32_bf16 v[50:53], v[114:117], v[194:197], v[50:53]
	v_mfma_f32_16x16x32_bf16 v[42:45], v[122:125], v[194:197], v[42:45]
	v_mfma_f32_16x16x32_bf16 v[34:37], v[114:117], v[206:209], v[34:37]
	v_mfma_f32_16x16x32_bf16 v[26:29], v[122:125], v[206:209], v[26:29]
	v_mfma_f32_16x16x32_bf16 v[18:21], v[114:117], v[214:217], v[18:21]
	v_mfma_f32_16x16x32_bf16 v[10:13], v[122:125], v[214:217], v[10:13]
	v_mfma_f32_16x16x32_bf16 v[62:65], v[118:121], v[166:169], v[62:65]
	v_mfma_f32_16x16x32_bf16 v[58:61], v[126:129], v[166:169], v[58:61]
	v_mfma_f32_16x16x32_bf16 v[50:53], v[118:121], v[198:201], v[50:53]
	v_mfma_f32_16x16x32_bf16 v[42:45], v[126:129], v[198:201], v[42:45]
	v_mfma_f32_16x16x32_bf16 v[34:37], v[118:121], v[210:213], v[34:37]
	v_mfma_f32_16x16x32_bf16 v[26:29], v[126:129], v[210:213], v[26:29]
	v_mfma_f32_16x16x32_bf16 v[18:21], v[118:121], v[218:221], v[18:21]
	v_mfma_f32_16x16x32_bf16 v[10:13], v[126:129], v[218:221], v[10:13]
	v_mfma_f32_16x16x32_bf16 v[54:57], v[146:149], v[162:165], v[54:57]
	v_mfma_f32_16x16x32_bf16 v[46:49], v[154:157], v[162:165], v[46:49]
	v_mfma_f32_16x16x32_bf16 v[38:41], v[146:149], v[194:197], v[38:41]
	v_mfma_f32_16x16x32_bf16 v[30:33], v[154:157], v[194:197], v[30:33]
	v_mfma_f32_16x16x32_bf16 v[22:25], v[146:149], v[206:209], v[22:25]
	v_mfma_f32_16x16x32_bf16 v[14:17], v[154:157], v[206:209], v[14:17]
	v_mfma_f32_16x16x32_bf16 v[6:9], v[146:149], v[214:217], v[6:9]
	v_mfma_f32_16x16x32_bf16 v[2:5], v[154:157], v[214:217], v[2:5]
	v_mfma_f32_16x16x32_bf16 v[54:57], v[150:153], v[166:169], v[54:57]
	v_mfma_f32_16x16x32_bf16 v[46:49], v[158:161], v[166:169], v[46:49]
	v_mfma_f32_16x16x32_bf16 v[38:41], v[150:153], v[198:201], v[38:41]
	v_mfma_f32_16x16x32_bf16 v[30:33], v[158:161], v[198:201], v[30:33]
	v_mfma_f32_16x16x32_bf16 v[22:25], v[150:153], v[210:213], v[22:25]
	v_mfma_f32_16x16x32_bf16 v[14:17], v[158:161], v[210:213], v[14:17]
	v_mfma_f32_16x16x32_bf16 v[6:9], v[150:153], v[218:221], v[6:9]
	v_mfma_f32_16x16x32_bf16 v[2:5], v[158:161], v[218:221], v[2:5]
	s_setprio 0
	s_barrier
	s_add_u32 s76, s76, 0x100
	s_addc_u32 s77, s77, 0
	s_add_u32 s47, s47, 0x100
	s_addc_u32 s62, s62, 0
	s_cmp_ge_i32 s82, s7
	s_mov_b32 s63, s82
	.p2align	6

.LBB0_744:
	s_add_u32 s36, s96, s22
	s_addc_u32 s37, s97, s23
	s_and_b64 s[14:15], s[4:5], exec
	s_cselect_b32 s14, s37, s43
	s_cselect_b32 s15, s36, s42
	s_add_u32 s38, s2, s26
	s_addc_u32 s39, s3, s27
	s_and_b64 s[46:47], s[4:5], exec
	s_cselect_b32 s21, s39, s45
	s_cselect_b32 s65, s38, s44
	s_add_u32 s42, s42, 0x40080
	s_addc_u32 s43, s43, 0
	s_add_u32 s66, s44, 0x100
	s_addc_u32 s67, s45, 0
	s_mov_b32 s68, -2
	ds_read_b128 v[154:157], v150
	ds_read_b128 v[158:161], v150 offset:1024
	ds_read_b128 v[162:165], v150 offset:2048
	ds_read_b128 v[166:169], v150 offset:3072
	ds_read_b128 v[170:173], v151
	ds_read_b128 v[174:177], v151 offset:1024
	ds_read_b128 v[178:181], v151 offset:2048
	ds_read_b128 v[182:185], v151 offset:3072
	s_add_u32 s44, s42, 0xfffc0080
	s_addc_u32 s45, s43, -1
	s_cmp_eq_u32 s68, 12
	s_cselect_b32 s47, s14, s45
	s_cselect_b32 s46, s15, s44
	s_cselect_b32 s45, s21, s67
	s_cselect_b32 s44, s65, s66
	v_lshl_add_u64 v[146:147], s[42:43], 0, v[138:139]
	s_add_i32 m0, s19, 0xc000
	ds_read_b128 v[186:189], v152
	ds_read_b128 v[190:193], v152 offset:1024
	ds_read_b128 v[194:197], v152 offset:2048
	ds_read_b128 v[198:201], v152 offset:3072
	ds_read_b128 v[206:209], v152 offset:4096
	ds_read_b128 v[210:213], v152 offset:5120
	ds_read_b128 v[214:217], v152 offset:6144
	ds_read_b128 v[218:221], v152 offset:7168
	global_load_lds_dwordx4 v[146:147], off
	s_add_i32 m0, s19, 0xe000
	v_lshl_add_u64 v[146:147], s[42:43], 0, v[140:141]
	global_load_lds_dwordx4 v[146:147], off
	s_waitcnt vmcnt(8) lgkmcnt(0)
	s_setprio 1
	s_barrier
	v_mfma_f32_16x16x32_bf16 v[126:129], v[154:157], v[186:189], 0
	v_mfma_f32_16x16x32_bf16 v[122:125], v[162:165], v[186:189], 0
	v_mfma_f32_16x16x32_bf16 v[110:113], v[154:157], v[194:197], 0
	v_mfma_f32_16x16x32_bf16 v[106:109], v[162:165], v[194:197], 0
	v_mfma_f32_16x16x32_bf16 v[94:97], v[154:157], v[206:209], 0
	v_mfma_f32_16x16x32_bf16 v[90:93], v[162:165], v[206:209], 0
	v_mfma_f32_16x16x32_bf16 v[78:81], v[154:157], v[214:217], 0
	v_mfma_f32_16x16x32_bf16 v[74:77], v[162:165], v[214:217], 0
	v_mfma_f32_16x16x32_bf16 v[126:129], v[158:161], v[190:193], v[126:129]
	v_mfma_f32_16x16x32_bf16 v[122:125], v[166:169], v[190:193], v[122:125]
	v_mfma_f32_16x16x32_bf16 v[110:113], v[158:161], v[198:201], v[110:113]
	v_mfma_f32_16x16x32_bf16 v[106:109], v[166:169], v[198:201], v[106:109]
	v_mfma_f32_16x16x32_bf16 v[94:97], v[158:161], v[210:213], v[94:97]
	v_mfma_f32_16x16x32_bf16 v[90:93], v[166:169], v[210:213], v[90:93]
	v_mfma_f32_16x16x32_bf16 v[78:81], v[158:161], v[218:221], v[78:81]
	v_mfma_f32_16x16x32_bf16 v[74:77], v[166:169], v[218:221], v[74:77]
	v_mfma_f32_16x16x32_bf16 v[118:121], v[170:173], v[186:189], 0
	v_mfma_f32_16x16x32_bf16 v[114:117], v[178:181], v[186:189], 0
	v_mfma_f32_16x16x32_bf16 v[102:105], v[170:173], v[194:197], 0
	v_mfma_f32_16x16x32_bf16 v[98:101], v[178:181], v[194:197], 0
	v_mfma_f32_16x16x32_bf16 v[86:89], v[170:173], v[206:209], 0
	v_mfma_f32_16x16x32_bf16 v[82:85], v[178:181], v[206:209], 0
	v_mfma_f32_16x16x32_bf16 v[70:73], v[170:173], v[214:217], 0
	v_mfma_f32_16x16x32_bf16 v[66:69], v[178:181], v[214:217], 0
	v_mfma_f32_16x16x32_bf16 v[118:121], v[174:177], v[190:193], v[118:121]
	v_mfma_f32_16x16x32_bf16 v[114:117], v[182:185], v[190:193], v[114:117]
	v_mfma_f32_16x16x32_bf16 v[102:105], v[174:177], v[198:201], v[102:105]
	v_mfma_f32_16x16x32_bf16 v[98:101], v[182:185], v[198:201], v[98:101]
	v_mfma_f32_16x16x32_bf16 v[86:89], v[174:177], v[210:213], v[86:89]
	v_mfma_f32_16x16x32_bf16 v[82:85], v[182:185], v[210:213], v[82:85]
	v_mfma_f32_16x16x32_bf16 v[70:73], v[174:177], v[218:221], v[70:73]
	v_mfma_f32_16x16x32_bf16 v[66:69], v[182:185], v[218:221], v[66:69]
	s_setprio 0
	s_barrier
	s_add_i32 s69, s49, s16
	v_lshl_add_u64 v[146:147], s[44:45], 0, v[134:135]
	s_mov_b32 m0, s69
	ds_read_b128 v[186:189], v152 offset:16384
	ds_read_b128 v[190:193], v152 offset:17408
	ds_read_b128 v[194:197], v152 offset:18432
	ds_read_b128 v[198:201], v152 offset:19456
	ds_read_b128 v[206:209], v152 offset:20480
	ds_read_b128 v[210:213], v152 offset:21504
	ds_read_b128 v[214:217], v152 offset:22528
	ds_read_b128 v[218:221], v152 offset:23552
	global_load_lds_dwordx4 v[146:147], off
	s_add_i32 m0, s69, 0x2000
	s_add_u32 s70, s44, 0x40000
	v_lshl_add_u64 v[202:203], s[44:45], 0, v[130:131]
	s_addc_u32 s71, s45, 0
	s_add_i32 s69, s62, s16
	global_load_lds_dwordx4 v[202:203], off
	v_lshl_add_u64 v[222:223], s[70:71], 0, v[134:135]
	s_mov_b32 m0, s69
	v_lshl_add_u64 v[224:225], s[46:47], 0, v[132:133]
	global_load_lds_dwordx4 v[222:223], off
	s_add_i32 m0, s69, 0x2000
	v_lshl_add_u64 v[222:223], s[70:71], 0, v[130:131]
	global_load_lds_dwordx4 v[222:223], off
	s_mov_b32 m0, s19
	v_lshl_add_u64 v[222:223], s[46:47], 0, v[136:137]
	global_load_lds_dwordx4 v[222:223], off
	s_mov_b32 m0, s24
	s_nop 0
	global_load_lds_dwordx4 v[224:225], off
	s_waitcnt vmcnt(8) lgkmcnt(0)
	s_setprio 1
	s_barrier
	v_mfma_f32_16x16x32_bf16 v[62:65], v[154:157], v[186:189], 0
	v_mfma_f32_16x16x32_bf16 v[58:61], v[162:165], v[186:189], 0
	v_mfma_f32_16x16x32_bf16 v[46:49], v[154:157], v[194:197], 0
	v_mfma_f32_16x16x32_bf16 v[42:45], v[162:165], v[194:197], 0
	v_mfma_f32_16x16x32_bf16 v[30:33], v[154:157], v[206:209], 0
	v_mfma_f32_16x16x32_bf16 v[26:29], v[162:165], v[206:209], 0
	v_mfma_f32_16x16x32_bf16 v[14:17], v[154:157], v[214:217], 0
	v_mfma_f32_16x16x32_bf16 v[10:13], v[162:165], v[214:217], 0
	v_mfma_f32_16x16x32_bf16 v[62:65], v[158:161], v[190:193], v[62:65]
	v_mfma_f32_16x16x32_bf16 v[58:61], v[166:169], v[190:193], v[58:61]
	v_mfma_f32_16x16x32_bf16 v[46:49], v[158:161], v[198:201], v[46:49]
	v_mfma_f32_16x16x32_bf16 v[42:45], v[166:169], v[198:201], v[42:45]
	v_mfma_f32_16x16x32_bf16 v[30:33], v[158:161], v[210:213], v[30:33]
	v_mfma_f32_16x16x32_bf16 v[26:29], v[166:169], v[210:213], v[26:29]
	v_mfma_f32_16x16x32_bf16 v[14:17], v[158:161], v[218:221], v[14:17]
	v_mfma_f32_16x16x32_bf16 v[10:13], v[166:169], v[218:221], v[10:13]
	v_mfma_f32_16x16x32_bf16 v[54:57], v[170:173], v[186:189], 0
	v_mfma_f32_16x16x32_bf16 v[50:53], v[178:181], v[186:189], 0
	v_mfma_f32_16x16x32_bf16 v[38:41], v[170:173], v[194:197], 0
	v_mfma_f32_16x16x32_bf16 v[34:37], v[178:181], v[194:197], 0
	v_mfma_f32_16x16x32_bf16 v[22:25], v[170:173], v[206:209], 0
	v_mfma_f32_16x16x32_bf16 v[18:21], v[178:181], v[206:209], 0
	v_mfma_f32_16x16x32_bf16 v[6:9], v[170:173], v[214:217], 0
	v_mfma_f32_16x16x32_bf16 v[2:5], v[178:181], v[214:217], 0
	v_mfma_f32_16x16x32_bf16 v[54:57], v[174:177], v[190:193], v[54:57]
	v_mfma_f32_16x16x32_bf16 v[50:53], v[182:185], v[190:193], v[50:53]
	v_mfma_f32_16x16x32_bf16 v[38:41], v[174:177], v[198:201], v[38:41]
	v_mfma_f32_16x16x32_bf16 v[34:37], v[182:185], v[198:201], v[34:37]
	v_mfma_f32_16x16x32_bf16 v[22:25], v[174:177], v[210:213], v[22:25]
	v_mfma_f32_16x16x32_bf16 v[18:21], v[182:185], v[210:213], v[18:21]
	v_mfma_f32_16x16x32_bf16 v[6:9], v[174:177], v[218:221], v[6:9]
	v_mfma_f32_16x16x32_bf16 v[2:5], v[182:185], v[218:221], v[2:5]
	s_setprio 0
	s_barrier
	s_add_i32 s69, 0, 0x18000
	v_add_u32_e32 v153, s69, v149
	s_add_i32 s70, 0, 0x1c000
	ds_read_b128 v[154:157], v153
	ds_read_b128 v[158:161], v153 offset:1024
	ds_read_b128 v[162:165], v153 offset:2048
	ds_read_b128 v[166:169], v153 offset:3072
	v_add_u32_e32 v153, s70, v149
	ds_read_b128 v[170:173], v153
	ds_read_b128 v[174:177], v153 offset:1024
	ds_read_b128 v[178:181], v153 offset:2048
	ds_read_b128 v[182:185], v153 offset:3072
	s_add_u32 s46, s46, 0x40000
	s_addc_u32 s47, s47, 0
	s_mov_b32 m0, s25
	v_lshl_add_u64 v[226:227], s[46:47], 0, v[136:137]
	ds_read_b128 v[186:189], v152 offset:32768
	ds_read_b128 v[190:193], v152 offset:33792
	ds_read_b128 v[194:197], v152 offset:34816
	ds_read_b128 v[198:201], v152 offset:35840
	ds_read_b128 v[206:209], v152 offset:36864
	ds_read_b128 v[210:213], v152 offset:37888
	ds_read_b128 v[214:217], v152 offset:38912
	ds_read_b128 v[218:221], v152 offset:39936
	global_load_lds_dwordx4 v[226:227], off
	s_mov_b32 m0, s28
	v_lshl_add_u64 v[226:227], s[46:47], 0, v[132:133]
	global_load_lds_dwordx4 v[226:227], off
	s_waitcnt vmcnt(8) lgkmcnt(0)
	s_setprio 1
	s_barrier
	v_mfma_f32_16x16x32_bf16 v[126:129], v[154:157], v[186:189], v[126:129]
	v_mfma_f32_16x16x32_bf16 v[122:125], v[162:165], v[186:189], v[122:125]
	v_mfma_f32_16x16x32_bf16 v[110:113], v[154:157], v[194:197], v[110:113]
	v_mfma_f32_16x16x32_bf16 v[106:109], v[162:165], v[194:197], v[106:109]
	v_mfma_f32_16x16x32_bf16 v[94:97], v[154:157], v[206:209], v[94:97]
	v_mfma_f32_16x16x32_bf16 v[90:93], v[162:165], v[206:209], v[90:93]
	v_mfma_f32_16x16x32_bf16 v[78:81], v[154:157], v[214:217], v[78:81]
	v_mfma_f32_16x16x32_bf16 v[74:77], v[162:165], v[214:217], v[74:77]
	v_mfma_f32_16x16x32_bf16 v[126:129], v[158:161], v[190:193], v[126:129]
	v_mfma_f32_16x16x32_bf16 v[122:125], v[166:169], v[190:193], v[122:125]
	v_mfma_f32_16x16x32_bf16 v[110:113], v[158:161], v[198:201], v[110:113]
	v_mfma_f32_16x16x32_bf16 v[106:109], v[166:169], v[198:201], v[106:109]
	v_mfma_f32_16x16x32_bf16 v[94:97], v[158:161], v[210:213], v[94:97]
	v_mfma_f32_16x16x32_bf16 v[90:93], v[166:169], v[210:213], v[90:93]
	v_mfma_f32_16x16x32_bf16 v[78:81], v[158:161], v[218:221], v[78:81]
	v_mfma_f32_16x16x32_bf16 v[74:77], v[166:169], v[218:221], v[74:77]
	v_mfma_f32_16x16x32_bf16 v[118:121], v[170:173], v[186:189], v[118:121]
	v_mfma_f32_16x16x32_bf16 v[114:117], v[178:181], v[186:189], v[114:117]
	v_mfma_f32_16x16x32_bf16 v[102:105], v[170:173], v[194:197], v[102:105]
	v_mfma_f32_16x16x32_bf16 v[98:101], v[178:181], v[194:197], v[98:101]
	v_mfma_f32_16x16x32_bf16 v[86:89], v[170:173], v[206:209], v[86:89]
	v_mfma_f32_16x16x32_bf16 v[82:85], v[178:181], v[206:209], v[82:85]
	v_mfma_f32_16x16x32_bf16 v[70:73], v[170:173], v[214:217], v[70:73]
	v_mfma_f32_16x16x32_bf16 v[66:69], v[178:181], v[214:217], v[66:69]
	v_mfma_f32_16x16x32_bf16 v[118:121], v[174:177], v[190:193], v[118:121]
	v_mfma_f32_16x16x32_bf16 v[114:117], v[182:185], v[190:193], v[114:117]
	v_mfma_f32_16x16x32_bf16 v[102:105], v[174:177], v[198:201], v[102:105]
	v_mfma_f32_16x16x32_bf16 v[98:101], v[182:185], v[198:201], v[98:101]
	v_mfma_f32_16x16x32_bf16 v[86:89], v[174:177], v[210:213], v[86:89]
	v_mfma_f32_16x16x32_bf16 v[82:85], v[182:185], v[210:213], v[82:85]
	v_mfma_f32_16x16x32_bf16 v[70:73], v[174:177], v[218:221], v[70:73]
	v_mfma_f32_16x16x32_bf16 v[66:69], v[182:185], v[218:221], v[66:69]
	s_setprio 0
	s_barrier
	s_add_i32 s46, s69, s16
	v_lshl_add_u64 v[146:147], v[146:147], 0, s[10:11]
	s_mov_b32 m0, s46
	ds_read_b128 v[186:189], v152 offset:49152
	ds_read_b128 v[190:193], v152 offset:50176
	ds_read_b128 v[194:197], v152 offset:51200
	ds_read_b128 v[198:201], v152 offset:52224
	ds_read_b128 v[206:209], v152 offset:53248
	ds_read_b128 v[210:213], v152 offset:54272
	ds_read_b128 v[214:217], v152 offset:55296
	ds_read_b128 v[218:221], v152 offset:56320
	global_load_lds_dwordx4 v[146:147], off
	s_add_i32 m0, s46, 0x2000
	s_add_u32 s44, s44, 0x40080
	v_lshl_add_u64 v[146:147], v[202:203], 0, s[10:11]
	s_addc_u32 s45, s45, 0
	s_add_i32 s46, s70, s16
	global_load_lds_dwordx4 v[146:147], off
	s_mov_b32 m0, s46
	v_lshl_add_u64 v[146:147], s[44:45], 0, v[134:135]
	global_load_lds_dwordx4 v[146:147], off
	s_add_i32 m0, s46, 0x2000
	v_lshl_add_u64 v[146:147], s[44:45], 0, v[130:131]
	global_load_lds_dwordx4 v[146:147], off
	s_mov_b32 m0, s33
	v_lshl_add_u64 v[146:147], v[222:223], 0, s[10:11]
	global_load_lds_dwordx4 v[146:147], off
	s_mov_b32 m0, s35
	v_lshl_add_u64 v[146:147], v[224:225], 0, s[10:11]
	global_load_lds_dwordx4 v[146:147], off
	s_waitcnt vmcnt(8) lgkmcnt(0)
	s_setprio 1
	s_barrier
	v_mfma_f32_16x16x32_bf16 v[62:65], v[154:157], v[186:189], v[62:65]
	v_mfma_f32_16x16x32_bf16 v[58:61], v[162:165], v[186:189], v[58:61]
	v_mfma_f32_16x16x32_bf16 v[46:49], v[154:157], v[194:197], v[46:49]
	v_mfma_f32_16x16x32_bf16 v[42:45], v[162:165], v[194:197], v[42:45]
	v_mfma_f32_16x16x32_bf16 v[30:33], v[154:157], v[206:209], v[30:33]
	v_mfma_f32_16x16x32_bf16 v[26:29], v[162:165], v[206:209], v[26:29]
	v_mfma_f32_16x16x32_bf16 v[14:17], v[154:157], v[214:217], v[14:17]
	v_mfma_f32_16x16x32_bf16 v[10:13], v[162:165], v[214:217], v[10:13]
	v_mfma_f32_16x16x32_bf16 v[62:65], v[158:161], v[190:193], v[62:65]
	v_mfma_f32_16x16x32_bf16 v[58:61], v[166:169], v[190:193], v[58:61]
	v_mfma_f32_16x16x32_bf16 v[46:49], v[158:161], v[198:201], v[46:49]
	v_mfma_f32_16x16x32_bf16 v[42:45], v[166:169], v[198:201], v[42:45]
	v_mfma_f32_16x16x32_bf16 v[30:33], v[158:161], v[210:213], v[30:33]
	v_mfma_f32_16x16x32_bf16 v[26:29], v[166:169], v[210:213], v[26:29]
	v_mfma_f32_16x16x32_bf16 v[14:17], v[158:161], v[218:221], v[14:17]
	v_mfma_f32_16x16x32_bf16 v[10:13], v[166:169], v[218:221], v[10:13]
	v_mfma_f32_16x16x32_bf16 v[54:57], v[170:173], v[186:189], v[54:57]
	v_mfma_f32_16x16x32_bf16 v[50:53], v[178:181], v[186:189], v[50:53]
	v_mfma_f32_16x16x32_bf16 v[38:41], v[170:173], v[194:197], v[38:41]
	v_mfma_f32_16x16x32_bf16 v[34:37], v[178:181], v[194:197], v[34:37]
	v_mfma_f32_16x16x32_bf16 v[22:25], v[170:173], v[206:209], v[22:25]
	v_mfma_f32_16x16x32_bf16 v[18:21], v[178:181], v[206:209], v[18:21]
	v_mfma_f32_16x16x32_bf16 v[6:9], v[170:173], v[214:217], v[6:9]
	v_mfma_f32_16x16x32_bf16 v[2:5], v[178:181], v[214:217], v[2:5]
	v_mfma_f32_16x16x32_bf16 v[54:57], v[174:177], v[190:193], v[54:57]
	v_mfma_f32_16x16x32_bf16 v[50:53], v[182:185], v[190:193], v[50:53]
	v_mfma_f32_16x16x32_bf16 v[38:41], v[174:177], v[198:201], v[38:41]
	v_mfma_f32_16x16x32_bf16 v[34:37], v[182:185], v[198:201], v[34:37]
	v_mfma_f32_16x16x32_bf16 v[22:25], v[174:177], v[210:213], v[22:25]
	v_mfma_f32_16x16x32_bf16 v[18:21], v[182:185], v[210:213], v[18:21]
	v_mfma_f32_16x16x32_bf16 v[6:9], v[174:177], v[218:221], v[6:9]
	v_mfma_f32_16x16x32_bf16 v[2:5], v[182:185], v[218:221], v[2:5]
	s_setprio 0
	s_barrier
	s_add_i32 s68, s68, 2
	s_add_u32 s42, s42, 0x100
	s_addc_u32 s43, s43, 0
	s_add_u32 s66, s66, 0x100
	s_addc_u32 s67, s67, 0
	s_cmp_gt_u32 s68, 13
	.p2align	6

.LBB0_833:
	s_add_u32 s72, s0, s68
	s_addc_u32 s73, s1, s69
	s_and_b64 s[62:63], s[70:71], exec
	s_cselect_b32 s15, s73, s77
	s_cselect_b32 s33, s72, s76
	s_add_u32 s74, s35, s66
	s_addc_u32 s75, s85, s67
	s_and_b64 s[62:63], s[70:71], exec
	s_cselect_b32 s34, s75, s79
	s_cselect_b32 s39, s74, s78
	s_add_i32 s45, s7, -2
	s_add_u32 s76, s76, 0x100080
	s_addc_u32 s77, s77, 0
	s_add_u32 s47, s78, 0x100
	s_addc_u32 s62, s79, 0
	s_mov_b32 s63, 0
	s_waitcnt vmcnt(0)
	ds_read_b128 v[114:117], v190
	ds_read_b128 v[118:121], v190 offset:1024
	ds_read_b128 v[122:125], v190 offset:2048
	ds_read_b128 v[126:129], v190 offset:3072
	ds_read_b128 v[146:149], v191
	ds_read_b128 v[150:153], v191 offset:1024
	ds_read_b128 v[154:157], v191 offset:2048
	ds_read_b128 v[158:161], v191 offset:3072
	s_add_i32 s82, s63, 2
	s_add_u32 s78, s76, 0xfff00080
	s_addc_u32 s79, s77, -1
	s_cmp_eq_u32 s45, s63
	s_cselect_b32 s81, s15, s79
	s_cselect_b32 s80, s33, s78
	s_cselect_b32 s79, s34, s62
	s_cselect_b32 s78, s39, s47
	v_lshl_add_u64 v[186:187], s[76:77], 0, v[180:181]
	s_add_i32 m0, s87, 0xc000
	ds_read_b128 v[162:165], v192
	ds_read_b128 v[166:169], v192 offset:1024
	ds_read_b128 v[194:197], v192 offset:2048
	ds_read_b128 v[198:201], v192 offset:3072
	ds_read_b128 v[206:209], v192 offset:4096
	ds_read_b128 v[210:213], v192 offset:5120
	ds_read_b128 v[214:217], v192 offset:6144
	ds_read_b128 v[218:221], v192 offset:7168
	global_load_lds_dwordx4 v[186:187], off
	s_add_i32 m0, s87, 0xe000
	v_lshl_add_u64 v[186:187], s[76:77], 0, v[182:183]
	global_load_lds_dwordx4 v[186:187], off
	s_waitcnt vmcnt(8) lgkmcnt(0)
	s_setprio 1
	s_barrier
	v_mfma_f32_16x16x32_bf16 v[142:145], v[114:117], v[162:165], 0
	v_mfma_f32_16x16x32_bf16 v[138:141], v[122:125], v[162:165], 0
	v_mfma_f32_16x16x32_bf16 v[110:113], v[114:117], v[194:197], 0
	v_mfma_f32_16x16x32_bf16 v[106:109], v[122:125], v[194:197], 0
	v_mfma_f32_16x16x32_bf16 v[98:101], v[114:117], v[206:209], 0
	v_mfma_f32_16x16x32_bf16 v[90:93], v[122:125], v[206:209], 0
	v_mfma_f32_16x16x32_bf16 v[82:85], v[114:117], v[214:217], 0
	v_mfma_f32_16x16x32_bf16 v[74:77], v[122:125], v[214:217], 0
	v_mfma_f32_16x16x32_bf16 v[142:145], v[118:121], v[166:169], v[142:145]
	v_mfma_f32_16x16x32_bf16 v[138:141], v[126:129], v[166:169], v[138:141]
	v_mfma_f32_16x16x32_bf16 v[110:113], v[118:121], v[198:201], v[110:113]
	v_mfma_f32_16x16x32_bf16 v[106:109], v[126:129], v[198:201], v[106:109]
	v_mfma_f32_16x16x32_bf16 v[98:101], v[118:121], v[210:213], v[98:101]
	v_mfma_f32_16x16x32_bf16 v[90:93], v[126:129], v[210:213], v[90:93]
	v_mfma_f32_16x16x32_bf16 v[82:85], v[118:121], v[218:221], v[82:85]
	v_mfma_f32_16x16x32_bf16 v[74:77], v[126:129], v[218:221], v[74:77]
	v_mfma_f32_16x16x32_bf16 v[134:137], v[146:149], v[162:165], 0
	v_mfma_f32_16x16x32_bf16 v[130:133], v[154:157], v[162:165], 0
	v_mfma_f32_16x16x32_bf16 v[102:105], v[146:149], v[194:197], 0
	v_mfma_f32_16x16x32_bf16 v[94:97], v[154:157], v[194:197], 0
	v_mfma_f32_16x16x32_bf16 v[86:89], v[146:149], v[206:209], 0
	v_mfma_f32_16x16x32_bf16 v[78:81], v[154:157], v[206:209], 0
	v_mfma_f32_16x16x32_bf16 v[70:73], v[146:149], v[214:217], 0
	v_mfma_f32_16x16x32_bf16 v[66:69], v[154:157], v[214:217], 0
	v_mfma_f32_16x16x32_bf16 v[134:137], v[150:153], v[166:169], v[134:137]
	v_mfma_f32_16x16x32_bf16 v[130:133], v[158:161], v[166:169], v[130:133]
	v_mfma_f32_16x16x32_bf16 v[102:105], v[150:153], v[198:201], v[102:105]
	v_mfma_f32_16x16x32_bf16 v[94:97], v[158:161], v[198:201], v[94:97]
	v_mfma_f32_16x16x32_bf16 v[86:89], v[150:153], v[210:213], v[86:89]
	v_mfma_f32_16x16x32_bf16 v[78:81], v[158:161], v[210:213], v[78:81]
	v_mfma_f32_16x16x32_bf16 v[70:73], v[150:153], v[218:221], v[70:73]
	v_mfma_f32_16x16x32_bf16 v[66:69], v[158:161], v[218:221], v[66:69]
	s_setprio 0
	s_barrier
	s_add_i32 s63, s24, s86
	v_lshl_add_u64 v[186:187], s[78:79], 0, v[172:173]
	s_mov_b32 m0, s63
	ds_read_b128 v[162:165], v192 offset:16384
	ds_read_b128 v[166:169], v192 offset:17408
	ds_read_b128 v[194:197], v192 offset:18432
	ds_read_b128 v[198:201], v192 offset:19456
	ds_read_b128 v[206:209], v192 offset:20480
	ds_read_b128 v[210:213], v192 offset:21504
	ds_read_b128 v[214:217], v192 offset:22528
	ds_read_b128 v[218:221], v192 offset:23552
	global_load_lds_dwordx4 v[186:187], off
	s_add_i32 m0, s63, 0x2000
	s_add_u32 vcc_lo, s78, 0x100000
	v_lshl_add_u64 v[202:203], s[78:79], 0, v[176:177]
	s_addc_u32 vcc_hi, s79, 0
	s_add_i32 s63, s25, s86
	global_load_lds_dwordx4 v[202:203], off
	v_lshl_add_u64 v[222:223], vcc, 0, v[172:173]
	s_mov_b32 m0, s63
	v_lshl_add_u64 v[224:225], s[80:81], 0, v[174:175]
	global_load_lds_dwordx4 v[222:223], off
	s_add_i32 m0, s63, 0x2000
	v_lshl_add_u64 v[222:223], vcc, 0, v[176:177]
	global_load_lds_dwordx4 v[222:223], off
	s_mov_b32 m0, s87
	v_lshl_add_u64 v[222:223], s[80:81], 0, v[170:171]
	global_load_lds_dwordx4 v[222:223], off
	s_mov_b32 m0, s88
	s_nop 0
	global_load_lds_dwordx4 v[224:225], off
	s_waitcnt vmcnt(8) lgkmcnt(0)
	s_setprio 1
	s_barrier
	v_mfma_f32_16x16x32_bf16 v[62:65], v[114:117], v[162:165], 0
	v_mfma_f32_16x16x32_bf16 v[58:61], v[122:125], v[162:165], 0
	v_mfma_f32_16x16x32_bf16 v[50:53], v[114:117], v[194:197], 0
	v_mfma_f32_16x16x32_bf16 v[42:45], v[122:125], v[194:197], 0
	v_mfma_f32_16x16x32_bf16 v[34:37], v[114:117], v[206:209], 0
	v_mfma_f32_16x16x32_bf16 v[26:29], v[122:125], v[206:209], 0
	v_mfma_f32_16x16x32_bf16 v[18:21], v[114:117], v[214:217], 0
	v_mfma_f32_16x16x32_bf16 v[10:13], v[122:125], v[214:217], 0
	v_mfma_f32_16x16x32_bf16 v[62:65], v[118:121], v[166:169], v[62:65]
	v_mfma_f32_16x16x32_bf16 v[58:61], v[126:129], v[166:169], v[58:61]
	v_mfma_f32_16x16x32_bf16 v[50:53], v[118:121], v[198:201], v[50:53]
	v_mfma_f32_16x16x32_bf16 v[42:45], v[126:129], v[198:201], v[42:45]
	v_mfma_f32_16x16x32_bf16 v[34:37], v[118:121], v[210:213], v[34:37]
	v_mfma_f32_16x16x32_bf16 v[26:29], v[126:129], v[210:213], v[26:29]
	v_mfma_f32_16x16x32_bf16 v[18:21], v[118:121], v[218:221], v[18:21]
	v_mfma_f32_16x16x32_bf16 v[10:13], v[126:129], v[218:221], v[10:13]
	v_mfma_f32_16x16x32_bf16 v[54:57], v[146:149], v[162:165], 0
	v_mfma_f32_16x16x32_bf16 v[46:49], v[154:157], v[162:165], 0
	v_mfma_f32_16x16x32_bf16 v[38:41], v[146:149], v[194:197], 0
	v_mfma_f32_16x16x32_bf16 v[30:33], v[154:157], v[194:197], 0
	v_mfma_f32_16x16x32_bf16 v[22:25], v[146:149], v[206:209], 0
	v_mfma_f32_16x16x32_bf16 v[14:17], v[154:157], v[206:209], 0
	v_mfma_f32_16x16x32_bf16 v[6:9], v[146:149], v[214:217], 0
	v_mfma_f32_16x16x32_bf16 v[2:5], v[154:157], v[214:217], 0
	v_mfma_f32_16x16x32_bf16 v[54:57], v[150:153], v[166:169], v[54:57]
	v_mfma_f32_16x16x32_bf16 v[46:49], v[158:161], v[166:169], v[46:49]
	v_mfma_f32_16x16x32_bf16 v[38:41], v[150:153], v[198:201], v[38:41]
	v_mfma_f32_16x16x32_bf16 v[30:33], v[158:161], v[198:201], v[30:33]
	v_mfma_f32_16x16x32_bf16 v[22:25], v[150:153], v[210:213], v[22:25]
	v_mfma_f32_16x16x32_bf16 v[14:17], v[158:161], v[210:213], v[14:17]
	v_mfma_f32_16x16x32_bf16 v[6:9], v[150:153], v[218:221], v[6:9]
	v_mfma_f32_16x16x32_bf16 v[2:5], v[158:161], v[218:221], v[2:5]
	s_setprio 0
	s_barrier
	s_add_i32 s63, 0, 0x18000
	s_add_i32 s83, 0, 0x1c000
	v_add_u32_e32 v126, s63, v189
	v_add_u32_e32 v158, s83, v189
	ds_read_b128 v[114:117], v126
	ds_read_b128 v[118:121], v126 offset:1024
	ds_read_b128 v[122:125], v126 offset:2048
	ds_read_b128 v[126:129], v126 offset:3072
	ds_read_b128 v[146:149], v158
	ds_read_b128 v[150:153], v158 offset:1024
	ds_read_b128 v[154:157], v158 offset:2048
	ds_read_b128 v[158:161], v158 offset:3072
	s_add_u32 s80, s80, 0x100000
	s_addc_u32 s81, s81, 0
	s_mov_b32 m0, s89
	v_lshl_add_u64 v[226:227], s[80:81], 0, v[170:171]
	ds_read_b128 v[162:165], v192 offset:32768
	ds_read_b128 v[166:169], v192 offset:33792
	ds_read_b128 v[194:197], v192 offset:34816
	ds_read_b128 v[198:201], v192 offset:35840
	ds_read_b128 v[206:209], v192 offset:36864
	ds_read_b128 v[210:213], v192 offset:37888
	ds_read_b128 v[214:217], v192 offset:38912
	ds_read_b128 v[218:221], v192 offset:39936
	global_load_lds_dwordx4 v[226:227], off
	s_mov_b32 m0, s90
	v_lshl_add_u64 v[226:227], s[80:81], 0, v[174:175]
	global_load_lds_dwordx4 v[226:227], off
	s_waitcnt vmcnt(8) lgkmcnt(0)
	s_setprio 1
	s_barrier
	v_mfma_f32_16x16x32_bf16 v[142:145], v[114:117], v[162:165], v[142:145]
	v_mfma_f32_16x16x32_bf16 v[138:141], v[122:125], v[162:165], v[138:141]
	v_mfma_f32_16x16x32_bf16 v[110:113], v[114:117], v[194:197], v[110:113]
	v_mfma_f32_16x16x32_bf16 v[106:109], v[122:125], v[194:197], v[106:109]
	v_mfma_f32_16x16x32_bf16 v[98:101], v[114:117], v[206:209], v[98:101]
	v_mfma_f32_16x16x32_bf16 v[90:93], v[122:125], v[206:209], v[90:93]
	v_mfma_f32_16x16x32_bf16 v[82:85], v[114:117], v[214:217], v[82:85]
	v_mfma_f32_16x16x32_bf16 v[74:77], v[122:125], v[214:217], v[74:77]
	v_mfma_f32_16x16x32_bf16 v[142:145], v[118:121], v[166:169], v[142:145]
	v_mfma_f32_16x16x32_bf16 v[138:141], v[126:129], v[166:169], v[138:141]
	v_mfma_f32_16x16x32_bf16 v[110:113], v[118:121], v[198:201], v[110:113]
	v_mfma_f32_16x16x32_bf16 v[106:109], v[126:129], v[198:201], v[106:109]
	v_mfma_f32_16x16x32_bf16 v[98:101], v[118:121], v[210:213], v[98:101]
	v_mfma_f32_16x16x32_bf16 v[90:93], v[126:129], v[210:213], v[90:93]
	v_mfma_f32_16x16x32_bf16 v[82:85], v[118:121], v[218:221], v[82:85]
	v_mfma_f32_16x16x32_bf16 v[74:77], v[126:129], v[218:221], v[74:77]
	v_mfma_f32_16x16x32_bf16 v[134:137], v[146:149], v[162:165], v[134:137]
	v_mfma_f32_16x16x32_bf16 v[130:133], v[154:157], v[162:165], v[130:133]
	v_mfma_f32_16x16x32_bf16 v[102:105], v[146:149], v[194:197], v[102:105]
	v_mfma_f32_16x16x32_bf16 v[94:97], v[154:157], v[194:197], v[94:97]
	v_mfma_f32_16x16x32_bf16 v[86:89], v[146:149], v[206:209], v[86:89]
	v_mfma_f32_16x16x32_bf16 v[78:81], v[154:157], v[206:209], v[78:81]
	v_mfma_f32_16x16x32_bf16 v[70:73], v[146:149], v[214:217], v[70:73]
	v_mfma_f32_16x16x32_bf16 v[66:69], v[154:157], v[214:217], v[66:69]
	v_mfma_f32_16x16x32_bf16 v[134:137], v[150:153], v[166:169], v[134:137]
	v_mfma_f32_16x16x32_bf16 v[130:133], v[158:161], v[166:169], v[130:133]
	v_mfma_f32_16x16x32_bf16 v[102:105], v[150:153], v[198:201], v[102:105]
	v_mfma_f32_16x16x32_bf16 v[94:97], v[158:161], v[198:201], v[94:97]
	v_mfma_f32_16x16x32_bf16 v[86:89], v[150:153], v[210:213], v[86:89]
	v_mfma_f32_16x16x32_bf16 v[78:81], v[158:161], v[210:213], v[78:81]
	v_mfma_f32_16x16x32_bf16 v[70:73], v[150:153], v[218:221], v[70:73]
	v_mfma_f32_16x16x32_bf16 v[66:69], v[158:161], v[218:221], v[66:69]
	s_setprio 0
	s_barrier
	s_add_i32 s63, s63, s86
	v_lshl_add_u64 v[186:187], v[186:187], 0, s[22:23]
	s_mov_b32 m0, s63
	ds_read_b128 v[162:165], v192 offset:49152
	ds_read_b128 v[166:169], v192 offset:50176
	ds_read_b128 v[194:197], v192 offset:51200
	ds_read_b128 v[198:201], v192 offset:52224
	ds_read_b128 v[206:209], v192 offset:53248
	ds_read_b128 v[210:213], v192 offset:54272
	ds_read_b128 v[214:217], v192 offset:55296
	ds_read_b128 v[218:221], v192 offset:56320
	global_load_lds_dwordx4 v[186:187], off
	s_add_i32 m0, s63, 0x2000
	s_add_u32 s78, s78, 0x100080
	v_lshl_add_u64 v[186:187], v[202:203], 0, s[22:23]
	s_addc_u32 s79, s79, 0
	s_add_i32 s63, s83, s86
	global_load_lds_dwordx4 v[186:187], off
	s_mov_b32 m0, s63
	v_lshl_add_u64 v[186:187], s[78:79], 0, v[172:173]
	global_load_lds_dwordx4 v[186:187], off
	s_add_i32 m0, s63, 0x2000
	v_lshl_add_u64 v[186:187], s[78:79], 0, v[176:177]
	global_load_lds_dwordx4 v[186:187], off
	s_mov_b32 m0, s95
	v_lshl_add_u64 v[186:187], v[222:223], 0, s[22:23]
	global_load_lds_dwordx4 v[186:187], off
	s_mov_b32 m0, s96
	v_lshl_add_u64 v[186:187], v[224:225], 0, s[22:23]
	global_load_lds_dwordx4 v[186:187], off
	s_waitcnt vmcnt(8) lgkmcnt(0)
	s_setprio 1
	s_barrier
	v_mfma_f32_16x16x32_bf16 v[62:65], v[114:117], v[162:165], v[62:65]
	v_mfma_f32_16x16x32_bf16 v[58:61], v[122:125], v[162:165], v[58:61]
	v_mfma_f32_16x16x32_bf16 v[50:53], v[114:117], v[194:197], v[50:53]
	v_mfma_f32_16x16x32_bf16 v[42:45], v[122:125], v[194:197], v[42:45]
	v_mfma_f32_16x16x32_bf16 v[34:37], v[114:117], v[206:209], v[34:37]
	v_mfma_f32_16x16x32_bf16 v[26:29], v[122:125], v[206:209], v[26:29]
	v_mfma_f32_16x16x32_bf16 v[18:21], v[114:117], v[214:217], v[18:21]
	v_mfma_f32_16x16x32_bf16 v[10:13], v[122:125], v[214:217], v[10:13]
	v_mfma_f32_16x16x32_bf16 v[62:65], v[118:121], v[166:169], v[62:65]
	v_mfma_f32_16x16x32_bf16 v[58:61], v[126:129], v[166:169], v[58:61]
	v_mfma_f32_16x16x32_bf16 v[50:53], v[118:121], v[198:201], v[50:53]
	v_mfma_f32_16x16x32_bf16 v[42:45], v[126:129], v[198:201], v[42:45]
	v_mfma_f32_16x16x32_bf16 v[34:37], v[118:121], v[210:213], v[34:37]
	v_mfma_f32_16x16x32_bf16 v[26:29], v[126:129], v[210:213], v[26:29]
	v_mfma_f32_16x16x32_bf16 v[18:21], v[118:121], v[218:221], v[18:21]
	v_mfma_f32_16x16x32_bf16 v[10:13], v[126:129], v[218:221], v[10:13]
	v_mfma_f32_16x16x32_bf16 v[54:57], v[146:149], v[162:165], v[54:57]
	v_mfma_f32_16x16x32_bf16 v[46:49], v[154:157], v[162:165], v[46:49]
	v_mfma_f32_16x16x32_bf16 v[38:41], v[146:149], v[194:197], v[38:41]
	v_mfma_f32_16x16x32_bf16 v[30:33], v[154:157], v[194:197], v[30:33]
	v_mfma_f32_16x16x32_bf16 v[22:25], v[146:149], v[206:209], v[22:25]
	v_mfma_f32_16x16x32_bf16 v[14:17], v[154:157], v[206:209], v[14:17]
	v_mfma_f32_16x16x32_bf16 v[6:9], v[146:149], v[214:217], v[6:9]
	v_mfma_f32_16x16x32_bf16 v[2:5], v[154:157], v[214:217], v[2:5]
	v_mfma_f32_16x16x32_bf16 v[54:57], v[150:153], v[166:169], v[54:57]
	v_mfma_f32_16x16x32_bf16 v[46:49], v[158:161], v[166:169], v[46:49]
	v_mfma_f32_16x16x32_bf16 v[38:41], v[150:153], v[198:201], v[38:41]
	v_mfma_f32_16x16x32_bf16 v[30:33], v[158:161], v[198:201], v[30:33]
	v_mfma_f32_16x16x32_bf16 v[22:25], v[150:153], v[210:213], v[22:25]
	v_mfma_f32_16x16x32_bf16 v[14:17], v[158:161], v[210:213], v[14:17]
	v_mfma_f32_16x16x32_bf16 v[6:9], v[150:153], v[218:221], v[6:9]
	v_mfma_f32_16x16x32_bf16 v[2:5], v[158:161], v[218:221], v[2:5]
	s_setprio 0
	s_barrier
	s_add_u32 s76, s76, 0x100
	s_addc_u32 s77, s77, 0
	s_add_u32 s47, s47, 0x100
	s_addc_u32 s62, s62, 0
	s_cmp_ge_i32 s82, s7
	s_mov_b32 s63, s82
	.p2align	6

.LBB0_1012:
	s_add_u32 s48, s96, s44
	s_addc_u32 s49, s97, s45
	s_and_b64 s[14:15], s[4:5], exec
	s_cselect_b32 s6, s49, s65
	s_cselect_b32 s14, s48, s64
	s_add_u32 s50, s3, s46
	s_addc_u32 s51, s35, s47
	s_and_b64 s[18:19], s[4:5], exec
	s_cselect_b32 s15, s51, s67
	s_cselect_b32 s17, s50, s66
	s_add_u32 s64, s64, 0x40080
	s_addc_u32 s65, s65, 0
	s_add_u32 s18, s66, 0x100
	s_addc_u32 s19, s67, 0
	s_mov_b32 s24, -2
	s_waitcnt vmcnt(0)
	ds_read_b128 v[130:133], v172
	ds_read_b128 v[134:137], v172 offset:1024
	ds_read_b128 v[138:141], v172 offset:2048
	ds_read_b128 v[142:145], v172 offset:3072
	ds_read_b128 v[164:167], v173
	ds_read_b128 v[176:179], v173 offset:1024
	ds_read_b128 v[180:183], v173 offset:2048
	ds_read_b128 v[184:187], v173 offset:3072
	s_add_u32 s25, s64, 0xfffc0080
	s_addc_u32 s28, s65, -1
	s_cmp_eq_u32 s24, 12
	s_cselect_b32 s69, s6, s28
	s_cselect_b32 s68, s14, s25
	s_cselect_b32 s67, s15, s19
	s_cselect_b32 s66, s17, s18
	v_lshl_add_u64 v[168:169], s[64:65], 0, v[156:157]
	s_add_i32 m0, s73, 0xc000
	ds_read_b128 v[188:191], v174
	ds_read_b128 v[192:195], v174 offset:1024
	ds_read_b128 v[196:199], v174 offset:2048
	ds_read_b128 v[200:203], v174 offset:3072
	ds_read_b128 v[206:209], v174 offset:4096
	ds_read_b128 v[210:213], v174 offset:5120
	ds_read_b128 v[214:217], v174 offset:6144
	ds_read_b128 v[218:221], v174 offset:7168
	global_load_lds_dwordx4 v[168:169], off
	s_add_i32 m0, s73, 0xe000
	v_lshl_add_u64 v[168:169], s[64:65], 0, v[158:159]
	global_load_lds_dwordx4 v[168:169], off
	s_waitcnt vmcnt(8) lgkmcnt(0)
	s_setprio 1
	s_barrier
	v_mfma_f32_16x16x32_bf16 v[126:129], v[130:133], v[188:191], 0
	v_mfma_f32_16x16x32_bf16 v[122:125], v[138:141], v[188:191], 0
	v_mfma_f32_16x16x32_bf16 v[110:113], v[130:133], v[196:199], 0
	v_mfma_f32_16x16x32_bf16 v[106:109], v[138:141], v[196:199], 0
	v_mfma_f32_16x16x32_bf16 v[94:97], v[130:133], v[206:209], 0
	v_mfma_f32_16x16x32_bf16 v[90:93], v[138:141], v[206:209], 0
	v_mfma_f32_16x16x32_bf16 v[78:81], v[130:133], v[214:217], 0
	v_mfma_f32_16x16x32_bf16 v[74:77], v[138:141], v[214:217], 0
	v_mfma_f32_16x16x32_bf16 v[126:129], v[134:137], v[192:195], v[126:129]
	v_mfma_f32_16x16x32_bf16 v[122:125], v[142:145], v[192:195], v[122:125]
	v_mfma_f32_16x16x32_bf16 v[110:113], v[134:137], v[200:203], v[110:113]
	v_mfma_f32_16x16x32_bf16 v[106:109], v[142:145], v[200:203], v[106:109]
	v_mfma_f32_16x16x32_bf16 v[94:97], v[134:137], v[210:213], v[94:97]
	v_mfma_f32_16x16x32_bf16 v[90:93], v[142:145], v[210:213], v[90:93]
	v_mfma_f32_16x16x32_bf16 v[78:81], v[134:137], v[218:221], v[78:81]
	v_mfma_f32_16x16x32_bf16 v[74:77], v[142:145], v[218:221], v[74:77]
	v_mfma_f32_16x16x32_bf16 v[118:121], v[164:167], v[188:191], 0
	v_mfma_f32_16x16x32_bf16 v[114:117], v[180:183], v[188:191], 0
	v_mfma_f32_16x16x32_bf16 v[102:105], v[164:167], v[196:199], 0
	v_mfma_f32_16x16x32_bf16 v[98:101], v[180:183], v[196:199], 0
	v_mfma_f32_16x16x32_bf16 v[86:89], v[164:167], v[206:209], 0
	v_mfma_f32_16x16x32_bf16 v[82:85], v[180:183], v[206:209], 0
	v_mfma_f32_16x16x32_bf16 v[70:73], v[164:167], v[214:217], 0
	v_mfma_f32_16x16x32_bf16 v[66:69], v[180:183], v[214:217], 0
	v_mfma_f32_16x16x32_bf16 v[118:121], v[176:179], v[192:195], v[118:121]
	v_mfma_f32_16x16x32_bf16 v[114:117], v[184:187], v[192:195], v[114:117]
	v_mfma_f32_16x16x32_bf16 v[102:105], v[176:179], v[200:203], v[102:105]
	v_mfma_f32_16x16x32_bf16 v[98:101], v[184:187], v[200:203], v[98:101]
	v_mfma_f32_16x16x32_bf16 v[86:89], v[176:179], v[210:213], v[86:89]
	v_mfma_f32_16x16x32_bf16 v[82:85], v[184:187], v[210:213], v[82:85]
	v_mfma_f32_16x16x32_bf16 v[70:73], v[176:179], v[218:221], v[70:73]
	v_mfma_f32_16x16x32_bf16 v[66:69], v[184:187], v[218:221], v[66:69]
	s_setprio 0
	s_barrier
	s_add_i32 s25, s82, s70
	v_lshl_add_u64 v[168:169], s[66:67], 0, v[150:151]
	s_mov_b32 m0, s25
	ds_read_b128 v[188:191], v174 offset:16384
	ds_read_b128 v[192:195], v174 offset:17408
	ds_read_b128 v[196:199], v174 offset:18432
	ds_read_b128 v[200:203], v174 offset:19456
	ds_read_b128 v[206:209], v174 offset:20480
	ds_read_b128 v[210:213], v174 offset:21504
	ds_read_b128 v[214:217], v174 offset:22528
	ds_read_b128 v[218:221], v174 offset:23552
	global_load_lds_dwordx4 v[168:169], off
	s_add_i32 m0, s25, 0x2000
	s_add_u32 s28, s66, 0x40000
	v_lshl_add_u64 v[222:223], s[66:67], 0, v[146:147]
	s_addc_u32 s29, s67, 0
	s_add_i32 s25, s83, s70
	global_load_lds_dwordx4 v[222:223], off
	v_lshl_add_u64 v[224:225], s[28:29], 0, v[150:151]
	s_mov_b32 m0, s25
	v_lshl_add_u64 v[226:227], s[68:69], 0, v[148:149]
	global_load_lds_dwordx4 v[224:225], off
	s_add_i32 m0, s25, 0x2000
	v_lshl_add_u64 v[224:225], s[28:29], 0, v[146:147]
	global_load_lds_dwordx4 v[224:225], off
	s_mov_b32 m0, s73
	v_lshl_add_u64 v[224:225], s[68:69], 0, v[152:153]
	global_load_lds_dwordx4 v[224:225], off
	s_mov_b32 m0, s74
	s_nop 0
	global_load_lds_dwordx4 v[226:227], off
	s_waitcnt vmcnt(8) lgkmcnt(0)
	s_setprio 1
	s_barrier
	v_mfma_f32_16x16x32_bf16 v[62:65], v[130:133], v[188:191], 0
	v_mfma_f32_16x16x32_bf16 v[58:61], v[138:141], v[188:191], 0
	v_mfma_f32_16x16x32_bf16 v[46:49], v[130:133], v[196:199], 0
	v_mfma_f32_16x16x32_bf16 v[42:45], v[138:141], v[196:199], 0
	v_mfma_f32_16x16x32_bf16 v[30:33], v[130:133], v[206:209], 0
	v_mfma_f32_16x16x32_bf16 v[26:29], v[138:141], v[206:209], 0
	v_mfma_f32_16x16x32_bf16 v[14:17], v[130:133], v[214:217], 0
	v_mfma_f32_16x16x32_bf16 v[10:13], v[138:141], v[214:217], 0
	v_mfma_f32_16x16x32_bf16 v[62:65], v[134:137], v[192:195], v[62:65]
	v_mfma_f32_16x16x32_bf16 v[58:61], v[142:145], v[192:195], v[58:61]
	v_mfma_f32_16x16x32_bf16 v[46:49], v[134:137], v[200:203], v[46:49]
	v_mfma_f32_16x16x32_bf16 v[42:45], v[142:145], v[200:203], v[42:45]
	v_mfma_f32_16x16x32_bf16 v[30:33], v[134:137], v[210:213], v[30:33]
	v_mfma_f32_16x16x32_bf16 v[26:29], v[142:145], v[210:213], v[26:29]
	v_mfma_f32_16x16x32_bf16 v[14:17], v[134:137], v[218:221], v[14:17]
	v_mfma_f32_16x16x32_bf16 v[10:13], v[142:145], v[218:221], v[10:13]
	v_mfma_f32_16x16x32_bf16 v[54:57], v[164:167], v[188:191], 0
	v_mfma_f32_16x16x32_bf16 v[50:53], v[180:183], v[188:191], 0
	v_mfma_f32_16x16x32_bf16 v[38:41], v[164:167], v[196:199], 0
	v_mfma_f32_16x16x32_bf16 v[34:37], v[180:183], v[196:199], 0
	v_mfma_f32_16x16x32_bf16 v[22:25], v[164:167], v[206:209], 0
	v_mfma_f32_16x16x32_bf16 v[18:21], v[180:183], v[206:209], 0
	v_mfma_f32_16x16x32_bf16 v[6:9], v[164:167], v[214:217], 0
	v_mfma_f32_16x16x32_bf16 v[2:5], v[180:183], v[214:217], 0
	v_mfma_f32_16x16x32_bf16 v[54:57], v[176:179], v[192:195], v[54:57]
	v_mfma_f32_16x16x32_bf16 v[50:53], v[184:187], v[192:195], v[50:53]
	v_mfma_f32_16x16x32_bf16 v[38:41], v[176:179], v[200:203], v[38:41]
	v_mfma_f32_16x16x32_bf16 v[34:37], v[184:187], v[200:203], v[34:37]
	v_mfma_f32_16x16x32_bf16 v[22:25], v[176:179], v[210:213], v[22:25]
	v_mfma_f32_16x16x32_bf16 v[18:21], v[184:187], v[210:213], v[18:21]
	v_mfma_f32_16x16x32_bf16 v[6:9], v[176:179], v[218:221], v[6:9]
	v_mfma_f32_16x16x32_bf16 v[2:5], v[184:187], v[218:221], v[2:5]
	s_setprio 0
	s_barrier
	s_add_i32 s25, 0, 0x18000
	s_add_i32 s30, 0, 0x1c000
	v_add_u32_e32 v142, s25, v171
	v_add_u32_e32 v175, s30, v171
	ds_read_b128 v[130:133], v142
	ds_read_b128 v[134:137], v142 offset:1024
	ds_read_b128 v[138:141], v142 offset:2048
	ds_read_b128 v[142:145], v142 offset:3072
	ds_read_b128 v[164:167], v175
	ds_read_b128 v[176:179], v175 offset:1024
	ds_read_b128 v[180:183], v175 offset:2048
	ds_read_b128 v[184:187], v175 offset:3072
	s_add_u32 s28, s68, 0x40000
	s_addc_u32 s29, s69, 0
	s_mov_b32 m0, s75
	v_lshl_add_u64 v[228:229], s[28:29], 0, v[152:153]
	ds_read_b128 v[188:191], v174 offset:32768
	ds_read_b128 v[192:195], v174 offset:33792
	ds_read_b128 v[196:199], v174 offset:34816
	ds_read_b128 v[200:203], v174 offset:35840
	ds_read_b128 v[206:209], v174 offset:36864
	ds_read_b128 v[210:213], v174 offset:37888
	ds_read_b128 v[214:217], v174 offset:38912
	ds_read_b128 v[218:221], v174 offset:39936
	global_load_lds_dwordx4 v[228:229], off
	s_mov_b32 m0, s76
	v_lshl_add_u64 v[228:229], s[28:29], 0, v[148:149]
	global_load_lds_dwordx4 v[228:229], off
	s_waitcnt vmcnt(8) lgkmcnt(0)
	s_setprio 1
	s_barrier
	v_mfma_f32_16x16x32_bf16 v[126:129], v[130:133], v[188:191], v[126:129]
	v_mfma_f32_16x16x32_bf16 v[122:125], v[138:141], v[188:191], v[122:125]
	v_mfma_f32_16x16x32_bf16 v[110:113], v[130:133], v[196:199], v[110:113]
	v_mfma_f32_16x16x32_bf16 v[106:109], v[138:141], v[196:199], v[106:109]
	v_mfma_f32_16x16x32_bf16 v[94:97], v[130:133], v[206:209], v[94:97]
	v_mfma_f32_16x16x32_bf16 v[90:93], v[138:141], v[206:209], v[90:93]
	v_mfma_f32_16x16x32_bf16 v[78:81], v[130:133], v[214:217], v[78:81]
	v_mfma_f32_16x16x32_bf16 v[74:77], v[138:141], v[214:217], v[74:77]
	v_mfma_f32_16x16x32_bf16 v[126:129], v[134:137], v[192:195], v[126:129]
	v_mfma_f32_16x16x32_bf16 v[122:125], v[142:145], v[192:195], v[122:125]
	v_mfma_f32_16x16x32_bf16 v[110:113], v[134:137], v[200:203], v[110:113]
	v_mfma_f32_16x16x32_bf16 v[106:109], v[142:145], v[200:203], v[106:109]
	v_mfma_f32_16x16x32_bf16 v[94:97], v[134:137], v[210:213], v[94:97]
	v_mfma_f32_16x16x32_bf16 v[90:93], v[142:145], v[210:213], v[90:93]
	v_mfma_f32_16x16x32_bf16 v[78:81], v[134:137], v[218:221], v[78:81]
	v_mfma_f32_16x16x32_bf16 v[74:77], v[142:145], v[218:221], v[74:77]
	v_mfma_f32_16x16x32_bf16 v[118:121], v[164:167], v[188:191], v[118:121]
	v_mfma_f32_16x16x32_bf16 v[114:117], v[180:183], v[188:191], v[114:117]
	v_mfma_f32_16x16x32_bf16 v[102:105], v[164:167], v[196:199], v[102:105]
	v_mfma_f32_16x16x32_bf16 v[98:101], v[180:183], v[196:199], v[98:101]
	v_mfma_f32_16x16x32_bf16 v[86:89], v[164:167], v[206:209], v[86:89]
	v_mfma_f32_16x16x32_bf16 v[82:85], v[180:183], v[206:209], v[82:85]
	v_mfma_f32_16x16x32_bf16 v[70:73], v[164:167], v[214:217], v[70:73]
	v_mfma_f32_16x16x32_bf16 v[66:69], v[180:183], v[214:217], v[66:69]
	v_mfma_f32_16x16x32_bf16 v[118:121], v[176:179], v[192:195], v[118:121]
	v_mfma_f32_16x16x32_bf16 v[114:117], v[184:187], v[192:195], v[114:117]
	v_mfma_f32_16x16x32_bf16 v[102:105], v[176:179], v[200:203], v[102:105]
	v_mfma_f32_16x16x32_bf16 v[98:101], v[184:187], v[200:203], v[98:101]
	v_mfma_f32_16x16x32_bf16 v[86:89], v[176:179], v[210:213], v[86:89]
	v_mfma_f32_16x16x32_bf16 v[82:85], v[184:187], v[210:213], v[82:85]
	v_mfma_f32_16x16x32_bf16 v[70:73], v[176:179], v[218:221], v[70:73]
	v_mfma_f32_16x16x32_bf16 v[66:69], v[184:187], v[218:221], v[66:69]
	s_setprio 0
	s_barrier
	s_add_i32 s25, s25, s70
	v_lshl_add_u64 v[168:169], v[168:169], 0, s[36:37]
	s_mov_b32 m0, s25
	ds_read_b128 v[188:191], v174 offset:49152
	ds_read_b128 v[192:195], v174 offset:50176
	ds_read_b128 v[196:199], v174 offset:51200
	ds_read_b128 v[200:203], v174 offset:52224
	ds_read_b128 v[206:209], v174 offset:53248
	ds_read_b128 v[210:213], v174 offset:54272
	ds_read_b128 v[214:217], v174 offset:55296
	ds_read_b128 v[218:221], v174 offset:56320
	global_load_lds_dwordx4 v[168:169], off
	s_add_i32 m0, s25, 0x2000
	s_add_u32 s28, s66, 0x40080
	v_lshl_add_u64 v[168:169], v[222:223], 0, s[36:37]
	s_addc_u32 s29, s67, 0
	s_add_i32 s25, s30, s70
	global_load_lds_dwordx4 v[168:169], off
	s_mov_b32 m0, s25
	v_lshl_add_u64 v[168:169], s[28:29], 0, v[150:151]
	global_load_lds_dwordx4 v[168:169], off
	s_add_i32 m0, s25, 0x2000
	v_lshl_add_u64 v[168:169], s[28:29], 0, v[146:147]
	global_load_lds_dwordx4 v[168:169], off
	s_mov_b32 m0, s79
	v_lshl_add_u64 v[168:169], v[224:225], 0, s[36:37]
	global_load_lds_dwordx4 v[168:169], off
	s_mov_b32 m0, s80
	v_lshl_add_u64 v[168:169], v[226:227], 0, s[36:37]
	global_load_lds_dwordx4 v[168:169], off
	s_waitcnt vmcnt(8) lgkmcnt(0)
	s_setprio 1
	s_barrier
	v_mfma_f32_16x16x32_bf16 v[62:65], v[130:133], v[188:191], v[62:65]
	v_mfma_f32_16x16x32_bf16 v[58:61], v[138:141], v[188:191], v[58:61]
	v_mfma_f32_16x16x32_bf16 v[46:49], v[130:133], v[196:199], v[46:49]
	v_mfma_f32_16x16x32_bf16 v[42:45], v[138:141], v[196:199], v[42:45]
	v_mfma_f32_16x16x32_bf16 v[30:33], v[130:133], v[206:209], v[30:33]
	v_mfma_f32_16x16x32_bf16 v[26:29], v[138:141], v[206:209], v[26:29]
	v_mfma_f32_16x16x32_bf16 v[14:17], v[130:133], v[214:217], v[14:17]
	v_mfma_f32_16x16x32_bf16 v[10:13], v[138:141], v[214:217], v[10:13]
	v_mfma_f32_16x16x32_bf16 v[62:65], v[134:137], v[192:195], v[62:65]
	v_mfma_f32_16x16x32_bf16 v[58:61], v[142:145], v[192:195], v[58:61]
	v_mfma_f32_16x16x32_bf16 v[46:49], v[134:137], v[200:203], v[46:49]
	v_mfma_f32_16x16x32_bf16 v[42:45], v[142:145], v[200:203], v[42:45]
	v_mfma_f32_16x16x32_bf16 v[30:33], v[134:137], v[210:213], v[30:33]
	v_mfma_f32_16x16x32_bf16 v[26:29], v[142:145], v[210:213], v[26:29]
	v_mfma_f32_16x16x32_bf16 v[14:17], v[134:137], v[218:221], v[14:17]
	v_mfma_f32_16x16x32_bf16 v[10:13], v[142:145], v[218:221], v[10:13]
	v_mfma_f32_16x16x32_bf16 v[54:57], v[164:167], v[188:191], v[54:57]
	v_mfma_f32_16x16x32_bf16 v[50:53], v[180:183], v[188:191], v[50:53]
	v_mfma_f32_16x16x32_bf16 v[38:41], v[164:167], v[196:199], v[38:41]
	v_mfma_f32_16x16x32_bf16 v[34:37], v[180:183], v[196:199], v[34:37]
	v_mfma_f32_16x16x32_bf16 v[22:25], v[164:167], v[206:209], v[22:25]
	v_mfma_f32_16x16x32_bf16 v[18:21], v[180:183], v[206:209], v[18:21]
	v_mfma_f32_16x16x32_bf16 v[6:9], v[164:167], v[214:217], v[6:9]
	v_mfma_f32_16x16x32_bf16 v[2:5], v[180:183], v[214:217], v[2:5]
	v_mfma_f32_16x16x32_bf16 v[54:57], v[176:179], v[192:195], v[54:57]
	v_mfma_f32_16x16x32_bf16 v[50:53], v[184:187], v[192:195], v[50:53]
	v_mfma_f32_16x16x32_bf16 v[38:41], v[176:179], v[200:203], v[38:41]
	v_mfma_f32_16x16x32_bf16 v[34:37], v[184:187], v[200:203], v[34:37]
	v_mfma_f32_16x16x32_bf16 v[22:25], v[176:179], v[210:213], v[22:25]
	v_mfma_f32_16x16x32_bf16 v[18:21], v[184:187], v[210:213], v[18:21]
	v_mfma_f32_16x16x32_bf16 v[6:9], v[176:179], v[218:221], v[6:9]
	v_mfma_f32_16x16x32_bf16 v[2:5], v[184:187], v[218:221], v[2:5]
	s_setprio 0
	s_barrier
	s_add_i32 s24, s24, 2
	s_add_u32 s64, s64, 0x100
	s_addc_u32 s65, s65, 0
	s_add_u32 s18, s18, 0x100
	s_addc_u32 s19, s19, 0
	s_cmp_gt_u32 s24, 13
	.p2align	6

.LBB0_1427:
	s_add_u32 s90, s35, s86
	s_addc_u32 s91, s64, s87
	s_and_b64 s[14:15], s[88:89], exec
	s_cselect_b32 s14, s91, s11
	s_cselect_b32 s15, s90, s10
	s_add_u32 s92, s65, s74
	s_addc_u32 s93, s68, s75
	s_and_b64 s[66:67], s[88:89], exec
	s_cselect_b32 s51, s93, s95
	s_cselect_b32 s84, s92, s94
	s_add_i32 s85, s18, -2
	s_add_u32 s10, s10, 0x40080
	s_addc_u32 s11, s11, 0
	s_add_u32 vcc_lo, s94, 0x100
	s_addc_u32 vcc_hi, s95, 0
	s_mov_b32 s94, 0
	s_waitcnt vmcnt(0)
	s_add_i32 s66, s94, 2
	s_add_u32 s67, s10, 0xfffc0080
	s_addc_u32 s72, s11, -1
	s_cmp_eq_u32 s85, s94
	s_cselect_b32 s97, s14, s72
	s_cselect_b32 s96, s15, s67
	s_cselect_b32 s95, s51, vcc_hi
	s_cselect_b32 s94, s84, vcc_lo
	s_add_i32 s67, 0, 0x10000
	s_add_i32 s62, 0, 0x14000
	v_add_u32_e32 v126, s67, v199
	v_add_u32_e32 v158, s62, v199
	ds_read_b128 v[114:117], v126
	ds_read_b128 v[118:121], v126 offset:1024
	ds_read_b128 v[122:125], v126 offset:2048
	ds_read_b128 v[126:129], v126 offset:3072
	ds_read_b128 v[146:149], v158
	ds_read_b128 v[150:153], v158 offset:1024
	ds_read_b128 v[154:157], v158 offset:2048
	ds_read_b128 v[158:161], v158 offset:3072
	v_lshl_add_u64 v[202:203], s[10:11], 0, v[196:197]
	s_add_i32 m0, s28, 0xc000
	ds_read_b128 v[162:165], v214
	ds_read_b128 v[166:169], v214 offset:1024
	ds_read_b128 v[216:219], v214 offset:2048
	ds_read_b128 v[220:223], v214 offset:3072
	ds_read_b128 v[224:227], v214 offset:4096
	ds_read_b128 v[228:231], v214 offset:5120
	ds_read_b128 v[232:235], v214 offset:6144
	ds_read_b128 v[236:239], v214 offset:7168
	global_load_lds_dwordx4 v[202:203], off
	s_add_i32 m0, s28, 0xe000
	v_lshl_add_u64 v[202:203], s[10:11], 0, v[176:177]
	global_load_lds_dwordx4 v[202:203], off
	s_waitcnt vmcnt(8) lgkmcnt(0)
	s_setprio 1
	s_barrier
	v_mfma_f32_16x16x32_bf16 v[142:145], v[114:117], v[162:165], 0
	v_mfma_f32_16x16x32_bf16 v[138:141], v[122:125], v[162:165], 0
	v_mfma_f32_16x16x32_bf16 v[110:113], v[114:117], v[216:219], 0
	v_mfma_f32_16x16x32_bf16 v[106:109], v[122:125], v[216:219], 0
	v_mfma_f32_16x16x32_bf16 v[98:101], v[114:117], v[224:227], 0
	v_mfma_f32_16x16x32_bf16 v[90:93], v[122:125], v[224:227], 0
	v_mfma_f32_16x16x32_bf16 v[82:85], v[114:117], v[232:235], 0
	v_mfma_f32_16x16x32_bf16 v[74:77], v[122:125], v[232:235], 0
	v_mfma_f32_16x16x32_bf16 v[142:145], v[118:121], v[166:169], v[142:145]
	v_mfma_f32_16x16x32_bf16 v[138:141], v[126:129], v[166:169], v[138:141]
	v_mfma_f32_16x16x32_bf16 v[110:113], v[118:121], v[220:223], v[110:113]
	v_mfma_f32_16x16x32_bf16 v[106:109], v[126:129], v[220:223], v[106:109]
	v_mfma_f32_16x16x32_bf16 v[98:101], v[118:121], v[228:231], v[98:101]
	v_mfma_f32_16x16x32_bf16 v[90:93], v[126:129], v[228:231], v[90:93]
	v_mfma_f32_16x16x32_bf16 v[82:85], v[118:121], v[236:239], v[82:85]
	v_mfma_f32_16x16x32_bf16 v[74:77], v[126:129], v[236:239], v[74:77]
	v_mfma_f32_16x16x32_bf16 v[134:137], v[146:149], v[162:165], 0
	v_mfma_f32_16x16x32_bf16 v[130:133], v[154:157], v[162:165], 0
	v_mfma_f32_16x16x32_bf16 v[102:105], v[146:149], v[216:219], 0
	v_mfma_f32_16x16x32_bf16 v[94:97], v[154:157], v[216:219], 0
	v_mfma_f32_16x16x32_bf16 v[86:89], v[146:149], v[224:227], 0
	v_mfma_f32_16x16x32_bf16 v[78:81], v[154:157], v[224:227], 0
	v_mfma_f32_16x16x32_bf16 v[70:73], v[146:149], v[232:235], 0
	v_mfma_f32_16x16x32_bf16 v[66:69], v[154:157], v[232:235], 0
	v_mfma_f32_16x16x32_bf16 v[134:137], v[150:153], v[166:169], v[134:137]
	v_mfma_f32_16x16x32_bf16 v[130:133], v[158:161], v[166:169], v[130:133]
	v_mfma_f32_16x16x32_bf16 v[102:105], v[150:153], v[220:223], v[102:105]
	v_mfma_f32_16x16x32_bf16 v[94:97], v[158:161], v[220:223], v[94:97]
	v_mfma_f32_16x16x32_bf16 v[86:89], v[150:153], v[228:231], v[86:89]
	v_mfma_f32_16x16x32_bf16 v[78:81], v[158:161], v[228:231], v[78:81]
	v_mfma_f32_16x16x32_bf16 v[70:73], v[150:153], v[236:239], v[70:73]
	v_mfma_f32_16x16x32_bf16 v[66:69], v[158:161], v[236:239], v[66:69]
	s_setprio 0
	s_barrier
	s_add_i32 s63, s67, s17
	v_lshl_add_u64 v[202:203], s[94:95], 0, v[174:175]
	s_mov_b32 m0, s63
	ds_read_b128 v[162:165], v214 offset:16384
	ds_read_b128 v[166:169], v214 offset:17408
	ds_read_b128 v[216:219], v214 offset:18432
	ds_read_b128 v[220:223], v214 offset:19456
	ds_read_b128 v[224:227], v214 offset:20480
	ds_read_b128 v[228:231], v214 offset:21504
	ds_read_b128 v[232:235], v214 offset:22528
	ds_read_b128 v[236:239], v214 offset:23552
	global_load_lds_dwordx4 v[202:203], off
	s_add_i32 m0, s63, 0x2000
	s_add_u32 s72, s94, 0x40000
	v_lshl_add_u64 v[240:241], s[94:95], 0, v[178:179]
	s_addc_u32 s73, s95, 0
	s_add_i32 s62, s62, s17
	global_load_lds_dwordx4 v[240:241], off
	v_lshl_add_u64 v[242:243], s[72:73], 0, v[174:175]
	s_mov_b32 m0, s62
	v_lshl_add_u64 v[244:245], s[96:97], 0, v[176:177]
	global_load_lds_dwordx4 v[242:243], off
	s_add_i32 m0, s62, 0x2000
	v_lshl_add_u64 v[242:243], s[72:73], 0, v[178:179]
	global_load_lds_dwordx4 v[242:243], off
	s_mov_b32 m0, s28
	v_lshl_add_u64 v[242:243], s[96:97], 0, v[172:173]
	global_load_lds_dwordx4 v[242:243], off
	s_mov_b32 m0, s29
	s_nop 0
	global_load_lds_dwordx4 v[244:245], off
	s_waitcnt vmcnt(8) lgkmcnt(0)
	s_setprio 1
	s_barrier
	v_mfma_f32_16x16x32_bf16 v[62:65], v[114:117], v[162:165], 0
	v_mfma_f32_16x16x32_bf16 v[58:61], v[122:125], v[162:165], 0
	v_mfma_f32_16x16x32_bf16 v[50:53], v[114:117], v[216:219], 0
	v_mfma_f32_16x16x32_bf16 v[42:45], v[122:125], v[216:219], 0
	v_mfma_f32_16x16x32_bf16 v[34:37], v[114:117], v[224:227], 0
	v_mfma_f32_16x16x32_bf16 v[26:29], v[122:125], v[224:227], 0
	v_mfma_f32_16x16x32_bf16 v[18:21], v[114:117], v[232:235], 0
	v_mfma_f32_16x16x32_bf16 v[10:13], v[122:125], v[232:235], 0
	v_mfma_f32_16x16x32_bf16 v[62:65], v[118:121], v[166:169], v[62:65]
	v_mfma_f32_16x16x32_bf16 v[58:61], v[126:129], v[166:169], v[58:61]
	v_mfma_f32_16x16x32_bf16 v[50:53], v[118:121], v[220:223], v[50:53]
	v_mfma_f32_16x16x32_bf16 v[42:45], v[126:129], v[220:223], v[42:45]
	v_mfma_f32_16x16x32_bf16 v[34:37], v[118:121], v[228:231], v[34:37]
	v_mfma_f32_16x16x32_bf16 v[26:29], v[126:129], v[228:231], v[26:29]
	v_mfma_f32_16x16x32_bf16 v[18:21], v[118:121], v[236:239], v[18:21]
	v_mfma_f32_16x16x32_bf16 v[10:13], v[126:129], v[236:239], v[10:13]
	v_mfma_f32_16x16x32_bf16 v[54:57], v[146:149], v[162:165], 0
	v_mfma_f32_16x16x32_bf16 v[46:49], v[154:157], v[162:165], 0
	v_mfma_f32_16x16x32_bf16 v[38:41], v[146:149], v[216:219], 0
	v_mfma_f32_16x16x32_bf16 v[30:33], v[154:157], v[216:219], 0
	v_mfma_f32_16x16x32_bf16 v[22:25], v[146:149], v[224:227], 0
	v_mfma_f32_16x16x32_bf16 v[14:17], v[154:157], v[224:227], 0
	v_mfma_f32_16x16x32_bf16 v[6:9], v[146:149], v[232:235], 0
	v_mfma_f32_16x16x32_bf16 v[2:5], v[154:157], v[232:235], 0
	v_mfma_f32_16x16x32_bf16 v[54:57], v[150:153], v[166:169], v[54:57]
	v_mfma_f32_16x16x32_bf16 v[46:49], v[158:161], v[166:169], v[46:49]
	v_mfma_f32_16x16x32_bf16 v[38:41], v[150:153], v[220:223], v[38:41]
	v_mfma_f32_16x16x32_bf16 v[30:33], v[158:161], v[220:223], v[30:33]
	v_mfma_f32_16x16x32_bf16 v[22:25], v[150:153], v[228:231], v[22:25]
	v_mfma_f32_16x16x32_bf16 v[14:17], v[158:161], v[228:231], v[14:17]
	v_mfma_f32_16x16x32_bf16 v[6:9], v[150:153], v[236:239], v[6:9]
	v_mfma_f32_16x16x32_bf16 v[2:5], v[158:161], v[236:239], v[2:5]
	s_setprio 0
	s_barrier
	s_add_i32 s62, 0, 0x18000
	s_add_i32 s63, 0, 0x1c000
	v_add_u32_e32 v126, s62, v199
	v_add_u32_e32 v158, s63, v199
	ds_read_b128 v[114:117], v126
	ds_read_b128 v[118:121], v126 offset:1024
	ds_read_b128 v[122:125], v126 offset:2048
	ds_read_b128 v[126:129], v126 offset:3072
	ds_read_b128 v[146:149], v158
	ds_read_b128 v[150:153], v158 offset:1024
	ds_read_b128 v[154:157], v158 offset:2048
	ds_read_b128 v[158:161], v158 offset:3072
	s_add_u32 s72, s96, 0x40000
	s_addc_u32 s73, s97, 0
	s_mov_b32 m0, s30
	v_lshl_add_u64 v[246:247], s[72:73], 0, v[172:173]
	ds_read_b128 v[162:165], v214 offset:32768
	ds_read_b128 v[166:169], v214 offset:33792
	ds_read_b128 v[216:219], v214 offset:34816
	ds_read_b128 v[220:223], v214 offset:35840
	ds_read_b128 v[224:227], v214 offset:36864
	ds_read_b128 v[228:231], v214 offset:37888
	ds_read_b128 v[232:235], v214 offset:38912
	ds_read_b128 v[236:239], v214 offset:39936
	global_load_lds_dwordx4 v[246:247], off
	s_mov_b32 m0, s31
	v_lshl_add_u64 v[246:247], s[72:73], 0, v[176:177]
	global_load_lds_dwordx4 v[246:247], off
	s_waitcnt vmcnt(8) lgkmcnt(0)
	s_setprio 1
	s_barrier
	v_mfma_f32_16x16x32_bf16 v[142:145], v[114:117], v[162:165], v[142:145]
	v_mfma_f32_16x16x32_bf16 v[138:141], v[122:125], v[162:165], v[138:141]
	v_mfma_f32_16x16x32_bf16 v[110:113], v[114:117], v[216:219], v[110:113]
	v_mfma_f32_16x16x32_bf16 v[106:109], v[122:125], v[216:219], v[106:109]
	v_mfma_f32_16x16x32_bf16 v[98:101], v[114:117], v[224:227], v[98:101]
	v_mfma_f32_16x16x32_bf16 v[90:93], v[122:125], v[224:227], v[90:93]
	v_mfma_f32_16x16x32_bf16 v[82:85], v[114:117], v[232:235], v[82:85]
	v_mfma_f32_16x16x32_bf16 v[74:77], v[122:125], v[232:235], v[74:77]
	v_mfma_f32_16x16x32_bf16 v[142:145], v[118:121], v[166:169], v[142:145]
	v_mfma_f32_16x16x32_bf16 v[138:141], v[126:129], v[166:169], v[138:141]
	v_mfma_f32_16x16x32_bf16 v[110:113], v[118:121], v[220:223], v[110:113]
	v_mfma_f32_16x16x32_bf16 v[106:109], v[126:129], v[220:223], v[106:109]
	v_mfma_f32_16x16x32_bf16 v[98:101], v[118:121], v[228:231], v[98:101]
	v_mfma_f32_16x16x32_bf16 v[90:93], v[126:129], v[228:231], v[90:93]
	v_mfma_f32_16x16x32_bf16 v[82:85], v[118:121], v[236:239], v[82:85]
	v_mfma_f32_16x16x32_bf16 v[74:77], v[126:129], v[236:239], v[74:77]
	v_mfma_f32_16x16x32_bf16 v[134:137], v[146:149], v[162:165], v[134:137]
	v_mfma_f32_16x16x32_bf16 v[130:133], v[154:157], v[162:165], v[130:133]
	v_mfma_f32_16x16x32_bf16 v[102:105], v[146:149], v[216:219], v[102:105]
	v_mfma_f32_16x16x32_bf16 v[94:97], v[154:157], v[216:219], v[94:97]
	v_mfma_f32_16x16x32_bf16 v[86:89], v[146:149], v[224:227], v[86:89]
	v_mfma_f32_16x16x32_bf16 v[78:81], v[154:157], v[224:227], v[78:81]
	v_mfma_f32_16x16x32_bf16 v[70:73], v[146:149], v[232:235], v[70:73]
	v_mfma_f32_16x16x32_bf16 v[66:69], v[154:157], v[232:235], v[66:69]
	v_mfma_f32_16x16x32_bf16 v[134:137], v[150:153], v[166:169], v[134:137]
	v_mfma_f32_16x16x32_bf16 v[130:133], v[158:161], v[166:169], v[130:133]
	v_mfma_f32_16x16x32_bf16 v[102:105], v[150:153], v[220:223], v[102:105]
	v_mfma_f32_16x16x32_bf16 v[94:97], v[158:161], v[220:223], v[94:97]
	v_mfma_f32_16x16x32_bf16 v[86:89], v[150:153], v[228:231], v[86:89]
	v_mfma_f32_16x16x32_bf16 v[78:81], v[158:161], v[228:231], v[78:81]
	v_mfma_f32_16x16x32_bf16 v[70:73], v[150:153], v[236:239], v[70:73]
	v_mfma_f32_16x16x32_bf16 v[66:69], v[158:161], v[236:239], v[66:69]
	s_setprio 0
	s_barrier
	s_add_i32 s62, s62, s17
	v_lshl_add_u64 v[202:203], v[202:203], 0, s[76:77]
	s_mov_b32 m0, s62
	ds_read_b128 v[162:165], v214 offset:49152
	ds_read_b128 v[166:169], v214 offset:50176
	ds_read_b128 v[216:219], v214 offset:51200
	ds_read_b128 v[220:223], v214 offset:52224
	ds_read_b128 v[224:227], v214 offset:53248
	ds_read_b128 v[228:231], v214 offset:54272
	ds_read_b128 v[232:235], v214 offset:55296
	ds_read_b128 v[236:239], v214 offset:56320
	global_load_lds_dwordx4 v[202:203], off
	s_add_i32 m0, s62, 0x2000
	s_add_u32 s72, s94, 0x40080
	v_lshl_add_u64 v[202:203], v[240:241], 0, s[76:77]
	s_addc_u32 s73, s95, 0
	s_add_i32 s62, s63, s17
	global_load_lds_dwordx4 v[202:203], off
	s_mov_b32 m0, s62
	v_lshl_add_u64 v[202:203], s[72:73], 0, v[174:175]
	global_load_lds_dwordx4 v[202:203], off
	s_add_i32 m0, s62, 0x2000
	v_lshl_add_u64 v[202:203], s[72:73], 0, v[178:179]
	global_load_lds_dwordx4 v[202:203], off
	s_mov_b32 m0, s44
	v_lshl_add_u64 v[202:203], v[242:243], 0, s[76:77]
	global_load_lds_dwordx4 v[202:203], off
	s_mov_b32 m0, s36
	v_lshl_add_u64 v[202:203], v[244:245], 0, s[76:77]
	global_load_lds_dwordx4 v[202:203], off
	s_waitcnt vmcnt(8) lgkmcnt(0)
	s_setprio 1
	s_barrier
	v_mfma_f32_16x16x32_bf16 v[62:65], v[114:117], v[162:165], v[62:65]
	v_mfma_f32_16x16x32_bf16 v[58:61], v[122:125], v[162:165], v[58:61]
	v_mfma_f32_16x16x32_bf16 v[50:53], v[114:117], v[216:219], v[50:53]
	v_mfma_f32_16x16x32_bf16 v[42:45], v[122:125], v[216:219], v[42:45]
	v_mfma_f32_16x16x32_bf16 v[34:37], v[114:117], v[224:227], v[34:37]
	v_mfma_f32_16x16x32_bf16 v[26:29], v[122:125], v[224:227], v[26:29]
	v_mfma_f32_16x16x32_bf16 v[18:21], v[114:117], v[232:235], v[18:21]
	v_mfma_f32_16x16x32_bf16 v[10:13], v[122:125], v[232:235], v[10:13]
	v_mfma_f32_16x16x32_bf16 v[62:65], v[118:121], v[166:169], v[62:65]
	v_mfma_f32_16x16x32_bf16 v[58:61], v[126:129], v[166:169], v[58:61]
	v_mfma_f32_16x16x32_bf16 v[50:53], v[118:121], v[220:223], v[50:53]
	v_mfma_f32_16x16x32_bf16 v[42:45], v[126:129], v[220:223], v[42:45]
	v_mfma_f32_16x16x32_bf16 v[34:37], v[118:121], v[228:231], v[34:37]
	v_mfma_f32_16x16x32_bf16 v[26:29], v[126:129], v[228:231], v[26:29]
	v_mfma_f32_16x16x32_bf16 v[18:21], v[118:121], v[236:239], v[18:21]
	v_mfma_f32_16x16x32_bf16 v[10:13], v[126:129], v[236:239], v[10:13]
	v_mfma_f32_16x16x32_bf16 v[54:57], v[146:149], v[162:165], v[54:57]
	v_mfma_f32_16x16x32_bf16 v[46:49], v[154:157], v[162:165], v[46:49]
	v_mfma_f32_16x16x32_bf16 v[38:41], v[146:149], v[216:219], v[38:41]
	v_mfma_f32_16x16x32_bf16 v[30:33], v[154:157], v[216:219], v[30:33]
	v_mfma_f32_16x16x32_bf16 v[22:25], v[146:149], v[224:227], v[22:25]
	v_mfma_f32_16x16x32_bf16 v[14:17], v[154:157], v[224:227], v[14:17]
	v_mfma_f32_16x16x32_bf16 v[6:9], v[146:149], v[232:235], v[6:9]
	v_mfma_f32_16x16x32_bf16 v[2:5], v[154:157], v[232:235], v[2:5]
	v_mfma_f32_16x16x32_bf16 v[54:57], v[150:153], v[166:169], v[54:57]
	v_mfma_f32_16x16x32_bf16 v[46:49], v[158:161], v[166:169], v[46:49]
	v_mfma_f32_16x16x32_bf16 v[38:41], v[150:153], v[220:223], v[38:41]
	v_mfma_f32_16x16x32_bf16 v[30:33], v[158:161], v[220:223], v[30:33]
	v_mfma_f32_16x16x32_bf16 v[22:25], v[150:153], v[228:231], v[22:25]
	v_mfma_f32_16x16x32_bf16 v[14:17], v[158:161], v[228:231], v[14:17]
	v_mfma_f32_16x16x32_bf16 v[6:9], v[150:153], v[236:239], v[6:9]
	v_mfma_f32_16x16x32_bf16 v[2:5], v[158:161], v[236:239], v[2:5]
	s_setprio 0
	s_barrier
	s_add_u32 s10, s10, 0x100
	s_addc_u32 s11, s11, 0
	s_add_u32 vcc_lo, vcc_lo, 0x100
	s_addc_u32 vcc_hi, vcc_hi, 0
	s_cmp_ge_i32 s66, s18
	s_mov_b32 s94, s66
	.p2align	6

.LBB0_1618:
	s_add_u32 s24, s96, s20
	s_addc_u32 s25, s97, s21
	s_and_b64 s[14:15], s[4:5], exec
	s_cselect_b32 s14, s25, s29
	s_cselect_b32 s15, s24, s28
	s_add_u32 s26, s2, s22
	s_addc_u32 s27, s3, s23
	s_and_b64 s[36:37], s[4:5], exec
	s_cselect_b32 s17, s27, s31
	s_cselect_b32 s49, s26, s30
	s_add_u32 s28, s28, 0x40080
	s_addc_u32 s29, s29, 0
	s_add_u32 s50, s30, 0x100
	s_addc_u32 s51, s31, 0
	s_mov_b32 s62, -2
	ds_read_b128 v[154:157], v150
	ds_read_b128 v[158:161], v150 offset:1024
	ds_read_b128 v[162:165], v150 offset:2048
	ds_read_b128 v[166:169], v150 offset:3072
	ds_read_b128 v[170:173], v151
	ds_read_b128 v[174:177], v151 offset:1024
	ds_read_b128 v[178:181], v151 offset:2048
	ds_read_b128 v[182:185], v151 offset:3072
	s_add_u32 s30, s28, 0xfffc0080
	s_addc_u32 s31, s29, -1
	s_cmp_eq_u32 s62, 12
	s_cselect_b32 s37, s14, s31
	s_cselect_b32 s36, s15, s30
	s_cselect_b32 s31, s17, s51
	s_cselect_b32 s30, s49, s50
	v_lshl_add_u64 v[146:147], s[28:29], 0, v[138:139]
	s_add_i32 m0, s19, 0xc000
	ds_read_b128 v[186:189], v152
	ds_read_b128 v[190:193], v152 offset:1024
	ds_read_b128 v[194:197], v152 offset:2048
	ds_read_b128 v[198:201], v152 offset:3072
	ds_read_b128 v[206:209], v152 offset:4096
	ds_read_b128 v[210:213], v152 offset:5120
	ds_read_b128 v[214:217], v152 offset:6144
	ds_read_b128 v[218:221], v152 offset:7168
	global_load_lds_dwordx4 v[146:147], off
	s_add_i32 m0, s19, 0xe000
	v_lshl_add_u64 v[146:147], s[28:29], 0, v[140:141]
	global_load_lds_dwordx4 v[146:147], off
	s_waitcnt vmcnt(8) lgkmcnt(0)
	s_setprio 1
	s_barrier
	v_mfma_f32_16x16x32_bf16 v[126:129], v[154:157], v[186:189], 0
	v_mfma_f32_16x16x32_bf16 v[122:125], v[162:165], v[186:189], 0
	v_mfma_f32_16x16x32_bf16 v[110:113], v[154:157], v[194:197], 0
	v_mfma_f32_16x16x32_bf16 v[106:109], v[162:165], v[194:197], 0
	v_mfma_f32_16x16x32_bf16 v[94:97], v[154:157], v[206:209], 0
	v_mfma_f32_16x16x32_bf16 v[90:93], v[162:165], v[206:209], 0
	v_mfma_f32_16x16x32_bf16 v[78:81], v[154:157], v[214:217], 0
	v_mfma_f32_16x16x32_bf16 v[74:77], v[162:165], v[214:217], 0
	v_mfma_f32_16x16x32_bf16 v[126:129], v[158:161], v[190:193], v[126:129]
	v_mfma_f32_16x16x32_bf16 v[122:125], v[166:169], v[190:193], v[122:125]
	v_mfma_f32_16x16x32_bf16 v[110:113], v[158:161], v[198:201], v[110:113]
	v_mfma_f32_16x16x32_bf16 v[106:109], v[166:169], v[198:201], v[106:109]
	v_mfma_f32_16x16x32_bf16 v[94:97], v[158:161], v[210:213], v[94:97]
	v_mfma_f32_16x16x32_bf16 v[90:93], v[166:169], v[210:213], v[90:93]
	v_mfma_f32_16x16x32_bf16 v[78:81], v[158:161], v[218:221], v[78:81]
	v_mfma_f32_16x16x32_bf16 v[74:77], v[166:169], v[218:221], v[74:77]
	v_mfma_f32_16x16x32_bf16 v[118:121], v[170:173], v[186:189], 0
	v_mfma_f32_16x16x32_bf16 v[114:117], v[178:181], v[186:189], 0
	v_mfma_f32_16x16x32_bf16 v[102:105], v[170:173], v[194:197], 0
	v_mfma_f32_16x16x32_bf16 v[98:101], v[178:181], v[194:197], 0
	v_mfma_f32_16x16x32_bf16 v[86:89], v[170:173], v[206:209], 0
	v_mfma_f32_16x16x32_bf16 v[82:85], v[178:181], v[206:209], 0
	v_mfma_f32_16x16x32_bf16 v[70:73], v[170:173], v[214:217], 0
	v_mfma_f32_16x16x32_bf16 v[66:69], v[178:181], v[214:217], 0
	v_mfma_f32_16x16x32_bf16 v[118:121], v[174:177], v[190:193], v[118:121]
	v_mfma_f32_16x16x32_bf16 v[114:117], v[182:185], v[190:193], v[114:117]
	v_mfma_f32_16x16x32_bf16 v[102:105], v[174:177], v[198:201], v[102:105]
	v_mfma_f32_16x16x32_bf16 v[98:101], v[182:185], v[198:201], v[98:101]
	v_mfma_f32_16x16x32_bf16 v[86:89], v[174:177], v[210:213], v[86:89]
	v_mfma_f32_16x16x32_bf16 v[82:85], v[182:185], v[210:213], v[82:85]
	v_mfma_f32_16x16x32_bf16 v[70:73], v[174:177], v[218:221], v[70:73]
	v_mfma_f32_16x16x32_bf16 v[66:69], v[182:185], v[218:221], v[66:69]
	s_setprio 0
	s_barrier
	s_add_i32 s63, s45, s12
	v_lshl_add_u64 v[146:147], s[30:31], 0, v[134:135]
	s_mov_b32 m0, s63
	ds_read_b128 v[186:189], v152 offset:16384
	ds_read_b128 v[190:193], v152 offset:17408
	ds_read_b128 v[194:197], v152 offset:18432
	ds_read_b128 v[198:201], v152 offset:19456
	ds_read_b128 v[206:209], v152 offset:20480
	ds_read_b128 v[210:213], v152 offset:21504
	ds_read_b128 v[214:217], v152 offset:22528
	ds_read_b128 v[218:221], v152 offset:23552
	global_load_lds_dwordx4 v[146:147], off
	s_add_i32 m0, s63, 0x2000
	s_add_u32 s64, s30, 0x40000
	v_lshl_add_u64 v[202:203], s[30:31], 0, v[130:131]
	s_addc_u32 s65, s31, 0
	s_add_i32 s63, s46, s12
	global_load_lds_dwordx4 v[202:203], off
	v_lshl_add_u64 v[222:223], s[64:65], 0, v[134:135]
	s_mov_b32 m0, s63
	v_lshl_add_u64 v[224:225], s[36:37], 0, v[132:133]
	global_load_lds_dwordx4 v[222:223], off
	s_add_i32 m0, s63, 0x2000
	v_lshl_add_u64 v[222:223], s[64:65], 0, v[130:131]
	global_load_lds_dwordx4 v[222:223], off
	s_mov_b32 m0, s19
	v_lshl_add_u64 v[222:223], s[36:37], 0, v[136:137]
	global_load_lds_dwordx4 v[222:223], off
	s_mov_b32 m0, s33
	s_nop 0
	global_load_lds_dwordx4 v[224:225], off
	s_waitcnt vmcnt(8) lgkmcnt(0)
	s_setprio 1
	s_barrier
	v_mfma_f32_16x16x32_bf16 v[62:65], v[154:157], v[186:189], 0
	v_mfma_f32_16x16x32_bf16 v[58:61], v[162:165], v[186:189], 0
	v_mfma_f32_16x16x32_bf16 v[46:49], v[154:157], v[194:197], 0
	v_mfma_f32_16x16x32_bf16 v[42:45], v[162:165], v[194:197], 0
	v_mfma_f32_16x16x32_bf16 v[30:33], v[154:157], v[206:209], 0
	v_mfma_f32_16x16x32_bf16 v[26:29], v[162:165], v[206:209], 0
	v_mfma_f32_16x16x32_bf16 v[14:17], v[154:157], v[214:217], 0
	v_mfma_f32_16x16x32_bf16 v[10:13], v[162:165], v[214:217], 0
	v_mfma_f32_16x16x32_bf16 v[62:65], v[158:161], v[190:193], v[62:65]
	v_mfma_f32_16x16x32_bf16 v[58:61], v[166:169], v[190:193], v[58:61]
	v_mfma_f32_16x16x32_bf16 v[46:49], v[158:161], v[198:201], v[46:49]
	v_mfma_f32_16x16x32_bf16 v[42:45], v[166:169], v[198:201], v[42:45]
	v_mfma_f32_16x16x32_bf16 v[30:33], v[158:161], v[210:213], v[30:33]
	v_mfma_f32_16x16x32_bf16 v[26:29], v[166:169], v[210:213], v[26:29]
	v_mfma_f32_16x16x32_bf16 v[14:17], v[158:161], v[218:221], v[14:17]
	v_mfma_f32_16x16x32_bf16 v[10:13], v[166:169], v[218:221], v[10:13]
	v_mfma_f32_16x16x32_bf16 v[54:57], v[170:173], v[186:189], 0
	v_mfma_f32_16x16x32_bf16 v[50:53], v[178:181], v[186:189], 0
	v_mfma_f32_16x16x32_bf16 v[38:41], v[170:173], v[194:197], 0
	v_mfma_f32_16x16x32_bf16 v[34:37], v[178:181], v[194:197], 0
	v_mfma_f32_16x16x32_bf16 v[22:25], v[170:173], v[206:209], 0
	v_mfma_f32_16x16x32_bf16 v[18:21], v[178:181], v[206:209], 0
	v_mfma_f32_16x16x32_bf16 v[6:9], v[170:173], v[214:217], 0
	v_mfma_f32_16x16x32_bf16 v[2:5], v[178:181], v[214:217], 0
	v_mfma_f32_16x16x32_bf16 v[54:57], v[174:177], v[190:193], v[54:57]
	v_mfma_f32_16x16x32_bf16 v[50:53], v[182:185], v[190:193], v[50:53]
	v_mfma_f32_16x16x32_bf16 v[38:41], v[174:177], v[198:201], v[38:41]
	v_mfma_f32_16x16x32_bf16 v[34:37], v[182:185], v[198:201], v[34:37]
	v_mfma_f32_16x16x32_bf16 v[22:25], v[174:177], v[210:213], v[22:25]
	v_mfma_f32_16x16x32_bf16 v[18:21], v[182:185], v[210:213], v[18:21]
	v_mfma_f32_16x16x32_bf16 v[6:9], v[174:177], v[218:221], v[6:9]
	v_mfma_f32_16x16x32_bf16 v[2:5], v[182:185], v[218:221], v[2:5]
	s_setprio 0
	s_barrier
	s_add_i32 s63, 0, 0x18000
	v_add_u32_e32 v153, s63, v149
	s_add_i32 s64, 0, 0x1c000
	ds_read_b128 v[154:157], v153
	ds_read_b128 v[158:161], v153 offset:1024
	ds_read_b128 v[162:165], v153 offset:2048
	ds_read_b128 v[166:169], v153 offset:3072
	v_add_u32_e32 v153, s64, v149
	ds_read_b128 v[170:173], v153
	ds_read_b128 v[174:177], v153 offset:1024
	ds_read_b128 v[178:181], v153 offset:2048
	ds_read_b128 v[182:185], v153 offset:3072
	s_add_u32 s36, s36, 0x40000
	s_addc_u32 s37, s37, 0
	s_mov_b32 m0, s35
	v_lshl_add_u64 v[226:227], s[36:37], 0, v[136:137]
	ds_read_b128 v[186:189], v152 offset:32768
	ds_read_b128 v[190:193], v152 offset:33792
	ds_read_b128 v[194:197], v152 offset:34816
	ds_read_b128 v[198:201], v152 offset:35840
	ds_read_b128 v[206:209], v152 offset:36864
	ds_read_b128 v[210:213], v152 offset:37888
	ds_read_b128 v[214:217], v152 offset:38912
	ds_read_b128 v[218:221], v152 offset:39936
	global_load_lds_dwordx4 v[226:227], off
	s_mov_b32 m0, s38
	v_lshl_add_u64 v[226:227], s[36:37], 0, v[132:133]
	global_load_lds_dwordx4 v[226:227], off
	s_waitcnt vmcnt(8) lgkmcnt(0)
	s_setprio 1
	s_barrier
	v_mfma_f32_16x16x32_bf16 v[126:129], v[154:157], v[186:189], v[126:129]
	v_mfma_f32_16x16x32_bf16 v[122:125], v[162:165], v[186:189], v[122:125]
	v_mfma_f32_16x16x32_bf16 v[110:113], v[154:157], v[194:197], v[110:113]
	v_mfma_f32_16x16x32_bf16 v[106:109], v[162:165], v[194:197], v[106:109]
	v_mfma_f32_16x16x32_bf16 v[94:97], v[154:157], v[206:209], v[94:97]
	v_mfma_f32_16x16x32_bf16 v[90:93], v[162:165], v[206:209], v[90:93]
	v_mfma_f32_16x16x32_bf16 v[78:81], v[154:157], v[214:217], v[78:81]
	v_mfma_f32_16x16x32_bf16 v[74:77], v[162:165], v[214:217], v[74:77]
	v_mfma_f32_16x16x32_bf16 v[126:129], v[158:161], v[190:193], v[126:129]
	v_mfma_f32_16x16x32_bf16 v[122:125], v[166:169], v[190:193], v[122:125]
	v_mfma_f32_16x16x32_bf16 v[110:113], v[158:161], v[198:201], v[110:113]
	v_mfma_f32_16x16x32_bf16 v[106:109], v[166:169], v[198:201], v[106:109]
	v_mfma_f32_16x16x32_bf16 v[94:97], v[158:161], v[210:213], v[94:97]
	v_mfma_f32_16x16x32_bf16 v[90:93], v[166:169], v[210:213], v[90:93]
	v_mfma_f32_16x16x32_bf16 v[78:81], v[158:161], v[218:221], v[78:81]
	v_mfma_f32_16x16x32_bf16 v[74:77], v[166:169], v[218:221], v[74:77]
	v_mfma_f32_16x16x32_bf16 v[118:121], v[170:173], v[186:189], v[118:121]
	v_mfma_f32_16x16x32_bf16 v[114:117], v[178:181], v[186:189], v[114:117]
	v_mfma_f32_16x16x32_bf16 v[102:105], v[170:173], v[194:197], v[102:105]
	v_mfma_f32_16x16x32_bf16 v[98:101], v[178:181], v[194:197], v[98:101]
	v_mfma_f32_16x16x32_bf16 v[86:89], v[170:173], v[206:209], v[86:89]
	v_mfma_f32_16x16x32_bf16 v[82:85], v[178:181], v[206:209], v[82:85]
	v_mfma_f32_16x16x32_bf16 v[70:73], v[170:173], v[214:217], v[70:73]
	v_mfma_f32_16x16x32_bf16 v[66:69], v[178:181], v[214:217], v[66:69]
	v_mfma_f32_16x16x32_bf16 v[118:121], v[174:177], v[190:193], v[118:121]
	v_mfma_f32_16x16x32_bf16 v[114:117], v[182:185], v[190:193], v[114:117]
	v_mfma_f32_16x16x32_bf16 v[102:105], v[174:177], v[198:201], v[102:105]
	v_mfma_f32_16x16x32_bf16 v[98:101], v[182:185], v[198:201], v[98:101]
	v_mfma_f32_16x16x32_bf16 v[86:89], v[174:177], v[210:213], v[86:89]
	v_mfma_f32_16x16x32_bf16 v[82:85], v[182:185], v[210:213], v[82:85]
	v_mfma_f32_16x16x32_bf16 v[70:73], v[174:177], v[218:221], v[70:73]
	v_mfma_f32_16x16x32_bf16 v[66:69], v[182:185], v[218:221], v[66:69]
	s_setprio 0
	s_barrier
	s_add_i32 s36, s63, s12
	v_lshl_add_u64 v[146:147], v[146:147], 0, s[8:9]
	s_mov_b32 m0, s36
	ds_read_b128 v[186:189], v152 offset:49152
	ds_read_b128 v[190:193], v152 offset:50176
	ds_read_b128 v[194:197], v152 offset:51200
	ds_read_b128 v[198:201], v152 offset:52224
	ds_read_b128 v[206:209], v152 offset:53248
	ds_read_b128 v[210:213], v152 offset:54272
	ds_read_b128 v[214:217], v152 offset:55296
	ds_read_b128 v[218:221], v152 offset:56320
	global_load_lds_dwordx4 v[146:147], off
	s_add_i32 m0, s36, 0x2000
	s_add_u32 s30, s30, 0x40080
	v_lshl_add_u64 v[146:147], v[202:203], 0, s[8:9]
	s_addc_u32 s31, s31, 0
	s_add_i32 s36, s64, s12
	global_load_lds_dwordx4 v[146:147], off
	s_mov_b32 m0, s36
	v_lshl_add_u64 v[146:147], s[30:31], 0, v[134:135]
	global_load_lds_dwordx4 v[146:147], off
	s_add_i32 m0, s36, 0x2000
	v_lshl_add_u64 v[146:147], s[30:31], 0, v[130:131]
	global_load_lds_dwordx4 v[146:147], off
	s_mov_b32 m0, s42
	v_lshl_add_u64 v[146:147], v[222:223], 0, s[8:9]
	global_load_lds_dwordx4 v[146:147], off
	s_mov_b32 m0, s43
	v_lshl_add_u64 v[146:147], v[224:225], 0, s[8:9]
	global_load_lds_dwordx4 v[146:147], off
	s_waitcnt vmcnt(8) lgkmcnt(0)
	s_setprio 1
	s_barrier
	v_mfma_f32_16x16x32_bf16 v[62:65], v[154:157], v[186:189], v[62:65]
	v_mfma_f32_16x16x32_bf16 v[58:61], v[162:165], v[186:189], v[58:61]
	v_mfma_f32_16x16x32_bf16 v[46:49], v[154:157], v[194:197], v[46:49]
	v_mfma_f32_16x16x32_bf16 v[42:45], v[162:165], v[194:197], v[42:45]
	v_mfma_f32_16x16x32_bf16 v[30:33], v[154:157], v[206:209], v[30:33]
	v_mfma_f32_16x16x32_bf16 v[26:29], v[162:165], v[206:209], v[26:29]
	v_mfma_f32_16x16x32_bf16 v[14:17], v[154:157], v[214:217], v[14:17]
	v_mfma_f32_16x16x32_bf16 v[10:13], v[162:165], v[214:217], v[10:13]
	v_mfma_f32_16x16x32_bf16 v[62:65], v[158:161], v[190:193], v[62:65]
	v_mfma_f32_16x16x32_bf16 v[58:61], v[166:169], v[190:193], v[58:61]
	v_mfma_f32_16x16x32_bf16 v[46:49], v[158:161], v[198:201], v[46:49]
	v_mfma_f32_16x16x32_bf16 v[42:45], v[166:169], v[198:201], v[42:45]
	v_mfma_f32_16x16x32_bf16 v[30:33], v[158:161], v[210:213], v[30:33]
	v_mfma_f32_16x16x32_bf16 v[26:29], v[166:169], v[210:213], v[26:29]
	v_mfma_f32_16x16x32_bf16 v[14:17], v[158:161], v[218:221], v[14:17]
	v_mfma_f32_16x16x32_bf16 v[10:13], v[166:169], v[218:221], v[10:13]
	v_mfma_f32_16x16x32_bf16 v[54:57], v[170:173], v[186:189], v[54:57]
	v_mfma_f32_16x16x32_bf16 v[50:53], v[178:181], v[186:189], v[50:53]
	v_mfma_f32_16x16x32_bf16 v[38:41], v[170:173], v[194:197], v[38:41]
	v_mfma_f32_16x16x32_bf16 v[34:37], v[178:181], v[194:197], v[34:37]
	v_mfma_f32_16x16x32_bf16 v[22:25], v[170:173], v[206:209], v[22:25]
	v_mfma_f32_16x16x32_bf16 v[18:21], v[178:181], v[206:209], v[18:21]
	v_mfma_f32_16x16x32_bf16 v[6:9], v[170:173], v[214:217], v[6:9]
	v_mfma_f32_16x16x32_bf16 v[2:5], v[178:181], v[214:217], v[2:5]
	v_mfma_f32_16x16x32_bf16 v[54:57], v[174:177], v[190:193], v[54:57]
	v_mfma_f32_16x16x32_bf16 v[50:53], v[182:185], v[190:193], v[50:53]
	v_mfma_f32_16x16x32_bf16 v[38:41], v[174:177], v[198:201], v[38:41]
	v_mfma_f32_16x16x32_bf16 v[34:37], v[182:185], v[198:201], v[34:37]
	v_mfma_f32_16x16x32_bf16 v[22:25], v[174:177], v[210:213], v[22:25]
	v_mfma_f32_16x16x32_bf16 v[18:21], v[182:185], v[210:213], v[18:21]
	v_mfma_f32_16x16x32_bf16 v[6:9], v[174:177], v[218:221], v[6:9]
	v_mfma_f32_16x16x32_bf16 v[2:5], v[182:185], v[218:221], v[2:5]
	s_setprio 0
	s_barrier
	s_add_i32 s62, s62, 2
	s_add_u32 s28, s28, 0x100
	s_addc_u32 s29, s29, 0
	s_add_u32 s50, s50, 0x100
	s_addc_u32 s51, s51, 0
	s_cmp_gt_u32 s62, 13
	.p2align	6

.LBB0_1707:
	v_readlane_b32 s46, v249, 32
	v_readlane_b32 s47, v249, 33
	s_add_u32 s46, s46, s42
	s_addc_u32 s47, s47, s43
	s_and_b64 s[48:49], s[44:45], exec
	s_cselect_b32 s34, s47, s51
	s_cselect_b32 s66, s46, s50
	s_add_u32 s48, s35, s40
	s_addc_u32 s49, s70, s41
	s_and_b64 s[64:65], s[44:45], exec
	s_cselect_b32 s67, s49, s63
	s_cselect_b32 s68, s48, s62
	s_add_i32 s69, s7, -2
	s_add_u32 s50, s50, 0x100080
	s_addc_u32 s51, s51, 0
	s_add_u32 s91, s62, 0x100
	s_addc_u32 s92, s63, 0
	s_mov_b32 s62, 0
	s_waitcnt vmcnt(0)
	ds_read_b128 v[130:133], v168
	ds_read_b128 v[134:137], v168 offset:1024
	ds_read_b128 v[138:141], v168 offset:2048
	ds_read_b128 v[142:145], v168 offset:3072
	ds_read_b128 v[162:165], v169
	ds_read_b128 v[172:175], v169 offset:1024
	ds_read_b128 v[176:179], v169 offset:2048
	ds_read_b128 v[180:183], v169 offset:3072
	s_add_i32 s93, s62, 2
	s_add_u32 s63, s50, 0xfff00080
	s_addc_u32 s64, s51, -1
	s_cmp_eq_u32 s69, s62
	s_cselect_b32 s62, s68, s91
	s_cselect_b32 s65, s34, s64
	s_cselect_b32 s64, s66, s63
	s_cselect_b32 s63, s67, s92
	v_lshl_add_u64 v[218:219], s[50:51], 0, v[156:157]
	s_add_i32 m0, s12, 0xc000
	ds_read_b128 v[184:187], v170
	ds_read_b128 v[188:191], v170 offset:1024
	ds_read_b128 v[192:195], v170 offset:2048
	ds_read_b128 v[196:199], v170 offset:3072
	ds_read_b128 v[200:203], v170 offset:4096
	ds_read_b128 v[206:209], v170 offset:5120
	ds_read_b128 v[210:213], v170 offset:6144
	ds_read_b128 v[214:217], v170 offset:7168
	global_load_lds_dwordx4 v[218:219], off
	s_add_i32 m0, s12, 0xe000
	v_lshl_add_u64 v[218:219], s[50:51], 0, v[158:159]
	global_load_lds_dwordx4 v[218:219], off
	s_waitcnt vmcnt(8) lgkmcnt(0)
	s_setprio 1
	s_barrier
	v_mfma_f32_16x16x32_bf16 v[126:129], v[130:133], v[184:187], 0
	v_mfma_f32_16x16x32_bf16 v[122:125], v[138:141], v[184:187], 0
	v_mfma_f32_16x16x32_bf16 v[110:113], v[130:133], v[192:195], 0
	v_mfma_f32_16x16x32_bf16 v[106:109], v[138:141], v[192:195], 0
	v_mfma_f32_16x16x32_bf16 v[98:101], v[130:133], v[200:203], 0
	v_mfma_f32_16x16x32_bf16 v[90:93], v[138:141], v[200:203], 0
	v_mfma_f32_16x16x32_bf16 v[82:85], v[130:133], v[210:213], 0
	v_mfma_f32_16x16x32_bf16 v[74:77], v[138:141], v[210:213], 0
	v_mfma_f32_16x16x32_bf16 v[126:129], v[134:137], v[188:191], v[126:129]
	v_mfma_f32_16x16x32_bf16 v[122:125], v[142:145], v[188:191], v[122:125]
	v_mfma_f32_16x16x32_bf16 v[110:113], v[134:137], v[196:199], v[110:113]
	v_mfma_f32_16x16x32_bf16 v[106:109], v[142:145], v[196:199], v[106:109]
	v_mfma_f32_16x16x32_bf16 v[98:101], v[134:137], v[206:209], v[98:101]
	v_mfma_f32_16x16x32_bf16 v[90:93], v[142:145], v[206:209], v[90:93]
	v_mfma_f32_16x16x32_bf16 v[82:85], v[134:137], v[214:217], v[82:85]
	v_mfma_f32_16x16x32_bf16 v[74:77], v[142:145], v[214:217], v[74:77]
	v_mfma_f32_16x16x32_bf16 v[118:121], v[162:165], v[184:187], 0
	v_mfma_f32_16x16x32_bf16 v[114:117], v[176:179], v[184:187], 0
	v_mfma_f32_16x16x32_bf16 v[102:105], v[162:165], v[192:195], 0
	v_mfma_f32_16x16x32_bf16 v[94:97], v[176:179], v[192:195], 0
	v_mfma_f32_16x16x32_bf16 v[86:89], v[162:165], v[200:203], 0
	v_mfma_f32_16x16x32_bf16 v[78:81], v[176:179], v[200:203], 0
	v_mfma_f32_16x16x32_bf16 v[70:73], v[162:165], v[210:213], 0
	v_mfma_f32_16x16x32_bf16 v[66:69], v[176:179], v[210:213], 0
	v_mfma_f32_16x16x32_bf16 v[118:121], v[172:175], v[188:191], v[118:121]
	v_mfma_f32_16x16x32_bf16 v[114:117], v[180:183], v[188:191], v[114:117]
	v_mfma_f32_16x16x32_bf16 v[102:105], v[172:175], v[196:199], v[102:105]
	v_mfma_f32_16x16x32_bf16 v[94:97], v[180:183], v[196:199], v[94:97]
	v_mfma_f32_16x16x32_bf16 v[86:89], v[172:175], v[206:209], v[86:89]
	v_mfma_f32_16x16x32_bf16 v[78:81], v[180:183], v[206:209], v[78:81]
	v_mfma_f32_16x16x32_bf16 v[70:73], v[172:175], v[214:217], v[70:73]
	v_mfma_f32_16x16x32_bf16 v[66:69], v[180:183], v[214:217], v[66:69]
	s_setprio 0
	s_barrier
	s_add_i32 s94, s31, s2
	v_lshl_add_u64 v[218:219], s[62:63], 0, v[148:149]
	s_mov_b32 m0, s94
	ds_read_b128 v[184:187], v170 offset:16384
	ds_read_b128 v[188:191], v170 offset:17408
	ds_read_b128 v[192:195], v170 offset:18432
	ds_read_b128 v[196:199], v170 offset:19456
	ds_read_b128 v[200:203], v170 offset:20480
	ds_read_b128 v[206:209], v170 offset:21504
	ds_read_b128 v[210:213], v170 offset:22528
	ds_read_b128 v[214:217], v170 offset:23552
	global_load_lds_dwordx4 v[218:219], off
	s_add_i32 m0, s94, 0x2000
	s_add_u32 s94, s62, 0x100000
	v_lshl_add_u64 v[220:221], s[62:63], 0, v[152:153]
	s_addc_u32 s95, s63, 0
	s_add_i32 s96, s82, s2
	global_load_lds_dwordx4 v[220:221], off
	v_lshl_add_u64 v[222:223], s[94:95], 0, v[148:149]
	s_mov_b32 m0, s96
	v_lshl_add_u64 v[224:225], s[64:65], 0, v[150:151]
	global_load_lds_dwordx4 v[222:223], off
	s_add_i32 m0, s96, 0x2000
	v_lshl_add_u64 v[222:223], s[94:95], 0, v[152:153]
	global_load_lds_dwordx4 v[222:223], off
	s_mov_b32 m0, s12
	v_lshl_add_u64 v[222:223], s[64:65], 0, v[146:147]
	global_load_lds_dwordx4 v[222:223], off
	s_mov_b32 m0, s13
	s_nop 0
	global_load_lds_dwordx4 v[224:225], off
	s_waitcnt vmcnt(8) lgkmcnt(0)
	s_setprio 1
	s_barrier
	v_mfma_f32_16x16x32_bf16 v[62:65], v[130:133], v[184:187], 0
	v_mfma_f32_16x16x32_bf16 v[58:61], v[138:141], v[184:187], 0
	v_mfma_f32_16x16x32_bf16 v[50:53], v[130:133], v[192:195], 0
	v_mfma_f32_16x16x32_bf16 v[42:45], v[138:141], v[192:195], 0
	v_mfma_f32_16x16x32_bf16 v[34:37], v[130:133], v[200:203], 0
	v_mfma_f32_16x16x32_bf16 v[26:29], v[138:141], v[200:203], 0
	v_mfma_f32_16x16x32_bf16 v[18:21], v[130:133], v[210:213], 0
	v_mfma_f32_16x16x32_bf16 v[10:13], v[138:141], v[210:213], 0
	v_mfma_f32_16x16x32_bf16 v[62:65], v[134:137], v[188:191], v[62:65]
	v_mfma_f32_16x16x32_bf16 v[58:61], v[142:145], v[188:191], v[58:61]
	v_mfma_f32_16x16x32_bf16 v[50:53], v[134:137], v[196:199], v[50:53]
	v_mfma_f32_16x16x32_bf16 v[42:45], v[142:145], v[196:199], v[42:45]
	v_mfma_f32_16x16x32_bf16 v[34:37], v[134:137], v[206:209], v[34:37]
	v_mfma_f32_16x16x32_bf16 v[26:29], v[142:145], v[206:209], v[26:29]
	v_mfma_f32_16x16x32_bf16 v[18:21], v[134:137], v[214:217], v[18:21]
	v_mfma_f32_16x16x32_bf16 v[10:13], v[142:145], v[214:217], v[10:13]
	v_mfma_f32_16x16x32_bf16 v[54:57], v[162:165], v[184:187], 0
	v_mfma_f32_16x16x32_bf16 v[46:49], v[176:179], v[184:187], 0
	v_mfma_f32_16x16x32_bf16 v[38:41], v[162:165], v[192:195], 0
	v_mfma_f32_16x16x32_bf16 v[30:33], v[176:179], v[192:195], 0
	v_mfma_f32_16x16x32_bf16 v[22:25], v[162:165], v[200:203], 0
	v_mfma_f32_16x16x32_bf16 v[14:17], v[176:179], v[200:203], 0
	v_mfma_f32_16x16x32_bf16 v[6:9], v[162:165], v[210:213], 0
	v_mfma_f32_16x16x32_bf16 v[2:5], v[176:179], v[210:213], 0
	v_mfma_f32_16x16x32_bf16 v[54:57], v[172:175], v[188:191], v[54:57]
	v_mfma_f32_16x16x32_bf16 v[46:49], v[180:183], v[188:191], v[46:49]
	v_mfma_f32_16x16x32_bf16 v[38:41], v[172:175], v[196:199], v[38:41]
	v_mfma_f32_16x16x32_bf16 v[30:33], v[180:183], v[196:199], v[30:33]
	v_mfma_f32_16x16x32_bf16 v[22:25], v[172:175], v[206:209], v[22:25]
	v_mfma_f32_16x16x32_bf16 v[14:17], v[180:183], v[206:209], v[14:17]
	v_mfma_f32_16x16x32_bf16 v[6:9], v[172:175], v[214:217], v[6:9]
	v_mfma_f32_16x16x32_bf16 v[2:5], v[180:183], v[214:217], v[2:5]
	s_setprio 0
	s_barrier
	s_add_i32 s94, 0, 0x18000
	s_add_i32 s95, 0, 0x1c000
	v_add_u32_e32 v142, s94, v167
	v_add_u32_e32 v154, s95, v167
	ds_read_b128 v[130:133], v142
	ds_read_b128 v[134:137], v142 offset:1024
	ds_read_b128 v[138:141], v142 offset:2048
	ds_read_b128 v[142:145], v142 offset:3072
	ds_read_b128 v[162:165], v154
	ds_read_b128 v[172:175], v154 offset:1024
	ds_read_b128 v[176:179], v154 offset:2048
	ds_read_b128 v[180:183], v154 offset:3072
	s_add_u32 s64, s64, 0x100000
	s_addc_u32 s65, s65, 0
	s_mov_b32 m0, s18
	v_lshl_add_u64 v[226:227], s[64:65], 0, v[146:147]
	ds_read_b128 v[184:187], v170 offset:32768
	ds_read_b128 v[188:191], v170 offset:33792
	ds_read_b128 v[192:195], v170 offset:34816
	ds_read_b128 v[196:199], v170 offset:35840
	ds_read_b128 v[200:203], v170 offset:36864
	ds_read_b128 v[206:209], v170 offset:37888
	ds_read_b128 v[210:213], v170 offset:38912
	ds_read_b128 v[214:217], v170 offset:39936
	global_load_lds_dwordx4 v[226:227], off
	s_mov_b32 m0, s19
	v_lshl_add_u64 v[226:227], s[64:65], 0, v[150:151]
	global_load_lds_dwordx4 v[226:227], off
	s_waitcnt vmcnt(8) lgkmcnt(0)
	s_setprio 1
	s_barrier
	v_mfma_f32_16x16x32_bf16 v[126:129], v[130:133], v[184:187], v[126:129]
	v_mfma_f32_16x16x32_bf16 v[122:125], v[138:141], v[184:187], v[122:125]
	v_mfma_f32_16x16x32_bf16 v[110:113], v[130:133], v[192:195], v[110:113]
	v_mfma_f32_16x16x32_bf16 v[106:109], v[138:141], v[192:195], v[106:109]
	v_mfma_f32_16x16x32_bf16 v[98:101], v[130:133], v[200:203], v[98:101]
	v_mfma_f32_16x16x32_bf16 v[90:93], v[138:141], v[200:203], v[90:93]
	v_mfma_f32_16x16x32_bf16 v[82:85], v[130:133], v[210:213], v[82:85]
	v_mfma_f32_16x16x32_bf16 v[74:77], v[138:141], v[210:213], v[74:77]
	v_mfma_f32_16x16x32_bf16 v[126:129], v[134:137], v[188:191], v[126:129]
	v_mfma_f32_16x16x32_bf16 v[122:125], v[142:145], v[188:191], v[122:125]
	v_mfma_f32_16x16x32_bf16 v[110:113], v[134:137], v[196:199], v[110:113]
	v_mfma_f32_16x16x32_bf16 v[106:109], v[142:145], v[196:199], v[106:109]
	v_mfma_f32_16x16x32_bf16 v[98:101], v[134:137], v[206:209], v[98:101]
	v_mfma_f32_16x16x32_bf16 v[90:93], v[142:145], v[206:209], v[90:93]
	v_mfma_f32_16x16x32_bf16 v[82:85], v[134:137], v[214:217], v[82:85]
	v_mfma_f32_16x16x32_bf16 v[74:77], v[142:145], v[214:217], v[74:77]
	v_mfma_f32_16x16x32_bf16 v[118:121], v[162:165], v[184:187], v[118:121]
	v_mfma_f32_16x16x32_bf16 v[114:117], v[176:179], v[184:187], v[114:117]
	v_mfma_f32_16x16x32_bf16 v[102:105], v[162:165], v[192:195], v[102:105]
	v_mfma_f32_16x16x32_bf16 v[94:97], v[176:179], v[192:195], v[94:97]
	v_mfma_f32_16x16x32_bf16 v[86:89], v[162:165], v[200:203], v[86:89]
	v_mfma_f32_16x16x32_bf16 v[78:81], v[176:179], v[200:203], v[78:81]
	v_mfma_f32_16x16x32_bf16 v[70:73], v[162:165], v[210:213], v[70:73]
	v_mfma_f32_16x16x32_bf16 v[66:69], v[176:179], v[210:213], v[66:69]
	v_mfma_f32_16x16x32_bf16 v[118:121], v[172:175], v[188:191], v[118:121]
	v_mfma_f32_16x16x32_bf16 v[114:117], v[180:183], v[188:191], v[114:117]
	v_mfma_f32_16x16x32_bf16 v[102:105], v[172:175], v[196:199], v[102:105]
	v_mfma_f32_16x16x32_bf16 v[94:97], v[180:183], v[196:199], v[94:97]
	v_mfma_f32_16x16x32_bf16 v[86:89], v[172:175], v[206:209], v[86:89]
	v_mfma_f32_16x16x32_bf16 v[78:81], v[180:183], v[206:209], v[78:81]
	v_mfma_f32_16x16x32_bf16 v[70:73], v[172:175], v[214:217], v[70:73]
	v_mfma_f32_16x16x32_bf16 v[66:69], v[180:183], v[214:217], v[66:69]
	s_setprio 0
	s_barrier
	s_add_i32 s64, s94, s2
	v_lshl_add_u64 v[218:219], v[218:219], 0, s[16:17]
	s_mov_b32 m0, s64
	ds_read_b128 v[184:187], v170 offset:49152
	ds_read_b128 v[188:191], v170 offset:50176
	ds_read_b128 v[192:195], v170 offset:51200
	ds_read_b128 v[196:199], v170 offset:52224
	ds_read_b128 v[200:203], v170 offset:53248
	ds_read_b128 v[206:209], v170 offset:54272
	ds_read_b128 v[210:213], v170 offset:55296
	ds_read_b128 v[214:217], v170 offset:56320
	global_load_lds_dwordx4 v[218:219], off
	s_add_i32 m0, s64, 0x2000
	s_add_u32 s62, s62, 0x100080
	v_lshl_add_u64 v[218:219], v[220:221], 0, s[16:17]
	s_addc_u32 s63, s63, 0
	s_add_i32 s64, s95, s2
	global_load_lds_dwordx4 v[218:219], off
	s_mov_b32 m0, s64
	v_lshl_add_u64 v[218:219], s[62:63], 0, v[148:149]
	global_load_lds_dwordx4 v[218:219], off
	s_add_i32 m0, s64, 0x2000
	v_lshl_add_u64 v[218:219], s[62:63], 0, v[152:153]
	global_load_lds_dwordx4 v[218:219], off
	s_mov_b32 m0, s74
	v_lshl_add_u64 v[218:219], v[222:223], 0, s[16:17]
	global_load_lds_dwordx4 v[218:219], off
	s_mov_b32 m0, s75
	v_lshl_add_u64 v[218:219], v[224:225], 0, s[16:17]
	global_load_lds_dwordx4 v[218:219], off
	s_waitcnt vmcnt(8) lgkmcnt(0)
	s_setprio 1
	s_barrier
	v_mfma_f32_16x16x32_bf16 v[62:65], v[130:133], v[184:187], v[62:65]
	v_mfma_f32_16x16x32_bf16 v[58:61], v[138:141], v[184:187], v[58:61]
	v_mfma_f32_16x16x32_bf16 v[50:53], v[130:133], v[192:195], v[50:53]
	v_mfma_f32_16x16x32_bf16 v[42:45], v[138:141], v[192:195], v[42:45]
	v_mfma_f32_16x16x32_bf16 v[34:37], v[130:133], v[200:203], v[34:37]
	v_mfma_f32_16x16x32_bf16 v[26:29], v[138:141], v[200:203], v[26:29]
	v_mfma_f32_16x16x32_bf16 v[18:21], v[130:133], v[210:213], v[18:21]
	v_mfma_f32_16x16x32_bf16 v[10:13], v[138:141], v[210:213], v[10:13]
	v_mfma_f32_16x16x32_bf16 v[62:65], v[134:137], v[188:191], v[62:65]
	v_mfma_f32_16x16x32_bf16 v[58:61], v[142:145], v[188:191], v[58:61]
	v_mfma_f32_16x16x32_bf16 v[50:53], v[134:137], v[196:199], v[50:53]
	v_mfma_f32_16x16x32_bf16 v[42:45], v[142:145], v[196:199], v[42:45]
	v_mfma_f32_16x16x32_bf16 v[34:37], v[134:137], v[206:209], v[34:37]
	v_mfma_f32_16x16x32_bf16 v[26:29], v[142:145], v[206:209], v[26:29]
	v_mfma_f32_16x16x32_bf16 v[18:21], v[134:137], v[214:217], v[18:21]
	v_mfma_f32_16x16x32_bf16 v[10:13], v[142:145], v[214:217], v[10:13]
	v_mfma_f32_16x16x32_bf16 v[54:57], v[162:165], v[184:187], v[54:57]
	v_mfma_f32_16x16x32_bf16 v[46:49], v[176:179], v[184:187], v[46:49]
	v_mfma_f32_16x16x32_bf16 v[38:41], v[162:165], v[192:195], v[38:41]
	v_mfma_f32_16x16x32_bf16 v[30:33], v[176:179], v[192:195], v[30:33]
	v_mfma_f32_16x16x32_bf16 v[22:25], v[162:165], v[200:203], v[22:25]
	v_mfma_f32_16x16x32_bf16 v[14:17], v[176:179], v[200:203], v[14:17]
	v_mfma_f32_16x16x32_bf16 v[6:9], v[162:165], v[210:213], v[6:9]
	v_mfma_f32_16x16x32_bf16 v[2:5], v[176:179], v[210:213], v[2:5]
	v_mfma_f32_16x16x32_bf16 v[54:57], v[172:175], v[188:191], v[54:57]
	v_mfma_f32_16x16x32_bf16 v[46:49], v[180:183], v[188:191], v[46:49]
	v_mfma_f32_16x16x32_bf16 v[38:41], v[172:175], v[196:199], v[38:41]
	v_mfma_f32_16x16x32_bf16 v[30:33], v[180:183], v[196:199], v[30:33]
	v_mfma_f32_16x16x32_bf16 v[22:25], v[172:175], v[206:209], v[22:25]
	v_mfma_f32_16x16x32_bf16 v[14:17], v[180:183], v[206:209], v[14:17]
	v_mfma_f32_16x16x32_bf16 v[6:9], v[172:175], v[214:217], v[6:9]
	v_mfma_f32_16x16x32_bf16 v[2:5], v[180:183], v[214:217], v[2:5]
	s_setprio 0
	s_barrier
	s_add_u32 s50, s50, 0x100
	s_addc_u32 s51, s51, 0
	s_add_u32 s91, s91, 0x100
	s_addc_u32 s92, s92, 0
	s_cmp_ge_i32 s93, s7
	s_mov_b32 s62, s93
	.p2align	6
